# IEEE div seq -> v_rcp_f32 in sigmoid epilogues of phases 9/12 (79 sites)
# speedup vs baseline: 1.0150x; 1.0150x over previous
.LBB0_2087:
	s_cmp_eq_u32 s5, 1
	s_mov_b32 s12, 0x7000000
	s_cselect_b32 s12, s12, 0x8800000
	s_cmp_lg_u32 s5, 0
	s_cselect_b32 s12, s12, 0x4800000
	v_mov_b32_e32 v0, 0
	s_add_u32 s12, s19, s12
	s_waitcnt vmcnt(8)
	v_mov_b32_e32 v49, v186
	s_addc_u32 s13, s20, 0
	s_add_u32 s22, s0, s8
	v_lshlrev_b32_e32 v16, 4, v49
	v_ashrrev_i32_e32 v50, 3, v49
	v_and_b32_e32 v48, 0x70, v16
	v_lshl_or_b32 v160, v50, 10, v48
	s_addc_u32 s23, s1, s9
	v_lshl_add_u64 v[32:33], s[22:23], 0, v[160:161]
	s_barrier
	global_load_dwordx4 v[16:19], v160, s[12:13]
	v_add_u32_e32 v148, 0x8000, v160
	v_mov_b32_e32 v149, v161
	v_add_co_u32_e32 v156, vcc, s94, v32
	global_load_dwordx4 v[20:23], v148, s[12:13]
	v_add_u32_e32 v152, 0x10000, v160
	v_addc_co_u32_e32 v157, vcc, 0, v33, vcc
	v_lshl_add_u64 v[36:37], s[22:23], 0, v[148:149]
	v_mov_b32_e32 v153, v161
	global_load_dwordx4 v[24:27], v152, s[12:13]
	v_add_u32_e32 v154, 0x18000, v160
	v_add_co_u32_e32 v158, vcc, s94, v36
	global_load_dwordx4 v[28:31], v154, s[12:13]
	s_nop 0
	v_addc_co_u32_e32 v159, vcc, 0, v37, vcc
	v_lshl_add_u64 v[40:41], s[22:23], 0, v[152:153]
	v_mov_b32_e32 v155, v161
	global_load_dwordx4 v[32:35], v[156:157], off
	v_add_co_u32_e32 v164, vcc, s94, v40
	global_load_dwordx4 v[36:39], v[158:159], off
	s_nop 0
	v_addc_co_u32_e32 v165, vcc, 0, v41, vcc
	v_lshl_add_u64 v[44:45], s[22:23], 0, v[154:155]
	global_load_dwordx4 v[40:43], v[164:165], off
	v_add_co_u32_e32 v166, vcc, s94, v44
	v_mad_u64_u32 v[146:147], s[22:23], v50, s43, v[48:49]
	s_nop 0
	v_addc_co_u32_e32 v167, vcc, 0, v45, vcc
	global_load_dwordx4 v[44:47], v[166:167], off
	global_load_dwordx4 v[80:83], v160, s[12:13] offset:128
	global_load_dwordx4 v[84:87], v148, s[12:13] offset:128
	global_load_dwordx4 v[88:91], v152, s[12:13] offset:128
	global_load_dwordx4 v[92:95], v154, s[12:13] offset:128
	global_load_dwordx4 v[64:67], v[156:157], off offset:128
	global_load_dwordx4 v[68:71], v[158:159], off offset:128
	global_load_dwordx4 v[72:75], v[164:165], off offset:128
	global_load_dwordx4 v[76:79], v[166:167], off offset:128
	v_mov_b32_e32 v1, v0
	v_mov_b32_e32 v2, v0
	v_mov_b32_e32 v3, v0
	v_mov_b32_e32 v4, v0
	v_mov_b32_e32 v5, v0
	v_mov_b32_e32 v6, v0
	v_mov_b32_e32 v7, v0
	s_waitcnt vmcnt(16)
	v_mov_b32_e32 v8, v0
	v_mov_b32_e32 v9, v0
	v_mov_b32_e32 v10, v0
	v_mov_b32_e32 v11, v0
	v_mov_b32_e32 v12, v0
	v_mov_b32_e32 v13, v0
	v_mov_b32_e32 v14, v0
	v_mov_b32_e32 v15, v0
	v_add_u32_e32 v149, 0xd800, v146
	s_waitcnt vmcnt(15)
	ds_write_b128 v146, v[16:19]
	s_waitcnt vmcnt(14)
	ds_write_b128 v146, v[20:23] offset:4608
	s_waitcnt vmcnt(13)
	ds_write_b128 v146, v[24:27] offset:9216
	s_waitcnt vmcnt(12)
	ds_write_b128 v146, v[28:31] offset:13824
	s_waitcnt vmcnt(11)
	ds_write_b128 v146, v[32:35] offset:36864
	s_waitcnt vmcnt(10)
	ds_write_b128 v146, v[36:39] offset:41472
	s_waitcnt vmcnt(9)
	ds_write_b128 v146, v[40:43] offset:46080
	s_waitcnt vmcnt(8)
	ds_write_b128 v146, v[44:47] offset:50688
	v_lshrrev_b32_e32 v18, 1, v49
	s_waitcnt lgkmcnt(0)
	s_barrier
	v_and_b32_e32 v17, 0x5f, v49
	v_and_b32_e32 v16, 16, v18
	global_load_dwordx4 v[112:115], v160, s[12:13] offset:256
	global_load_dwordx4 v[116:119], v148, s[12:13] offset:256
	global_load_dwordx4 v[120:123], v152, s[12:13] offset:256
	global_load_dwordx4 v[124:127], v154, s[12:13] offset:256
	global_load_dwordx4 v[96:99], v[156:157], off offset:256
	global_load_dwordx4 v[100:103], v[158:159], off offset:256
	global_load_dwordx4 v[104:107], v[164:165], off offset:256
	global_load_dwordx4 v[108:111], v[166:167], off offset:256
	v_mad_u32_u24 v147, v17, s43, v16
	v_and_b32_e32 v17, 31, v49
	v_and_or_b32 v17, v18, s44, v17
	v_mad_u64_u32 v[150:151], s[22:23], v17, s43, v[16:17]
	ds_read_b128 v[128:131], v150 offset:4608
	ds_read_b128 v[132:135], v147 offset:41472
	ds_read_b128 v[16:19], v150
	ds_read_b128 v[136:139], v150 offset:32
	ds_read_b128 v[140:143], v147 offset:36864
	ds_read_b128 v[200:203], v147 offset:36896
	s_waitcnt lgkmcnt(1)
	v_mfma_f32_32x32x16_bf16 v[48:63], v[16:19], v[140:143], v[0:15]
	v_mov_b32_e32 v151, v161
	v_mfma_f32_32x32x16_bf16 v[32:47], v[16:19], v[132:135], v[0:15]
	v_mfma_f32_32x32x16_bf16 v[16:31], v[128:131], v[140:143], v[0:15]
	v_mfma_f32_32x32x16_bf16 v[0:15], v[128:131], v[132:135], v[0:15]
	ds_read_b128 v[128:131], v150 offset:4640
	ds_read_b128 v[132:135], v147 offset:41504
	s_waitcnt vmcnt(15)
	ds_write_b128 v146, v[80:83] offset:18432
	s_waitcnt vmcnt(14)
	ds_write_b128 v146, v[84:87] offset:23040
	s_waitcnt vmcnt(13)
	ds_write_b128 v146, v[88:91] offset:27648
	s_waitcnt vmcnt(12)
	ds_write_b128 v146, v[92:95] offset:32256
	ds_read_b128 v[80:83], v150 offset:64
	ds_read_b128 v[84:87], v150 offset:4672
	ds_read_b128 v[88:91], v147 offset:36928
	ds_read_b128 v[92:95], v147 offset:41536
	s_waitcnt vmcnt(11)
	ds_write_b128 v146, v[64:67] offset:55296
	s_waitcnt vmcnt(10)
	ds_write_b128 v146, v[68:71] offset:59904
	s_waitcnt vmcnt(9)
	ds_write_b128 v146, v[72:75] offset:64512
	s_waitcnt vmcnt(8)
	ds_write_b128 v149, v[76:79] offset:13824
	ds_read_b128 v[64:67], v150 offset:96
	ds_read_b128 v[68:71], v150 offset:4704
	ds_read_b128 v[72:75], v147 offset:36960
	ds_read_b128 v[76:79], v147 offset:41568
	s_waitcnt lgkmcnt(0)
	s_barrier
	v_mfma_f32_32x32x16_bf16 v[48:63], v[136:139], v[200:203], v[48:63]
	v_mfma_f32_32x32x16_bf16 v[32:47], v[136:139], v[132:135], v[32:47]
	v_mfma_f32_32x32x16_bf16 v[16:31], v[128:131], v[200:203], v[16:31]
	v_mfma_f32_32x32x16_bf16 v[0:15], v[128:131], v[132:135], v[0:15]
	v_mfma_f32_32x32x16_bf16 v[48:63], v[80:83], v[88:91], v[48:63]
	v_mfma_f32_32x32x16_bf16 v[32:47], v[80:83], v[92:95], v[32:47]
	v_mfma_f32_32x32x16_bf16 v[16:31], v[84:87], v[88:91], v[16:31]
	v_mfma_f32_32x32x16_bf16 v[0:15], v[84:87], v[92:95], v[0:15]
	v_mfma_f32_32x32x16_bf16 v[48:63], v[64:67], v[72:75], v[48:63]
	v_mfma_f32_32x32x16_bf16 v[32:47], v[64:67], v[76:79], v[32:47]
	v_mfma_f32_32x32x16_bf16 v[16:31], v[68:71], v[72:75], v[16:31]
	v_mfma_f32_32x32x16_bf16 v[0:15], v[68:71], v[76:79], v[0:15]
	global_load_dwordx4 v[128:131], v160, s[12:13] offset:384
	global_load_dwordx4 v[132:135], v148, s[12:13] offset:384
	global_load_dwordx4 v[136:139], v152, s[12:13] offset:384
	global_load_dwordx4 v[140:143], v154, s[12:13] offset:384
	global_load_dwordx4 v[64:67], v[156:157], off offset:384
	global_load_dwordx4 v[68:71], v[158:159], off offset:384
	global_load_dwordx4 v[72:75], v[164:165], off offset:384
	global_load_dwordx4 v[76:79], v[166:167], off offset:384
	ds_read_b128 v[80:83], v150 offset:23040
	ds_read_b128 v[84:87], v147 offset:59904
	ds_read_b128 v[88:91], v150 offset:18432
	ds_read_b128 v[92:95], v150 offset:18464
	ds_read_b128 v[200:203], v147 offset:55296
	ds_read_b128 v[226:229], v147 offset:55328
	s_waitcnt lgkmcnt(1)
	v_mfma_f32_32x32x16_bf16 v[48:63], v[88:91], v[200:203], v[48:63]
	v_mfma_f32_32x32x16_bf16 v[32:47], v[88:91], v[84:87], v[32:47]
	v_mfma_f32_32x32x16_bf16 v[16:31], v[80:83], v[200:203], v[16:31]
	v_mfma_f32_32x32x16_bf16 v[0:15], v[80:83], v[84:87], v[0:15]
	ds_read_b128 v[80:83], v150 offset:23072
	ds_read_b128 v[84:87], v147 offset:59936
	s_waitcnt vmcnt(15)
	ds_write_b128 v146, v[112:115]
	s_waitcnt vmcnt(14)
	ds_write_b128 v146, v[116:119] offset:4608
	s_waitcnt vmcnt(13)
	ds_write_b128 v146, v[120:123] offset:9216
	s_waitcnt vmcnt(12)
	ds_write_b128 v146, v[124:127] offset:13824
	s_waitcnt lgkmcnt(6)
	v_mfma_f32_32x32x16_bf16 v[48:63], v[92:95], v[226:229], v[48:63]
	s_waitcnt lgkmcnt(4)
	v_mfma_f32_32x32x16_bf16 v[32:47], v[92:95], v[84:87], v[32:47]
	v_mfma_f32_32x32x16_bf16 v[16:31], v[80:83], v[226:229], v[16:31]
	v_mfma_f32_32x32x16_bf16 v[0:15], v[80:83], v[84:87], v[0:15]
	ds_read_b128 v[80:83], v150 offset:18496
	ds_read_b128 v[84:87], v150 offset:23104
	ds_read_b128 v[88:91], v147 offset:55360
	ds_read_b128 v[92:95], v147 offset:59968
	s_waitcnt vmcnt(11)
	ds_write_b128 v146, v[96:99] offset:36864
	s_waitcnt vmcnt(10)
	ds_write_b128 v146, v[100:103] offset:41472
	s_waitcnt vmcnt(9)
	ds_write_b128 v146, v[104:107] offset:46080
	s_waitcnt vmcnt(8)
	ds_write_b128 v146, v[108:111] offset:50688
	s_waitcnt lgkmcnt(5)
	v_mfma_f32_32x32x16_bf16 v[48:63], v[80:83], v[88:91], v[48:63]
	s_waitcnt lgkmcnt(4)
	v_mfma_f32_32x32x16_bf16 v[32:47], v[80:83], v[92:95], v[32:47]
	v_mfma_f32_32x32x16_bf16 v[16:31], v[84:87], v[88:91], v[16:31]
	v_mfma_f32_32x32x16_bf16 v[0:15], v[84:87], v[92:95], v[0:15]
	ds_read_b128 v[80:83], v150 offset:18528
	ds_read_b128 v[84:87], v150 offset:23136
	ds_read_b128 v[88:91], v147 offset:55392
	ds_read_b128 v[92:95], v147 offset:60000
	s_waitcnt lgkmcnt(0)
	s_barrier
	v_mfma_f32_32x32x16_bf16 v[48:63], v[80:83], v[88:91], v[48:63]
	v_mfma_f32_32x32x16_bf16 v[32:47], v[80:83], v[92:95], v[32:47]
	v_mfma_f32_32x32x16_bf16 v[16:31], v[84:87], v[88:91], v[16:31]
	v_mfma_f32_32x32x16_bf16 v[0:15], v[84:87], v[92:95], v[0:15]
	global_load_dwordx4 v[96:99], v160, s[12:13] offset:512
	global_load_dwordx4 v[100:103], v148, s[12:13] offset:512
	global_load_dwordx4 v[104:107], v152, s[12:13] offset:512
	global_load_dwordx4 v[108:111], v154, s[12:13] offset:512
	global_load_dwordx4 v[80:83], v[156:157], off offset:512
	global_load_dwordx4 v[84:87], v[158:159], off offset:512
	global_load_dwordx4 v[88:91], v[164:165], off offset:512
	global_load_dwordx4 v[92:95], v[166:167], off offset:512
	ds_read_b128 v[112:115], v150 offset:4608
	ds_read_b128 v[116:119], v147 offset:41472
	ds_read_b128 v[120:123], v150
	ds_read_b128 v[124:127], v150 offset:32
	ds_read_b128 v[200:203], v147 offset:36864
	ds_read_b128 v[226:229], v147 offset:36896
	s_waitcnt lgkmcnt(1)
	v_mfma_f32_32x32x16_bf16 v[48:63], v[120:123], v[200:203], v[48:63]
	v_mfma_f32_32x32x16_bf16 v[32:47], v[120:123], v[116:119], v[32:47]
	v_mfma_f32_32x32x16_bf16 v[16:31], v[112:115], v[200:203], v[16:31]
	v_mfma_f32_32x32x16_bf16 v[0:15], v[112:115], v[116:119], v[0:15]
	ds_read_b128 v[112:115], v150 offset:4640
	ds_read_b128 v[116:119], v147 offset:41504
	s_waitcnt vmcnt(15)
	ds_write_b128 v146, v[128:131] offset:18432
	s_waitcnt vmcnt(14)
	ds_write_b128 v146, v[132:135] offset:23040
	s_waitcnt vmcnt(13)
	ds_write_b128 v146, v[136:139] offset:27648
	s_waitcnt vmcnt(12)
	ds_write_b128 v146, v[140:143] offset:32256
	s_waitcnt lgkmcnt(6)
	v_mfma_f32_32x32x16_bf16 v[48:63], v[124:127], v[226:229], v[48:63]
	s_waitcnt lgkmcnt(4)
	v_mfma_f32_32x32x16_bf16 v[32:47], v[124:127], v[116:119], v[32:47]
	v_mfma_f32_32x32x16_bf16 v[16:31], v[112:115], v[226:229], v[16:31]
	v_mfma_f32_32x32x16_bf16 v[0:15], v[112:115], v[116:119], v[0:15]
	ds_read_b128 v[112:115], v150 offset:64
	ds_read_b128 v[116:119], v150 offset:4672
	ds_read_b128 v[120:123], v147 offset:36928
	ds_read_b128 v[124:127], v147 offset:41536
	s_waitcnt vmcnt(11)
	ds_write_b128 v146, v[64:67] offset:55296
	s_waitcnt vmcnt(10)
	ds_write_b128 v146, v[68:71] offset:59904
	s_waitcnt vmcnt(9)
	ds_write_b128 v146, v[72:75] offset:64512
	s_waitcnt vmcnt(8)
	ds_write_b128 v149, v[76:79] offset:13824
	ds_read_b128 v[64:67], v150 offset:96
	ds_read_b128 v[68:71], v150 offset:4704
	ds_read_b128 v[72:75], v147 offset:36960
	ds_read_b128 v[76:79], v147 offset:41568
	s_waitcnt lgkmcnt(0)
	s_barrier
	v_mfma_f32_32x32x16_bf16 v[48:63], v[112:115], v[120:123], v[48:63]
	v_mfma_f32_32x32x16_bf16 v[32:47], v[112:115], v[124:127], v[32:47]
	v_mfma_f32_32x32x16_bf16 v[16:31], v[116:119], v[120:123], v[16:31]
	v_mfma_f32_32x32x16_bf16 v[0:15], v[116:119], v[124:127], v[0:15]
	v_mfma_f32_32x32x16_bf16 v[48:63], v[64:67], v[72:75], v[48:63]
	v_mfma_f32_32x32x16_bf16 v[32:47], v[64:67], v[76:79], v[32:47]
	v_mfma_f32_32x32x16_bf16 v[16:31], v[68:71], v[72:75], v[16:31]
	v_mfma_f32_32x32x16_bf16 v[0:15], v[68:71], v[76:79], v[0:15]
	global_load_dwordx4 v[112:115], v160, s[12:13] offset:640
	global_load_dwordx4 v[116:119], v148, s[12:13] offset:640
	global_load_dwordx4 v[120:123], v152, s[12:13] offset:640
	global_load_dwordx4 v[124:127], v154, s[12:13] offset:640
	global_load_dwordx4 v[64:67], v[156:157], off offset:640
	global_load_dwordx4 v[68:71], v[158:159], off offset:640
	global_load_dwordx4 v[72:75], v[164:165], off offset:640
	global_load_dwordx4 v[76:79], v[166:167], off offset:640
	ds_read_b128 v[128:131], v150 offset:23040
	ds_read_b128 v[132:135], v147 offset:59904
	ds_read_b128 v[136:139], v150 offset:18432
	ds_read_b128 v[140:143], v150 offset:18464
	ds_read_b128 v[200:203], v147 offset:55296
	ds_read_b128 v[226:229], v147 offset:55328
	s_waitcnt lgkmcnt(1)
	v_mfma_f32_32x32x16_bf16 v[48:63], v[136:139], v[200:203], v[48:63]
	v_mfma_f32_32x32x16_bf16 v[32:47], v[136:139], v[132:135], v[32:47]
	v_mfma_f32_32x32x16_bf16 v[16:31], v[128:131], v[200:203], v[16:31]
	v_mfma_f32_32x32x16_bf16 v[0:15], v[128:131], v[132:135], v[0:15]
	ds_read_b128 v[128:131], v150 offset:23072
	ds_read_b128 v[132:135], v147 offset:59936
	s_waitcnt vmcnt(15)
	ds_write_b128 v146, v[96:99]
	s_waitcnt vmcnt(14)
	ds_write_b128 v146, v[100:103] offset:4608
	s_waitcnt vmcnt(13)
	ds_write_b128 v146, v[104:107] offset:9216
	s_waitcnt vmcnt(12)
	ds_write_b128 v146, v[108:111] offset:13824
	ds_read_b128 v[96:99], v150 offset:18496
	ds_read_b128 v[100:103], v150 offset:23104
	ds_read_b128 v[104:107], v147 offset:55360
	ds_read_b128 v[108:111], v147 offset:59968
	s_waitcnt vmcnt(11)
	ds_write_b128 v146, v[80:83] offset:36864
	s_waitcnt vmcnt(10)
	ds_write_b128 v146, v[84:87] offset:41472
	s_waitcnt vmcnt(9)
	ds_write_b128 v146, v[88:91] offset:46080
	s_waitcnt vmcnt(8)
	ds_write_b128 v146, v[92:95] offset:50688
	ds_read_b128 v[80:83], v150 offset:18528
	ds_read_b128 v[84:87], v150 offset:23136
	ds_read_b128 v[88:91], v147 offset:55392
	ds_read_b128 v[92:95], v147 offset:60000
	s_waitcnt lgkmcnt(0)
	s_barrier
	v_mfma_f32_32x32x16_bf16 v[48:63], v[140:143], v[226:229], v[48:63]
	v_mfma_f32_32x32x16_bf16 v[32:47], v[140:143], v[132:135], v[32:47]
	v_mfma_f32_32x32x16_bf16 v[16:31], v[128:131], v[226:229], v[16:31]
	v_mfma_f32_32x32x16_bf16 v[0:15], v[128:131], v[132:135], v[0:15]
	v_mfma_f32_32x32x16_bf16 v[48:63], v[96:99], v[104:107], v[48:63]
	v_mfma_f32_32x32x16_bf16 v[32:47], v[96:99], v[108:111], v[32:47]
	v_mfma_f32_32x32x16_bf16 v[16:31], v[100:103], v[104:107], v[16:31]
	v_mfma_f32_32x32x16_bf16 v[0:15], v[100:103], v[108:111], v[0:15]
	v_mfma_f32_32x32x16_bf16 v[48:63], v[80:83], v[88:91], v[48:63]
	v_mfma_f32_32x32x16_bf16 v[32:47], v[80:83], v[92:95], v[32:47]
	v_mfma_f32_32x32x16_bf16 v[16:31], v[84:87], v[88:91], v[16:31]
	v_mfma_f32_32x32x16_bf16 v[0:15], v[84:87], v[92:95], v[0:15]
	global_load_dwordx4 v[96:99], v160, s[12:13] offset:768
	global_load_dwordx4 v[100:103], v148, s[12:13] offset:768
	global_load_dwordx4 v[104:107], v152, s[12:13] offset:768
	global_load_dwordx4 v[108:111], v154, s[12:13] offset:768
	global_load_dwordx4 v[80:83], v[156:157], off offset:768
	global_load_dwordx4 v[84:87], v[158:159], off offset:768
	global_load_dwordx4 v[88:91], v[164:165], off offset:768
	global_load_dwordx4 v[92:95], v[166:167], off offset:768
	ds_read_b128 v[128:131], v150 offset:4608
	ds_read_b128 v[132:135], v147 offset:41472
	ds_read_b128 v[136:139], v150
	ds_read_b128 v[140:143], v150 offset:32
	ds_read_b128 v[200:203], v147 offset:36864
	ds_read_b128 v[226:229], v147 offset:36896
	s_waitcnt lgkmcnt(1)
	v_mfma_f32_32x32x16_bf16 v[48:63], v[136:139], v[200:203], v[48:63]
	v_mfma_f32_32x32x16_bf16 v[32:47], v[136:139], v[132:135], v[32:47]
	v_mfma_f32_32x32x16_bf16 v[16:31], v[128:131], v[200:203], v[16:31]
	v_mfma_f32_32x32x16_bf16 v[0:15], v[128:131], v[132:135], v[0:15]
	ds_read_b128 v[128:131], v150 offset:4640
	ds_read_b128 v[132:135], v147 offset:41504
	s_waitcnt vmcnt(15)
	ds_write_b128 v146, v[112:115] offset:18432
	s_waitcnt vmcnt(14)
	ds_write_b128 v146, v[116:119] offset:23040
	s_waitcnt vmcnt(13)
	ds_write_b128 v146, v[120:123] offset:27648
	s_waitcnt vmcnt(12)
	ds_write_b128 v146, v[124:127] offset:32256
	ds_read_b128 v[112:115], v150 offset:64
	ds_read_b128 v[116:119], v150 offset:4672
	ds_read_b128 v[120:123], v147 offset:36928
	ds_read_b128 v[124:127], v147 offset:41536
	s_waitcnt vmcnt(11)
	ds_write_b128 v146, v[64:67] offset:55296
	s_waitcnt vmcnt(10)
	ds_write_b128 v146, v[68:71] offset:59904
	s_waitcnt vmcnt(9)
	ds_write_b128 v146, v[72:75] offset:64512
	s_waitcnt vmcnt(8)
	ds_write_b128 v149, v[76:79] offset:13824
	ds_read_b128 v[64:67], v150 offset:96
	ds_read_b128 v[68:71], v150 offset:4704
	ds_read_b128 v[72:75], v147 offset:36960
	ds_read_b128 v[76:79], v147 offset:41568
	s_waitcnt lgkmcnt(0)
	s_barrier
	v_mfma_f32_32x32x16_bf16 v[48:63], v[140:143], v[226:229], v[48:63]
	v_mfma_f32_32x32x16_bf16 v[32:47], v[140:143], v[132:135], v[32:47]
	v_mfma_f32_32x32x16_bf16 v[16:31], v[128:131], v[226:229], v[16:31]
	v_mfma_f32_32x32x16_bf16 v[0:15], v[128:131], v[132:135], v[0:15]
	v_mfma_f32_32x32x16_bf16 v[48:63], v[112:115], v[120:123], v[48:63]
	v_mfma_f32_32x32x16_bf16 v[32:47], v[112:115], v[124:127], v[32:47]
	v_mfma_f32_32x32x16_bf16 v[16:31], v[116:119], v[120:123], v[16:31]
	v_mfma_f32_32x32x16_bf16 v[0:15], v[116:119], v[124:127], v[0:15]
	v_mfma_f32_32x32x16_bf16 v[48:63], v[64:67], v[72:75], v[48:63]
	v_mfma_f32_32x32x16_bf16 v[32:47], v[64:67], v[76:79], v[32:47]
	v_mfma_f32_32x32x16_bf16 v[16:31], v[68:71], v[72:75], v[16:31]
	v_mfma_f32_32x32x16_bf16 v[0:15], v[68:71], v[76:79], v[0:15]
	global_load_dwordx4 v[112:115], v160, s[12:13] offset:896
	global_load_dwordx4 v[116:119], v148, s[12:13] offset:896
	global_load_dwordx4 v[120:123], v152, s[12:13] offset:896
	global_load_dwordx4 v[124:127], v154, s[12:13] offset:896
	global_load_dwordx4 v[64:67], v[156:157], off offset:896
	global_load_dwordx4 v[68:71], v[158:159], off offset:896
	global_load_dwordx4 v[72:75], v[164:165], off offset:896
	global_load_dwordx4 v[76:79], v[166:167], off offset:896
	ds_read_b128 v[128:131], v150 offset:23040
	ds_read_b128 v[132:135], v147 offset:59904
	ds_read_b128 v[136:139], v150 offset:18432
	ds_read_b128 v[140:143], v150 offset:18464
	ds_read_b128 v[152:155], v147 offset:55296
	ds_read_b128 v[156:159], v147 offset:55328
	s_add_u32 s12, s0, s14
	s_addc_u32 s13, s1, s15
	s_add_i32 s5, s5, 1
	s_add_u32 s8, s8, 0x100000
	s_addc_u32 s9, s9, 0
	s_waitcnt lgkmcnt(1)
	v_mfma_f32_32x32x16_bf16 v[48:63], v[136:139], v[152:155], v[48:63]
	s_add_u32 s14, s14, 0x200000
	s_addc_u32 s15, s15, 0
	s_cmp_eq_u32 s5, 3
	v_mfma_f32_32x32x16_bf16 v[0:15], v[128:131], v[132:135], v[0:15]
	v_mfma_f32_32x32x16_bf16 v[16:31], v[128:131], v[152:155], v[16:31]
	v_mov_b32_e32 v153, v161
	v_mfma_f32_32x32x16_bf16 v[32:47], v[136:139], v[132:135], v[32:47]
	ds_read_b128 v[128:131], v150 offset:23072
	ds_read_b128 v[132:135], v147 offset:59936
	s_waitcnt vmcnt(15)
	ds_write_b128 v146, v[96:99]
	s_waitcnt vmcnt(14)
	ds_write_b128 v146, v[100:103] offset:4608
	s_waitcnt vmcnt(13)
	ds_write_b128 v146, v[104:107] offset:9216
	s_waitcnt vmcnt(12)
	ds_write_b128 v146, v[108:111] offset:13824
	ds_read_b128 v[96:99], v150 offset:18496
	ds_read_b128 v[100:103], v150 offset:23104
	ds_read_b128 v[104:107], v147 offset:55360
	ds_read_b128 v[108:111], v147 offset:59968
	s_waitcnt vmcnt(11)
	ds_write_b128 v146, v[80:83] offset:36864
	s_waitcnt vmcnt(10)
	ds_write_b128 v146, v[84:87] offset:41472
	s_waitcnt vmcnt(9)
	ds_write_b128 v146, v[88:91] offset:46080
	s_waitcnt vmcnt(8)
	ds_write_b128 v146, v[92:95] offset:50688
	ds_read_b128 v[80:83], v150 offset:18528
	ds_read_b128 v[84:87], v150 offset:23136
	ds_read_b128 v[88:91], v147 offset:55392
	ds_read_b128 v[92:95], v147 offset:60000
	s_waitcnt lgkmcnt(0)
	s_barrier
	v_mfma_f32_32x32x16_bf16 v[48:63], v[140:143], v[156:159], v[48:63]
	v_mfma_f32_32x32x16_bf16 v[0:15], v[128:131], v[132:135], v[0:15]
	v_mfma_f32_32x32x16_bf16 v[16:31], v[128:131], v[156:159], v[16:31]
	v_mfma_f32_32x32x16_bf16 v[32:47], v[140:143], v[132:135], v[32:47]
	v_mfma_f32_32x32x16_bf16 v[48:63], v[96:99], v[104:107], v[48:63]
	v_mfma_f32_32x32x16_bf16 v[0:15], v[100:103], v[108:111], v[0:15]
	v_mfma_f32_32x32x16_bf16 v[16:31], v[100:103], v[104:107], v[16:31]
	v_mfma_f32_32x32x16_bf16 v[32:47], v[96:99], v[108:111], v[32:47]
	v_mfma_f32_32x32x16_bf16 v[48:63], v[80:83], v[88:91], v[48:63]
	v_mfma_f32_32x32x16_bf16 v[0:15], v[84:87], v[92:95], v[0:15]
	v_mfma_f32_32x32x16_bf16 v[16:31], v[84:87], v[88:91], v[16:31]
	v_mfma_f32_32x32x16_bf16 v[32:47], v[80:83], v[92:95], v[32:47]
	ds_read_b128 v[80:83], v150 offset:4608
	ds_read_b128 v[84:87], v147 offset:41472
	ds_read_b128 v[88:91], v150
	ds_read_b128 v[92:95], v150 offset:32
	ds_read_b128 v[96:99], v147 offset:36864
	ds_read_b128 v[100:103], v147 offset:36896
	s_waitcnt lgkmcnt(1)
	v_mfma_f32_32x32x16_bf16 v[48:63], v[88:91], v[96:99], v[48:63]
	v_mfma_f32_32x32x16_bf16 v[0:15], v[80:83], v[84:87], v[0:15]
	v_mfma_f32_32x32x16_bf16 v[16:31], v[80:83], v[96:99], v[16:31]
	v_mfma_f32_32x32x16_bf16 v[32:47], v[88:91], v[84:87], v[32:47]
	ds_read_b128 v[80:83], v150 offset:4640
	ds_read_b128 v[84:87], v147 offset:41504
	s_waitcnt vmcnt(7)
	ds_write_b128 v146, v[112:115] offset:18432
	s_waitcnt vmcnt(6)
	ds_write_b128 v146, v[116:119] offset:23040
	s_waitcnt vmcnt(5)
	ds_write_b128 v146, v[120:123] offset:27648
	s_waitcnt vmcnt(4)
	ds_write_b128 v146, v[124:127] offset:32256
	s_waitcnt lgkmcnt(6)
	v_mfma_f32_32x32x16_bf16 v[48:63], v[92:95], v[100:103], v[48:63]
	s_waitcnt lgkmcnt(4)
	v_mfma_f32_32x32x16_bf16 v[0:15], v[80:83], v[84:87], v[0:15]
	v_mfma_f32_32x32x16_bf16 v[16:31], v[80:83], v[100:103], v[16:31]
	v_mfma_f32_32x32x16_bf16 v[32:47], v[92:95], v[84:87], v[32:47]
	ds_read_b128 v[80:83], v150 offset:64
	ds_read_b128 v[84:87], v150 offset:4672
	ds_read_b128 v[88:91], v147 offset:36928
	ds_read_b128 v[92:95], v147 offset:41536
	s_waitcnt vmcnt(3)
	ds_write_b128 v146, v[64:67] offset:55296
	s_waitcnt vmcnt(2)
	ds_write_b128 v146, v[68:71] offset:59904
	s_waitcnt vmcnt(1)
	ds_write_b128 v146, v[72:75] offset:64512
	s_waitcnt vmcnt(0)
	ds_write_b128 v149, v[76:79] offset:13824
	ds_read_b128 v[64:67], v150 offset:96
	ds_read_b128 v[68:71], v150 offset:4704
	ds_read_b128 v[72:75], v147 offset:36960
	ds_read_b128 v[76:79], v147 offset:41568
	s_waitcnt lgkmcnt(0)
	s_barrier
	v_mov_b32_e32 v149, v161
	v_mfma_f32_32x32x16_bf16 v[48:63], v[80:83], v[88:91], v[48:63]
	v_mfma_f32_32x32x16_bf16 v[0:15], v[84:87], v[92:95], v[0:15]
	v_mfma_f32_32x32x16_bf16 v[16:31], v[84:87], v[88:91], v[16:31]
	v_mfma_f32_32x32x16_bf16 v[32:47], v[80:83], v[92:95], v[32:47]
	v_mfma_f32_32x32x16_bf16 v[48:63], v[64:67], v[72:75], v[48:63]
	v_mfma_f32_32x32x16_bf16 v[0:15], v[68:71], v[76:79], v[0:15]
	v_mfma_f32_32x32x16_bf16 v[16:31], v[68:71], v[72:75], v[16:31]
	v_mfma_f32_32x32x16_bf16 v[32:47], v[64:67], v[76:79], v[32:47]
	ds_read_b128 v[64:67], v150 offset:23040
	ds_read_b128 v[68:71], v147 offset:59904
	ds_read_b128 v[72:75], v150 offset:18432
	ds_read_b128 v[76:79], v150 offset:18464
	ds_read_b128 v[80:83], v147 offset:55296
	ds_read_b128 v[84:87], v147 offset:55328
	s_waitcnt lgkmcnt(1)
	v_mfma_f32_32x32x16_bf16 v[48:63], v[72:75], v[80:83], v[48:63]
	v_mfma_f32_32x32x16_bf16 v[0:15], v[64:67], v[68:71], v[0:15]
	v_mfma_f32_32x32x16_bf16 v[16:31], v[64:67], v[80:83], v[16:31]
	v_mfma_f32_32x32x16_bf16 v[32:47], v[72:75], v[68:71], v[32:47]
	ds_read_b128 v[64:67], v150 offset:23072
	ds_read_b128 v[68:71], v147 offset:59936
	s_waitcnt lgkmcnt(2)
	v_mfma_f32_32x32x16_bf16 v[48:63], v[76:79], v[84:87], v[48:63]
	s_waitcnt lgkmcnt(0)
	v_mfma_f32_32x32x16_bf16 v[0:15], v[64:67], v[68:71], v[0:15]
	v_mfma_f32_32x32x16_bf16 v[16:31], v[64:67], v[84:87], v[16:31]
	v_mfma_f32_32x32x16_bf16 v[32:47], v[76:79], v[68:71], v[32:47]
	ds_read_b128 v[64:67], v147 offset:59968
	ds_read_b128 v[68:71], v147 offset:55360
	ds_read_b128 v[72:75], v150 offset:23104
	ds_read_b128 v[76:79], v150 offset:18496
	s_waitcnt lgkmcnt(0)
	v_mfma_f32_32x32x16_bf16 v[48:63], v[76:79], v[68:71], v[48:63]
	v_mfma_f32_32x32x16_bf16 v[0:15], v[72:75], v[64:67], v[0:15]
	v_mfma_f32_32x32x16_bf16 v[16:31], v[72:75], v[68:71], v[16:31]
	v_mfma_f32_32x32x16_bf16 v[32:47], v[76:79], v[64:67], v[32:47]
	ds_read_b128 v[64:67], v147 offset:60000
	ds_read_b128 v[68:71], v147 offset:55392
	ds_read_b128 v[72:75], v150 offset:23136
	ds_read_b128 v[76:79], v150 offset:18528
	s_waitcnt lgkmcnt(0)
	s_barrier
	v_mfma_f32_32x32x16_bf16 v[48:63], v[76:79], v[68:71], v[48:63]
	v_mfma_f32_32x32x16_bf16 v[0:15], v[72:75], v[64:67], v[0:15]
	s_nop 10
	v_cvt_pk_bf16_f32 v200, v48, v49
	v_mov_b32_e32 v49, v186
	v_cvt_pk_bf16_f32 v189, v50, v51
	v_cvt_pk_bf16_f32 v188, v52, v53
	v_cvt_pk_bf16_f32 v208, v54, v55
	v_cvt_pk_bf16_f32 v195, v56, v57
	v_cvt_pk_bf16_f32 v192, v58, v59
	v_mfma_f32_32x32x16_bf16 v[16:31], v[72:75], v[68:71], v[16:31]
	v_cvt_pk_bf16_f32 v232, v0, v1
	v_mov_b32_e32 v0, v161
	s_nop 0
	v_ashrrev_i32_e32 v50, 3, v49
	s_barrier
	v_mfma_f32_32x32x16_bf16 v[32:47], v[76:79], v[64:67], v[32:47]
	s_nop 5
	v_cvt_pk_bf16_f32 v240, v16, v17
	v_lshlrev_b32_e32 v16, 4, v49
	v_and_b32_e32 v48, 0x70, v16
	v_lshl_or_b32 v160, v50, 11, v48
	v_cvt_pk_bf16_f32 v239, v18, v19
	global_load_dwordx4 v[16:19], v160, s[10:11]
	v_cvt_pk_bf16_f32 v248, v32, v33
	v_lshl_add_u64 v[32:33], s[12:13], 0, v[160:161]
	v_add_u32_e32 v148, 0x10000, v160
	v_add_co_u32_e32 v154, vcc, s95, v32
	v_cvt_pk_bf16_f32 v246, v36, v37
	v_cvt_pk_bf16_f32 v238, v20, v21
	v_cvt_pk_bf16_f32 v237, v22, v23
	global_load_dwordx4 v[20:23], v148, s[10:11]
	v_add_u32_e32 v150, 0x20000, v160
	v_addc_co_u32_e32 v155, vcc, 0, v33, vcc
	v_lshl_add_u64 v[36:37], s[12:13], 0, v[148:149]
	v_cvt_pk_bf16_f32 v236, v24, v25
	v_cvt_pk_bf16_f32 v235, v26, v27
	global_load_dwordx4 v[24:27], v150, s[10:11]
	v_add_u32_e32 v152, 0x30000, v160
	v_add_co_u32_e32 v156, vcc, s95, v36
	v_cvt_pk_bf16_f32 v244, v40, v41
	v_cvt_pk_bf16_f32 v234, v28, v29
	v_cvt_pk_bf16_f32 v233, v30, v31
	global_load_dwordx4 v[28:31], v152, s[10:11]
	v_addc_co_u32_e32 v157, vcc, 0, v37, vcc
	v_lshl_add_u64 v[40:41], s[12:13], 0, v[150:151]
	v_cvt_pk_bf16_f32 v247, v34, v35
	global_load_dwordx4 v[32:35], v[154:155], off
	v_add_co_u32_e32 v158, vcc, s95, v40
	v_cvt_pk_bf16_f32 v245, v38, v39
	v_cvt_pk_bf16_f32 v242, v44, v45
	global_load_dwordx4 v[36:39], v[156:157], off
	v_addc_co_u32_e32 v159, vcc, 0, v41, vcc
	v_lshl_add_u64 v[44:45], s[12:13], 0, v[152:153]
	v_cvt_pk_bf16_f32 v243, v42, v43
	global_load_dwordx4 v[40:43], v[158:159], off
	v_add_co_u32_e32 v164, vcc, s95, v44
	v_cvt_pk_bf16_f32 v241, v46, v47
	s_nop 0
	v_addc_co_u32_e32 v165, vcc, 0, v45, vcc
	global_load_dwordx4 v[44:47], v[164:165], off
	global_load_dwordx4 v[80:83], v160, s[10:11] offset:128
	global_load_dwordx4 v[84:87], v148, s[10:11] offset:128
	global_load_dwordx4 v[88:91], v150, s[10:11] offset:128
	global_load_dwordx4 v[92:95], v152, s[10:11] offset:128
	global_load_dwordx4 v[64:67], v[154:155], off offset:128
	global_load_dwordx4 v[68:71], v[156:157], off offset:128
	global_load_dwordx4 v[72:75], v[158:159], off offset:128
	global_load_dwordx4 v[76:79], v[164:165], off offset:128
	v_mad_u64_u32 v[146:147], s[12:13], v50, s43, v[48:49]
	s_waitcnt vmcnt(15)
	ds_write_b128 v146, v[16:19]
	s_waitcnt vmcnt(14)
	ds_write_b128 v146, v[20:23] offset:4608
	s_waitcnt vmcnt(13)
	ds_write_b128 v146, v[24:27] offset:9216
	s_waitcnt vmcnt(12)
	ds_write_b128 v146, v[28:31] offset:13824
	s_waitcnt vmcnt(11)
	ds_write_b128 v146, v[32:35] offset:36864
	s_waitcnt vmcnt(10)
	ds_write_b128 v146, v[36:39] offset:41472
	s_waitcnt vmcnt(9)
	ds_write_b128 v146, v[40:43] offset:46080
	s_waitcnt vmcnt(8)
	ds_write_b128 v146, v[44:47] offset:50688
	v_lshrrev_b32_e32 v18, 1, v49
	s_waitcnt lgkmcnt(0)
	s_barrier
	v_and_b32_e32 v17, 0x5f, v49
	v_and_b32_e32 v16, 16, v18
	global_load_dwordx4 v[112:115], v160, s[10:11] offset:256
	global_load_dwordx4 v[116:119], v148, s[10:11] offset:256
	global_load_dwordx4 v[120:123], v150, s[10:11] offset:256
	global_load_dwordx4 v[124:127], v152, s[10:11] offset:256
	global_load_dwordx4 v[96:99], v[154:155], off offset:256
	global_load_dwordx4 v[100:103], v[156:157], off offset:256
	global_load_dwordx4 v[104:107], v[158:159], off offset:256
	global_load_dwordx4 v[108:111], v[164:165], off offset:256
	v_mad_u32_u24 v147, v17, s43, v16
	v_and_b32_e32 v17, 31, v49
	v_and_or_b32 v17, v18, s44, v17
	v_mad_u64_u32 v[166:167], s[12:13], v17, s43, v[16:17]
	ds_read_b128 v[128:131], v166 offset:4608
	ds_read_b128 v[132:135], v147 offset:41472
	ds_read_b128 v[16:19], v166
	ds_read_b128 v[136:139], v166 offset:32
	ds_read_b128 v[140:143], v147 offset:36864
	ds_read_b128 v[202:205], v147 offset:36896
	v_cvt_pk_bf16_f32 v231, v2, v3
	v_cvt_pk_bf16_f32 v230, v4, v5
	v_cvt_pk_bf16_f32 v229, v6, v7
	v_cvt_pk_bf16_f32 v228, v8, v9
	v_cvt_pk_bf16_f32 v227, v10, v11
	v_cvt_pk_bf16_f32 v226, v12, v13
	v_cvt_pk_bf16_f32 v225, v14, v15
	v_mov_b32_e32 v1, v0
	v_mov_b32_e32 v2, v0
	v_mov_b32_e32 v3, v0
	v_mov_b32_e32 v4, v0
	v_mov_b32_e32 v5, v0
	v_mov_b32_e32 v6, v0
	v_mov_b32_e32 v7, v0
	v_mov_b32_e32 v8, v0
	v_mov_b32_e32 v9, v0
	v_mov_b32_e32 v10, v0
	v_mov_b32_e32 v11, v0
	v_mov_b32_e32 v12, v0
	v_mov_b32_e32 v13, v0
	v_mov_b32_e32 v14, v0
	v_mov_b32_e32 v15, v0
	v_cvt_pk_bf16_f32 v250, v60, v61
	v_cvt_pk_bf16_f32 v249, v62, v63
	s_waitcnt lgkmcnt(1)
	v_mfma_f32_32x32x16_bf16 v[48:63], v[16:19], v[140:143], v[0:15]
	v_add_u32_e32 v149, 0xd800, v146
	v_mfma_f32_32x32x16_bf16 v[32:47], v[16:19], v[132:135], v[0:15]
	v_mfma_f32_32x32x16_bf16 v[16:31], v[128:131], v[140:143], v[0:15]
	v_mfma_f32_32x32x16_bf16 v[0:15], v[128:131], v[132:135], v[0:15]
	ds_read_b128 v[128:131], v166 offset:4640
	ds_read_b128 v[132:135], v147 offset:41504
	s_waitcnt vmcnt(15)
	ds_write_b128 v146, v[80:83] offset:18432
	s_waitcnt vmcnt(14)
	ds_write_b128 v146, v[84:87] offset:23040
	s_waitcnt vmcnt(13)
	ds_write_b128 v146, v[88:91] offset:27648
	s_waitcnt vmcnt(12)
	ds_write_b128 v146, v[92:95] offset:32256
	ds_read_b128 v[80:83], v166 offset:64
	ds_read_b128 v[84:87], v166 offset:4672
	ds_read_b128 v[88:91], v147 offset:36928
	ds_read_b128 v[92:95], v147 offset:41536
	s_waitcnt vmcnt(11)
	ds_write_b128 v146, v[64:67] offset:55296
	s_waitcnt vmcnt(10)
	ds_write_b128 v146, v[68:71] offset:59904
	s_waitcnt vmcnt(9)
	ds_write_b128 v146, v[72:75] offset:64512
	s_waitcnt vmcnt(8)
	ds_write_b128 v149, v[76:79] offset:13824
	ds_read_b128 v[64:67], v166 offset:96
	ds_read_b128 v[68:71], v166 offset:4704
	ds_read_b128 v[72:75], v147 offset:36960
	ds_read_b128 v[76:79], v147 offset:41568
	s_waitcnt lgkmcnt(0)
	s_barrier
	v_mfma_f32_32x32x16_bf16 v[48:63], v[136:139], v[202:205], v[48:63]
	v_mfma_f32_32x32x16_bf16 v[32:47], v[136:139], v[132:135], v[32:47]
	v_mfma_f32_32x32x16_bf16 v[16:31], v[128:131], v[202:205], v[16:31]
	v_mfma_f32_32x32x16_bf16 v[0:15], v[128:131], v[132:135], v[0:15]
	v_mfma_f32_32x32x16_bf16 v[48:63], v[80:83], v[88:91], v[48:63]
	v_mfma_f32_32x32x16_bf16 v[32:47], v[80:83], v[92:95], v[32:47]
	v_mfma_f32_32x32x16_bf16 v[16:31], v[84:87], v[88:91], v[16:31]
	v_mfma_f32_32x32x16_bf16 v[0:15], v[84:87], v[92:95], v[0:15]
	v_mfma_f32_32x32x16_bf16 v[48:63], v[64:67], v[72:75], v[48:63]
	v_mfma_f32_32x32x16_bf16 v[32:47], v[64:67], v[76:79], v[32:47]
	v_mfma_f32_32x32x16_bf16 v[16:31], v[68:71], v[72:75], v[16:31]
	v_mfma_f32_32x32x16_bf16 v[0:15], v[68:71], v[76:79], v[0:15]
	global_load_dwordx4 v[128:131], v160, s[10:11] offset:384
	global_load_dwordx4 v[132:135], v148, s[10:11] offset:384
	global_load_dwordx4 v[136:139], v150, s[10:11] offset:384
	global_load_dwordx4 v[140:143], v152, s[10:11] offset:384
	global_load_dwordx4 v[64:67], v[154:155], off offset:384
	global_load_dwordx4 v[68:71], v[156:157], off offset:384
	global_load_dwordx4 v[72:75], v[158:159], off offset:384
	global_load_dwordx4 v[76:79], v[164:165], off offset:384
	ds_read_b128 v[80:83], v166 offset:23040
	ds_read_b128 v[84:87], v147 offset:59904
	ds_read_b128 v[88:91], v166 offset:18432
	ds_read_b128 v[92:95], v166 offset:18464
	ds_read_b128 v[202:205], v147 offset:55296
	ds_read_b128 v[196:199], v147 offset:55328
	s_waitcnt lgkmcnt(1)
	v_mfma_f32_32x32x16_bf16 v[48:63], v[88:91], v[202:205], v[48:63]
	v_mfma_f32_32x32x16_bf16 v[32:47], v[88:91], v[84:87], v[32:47]
	v_mfma_f32_32x32x16_bf16 v[16:31], v[80:83], v[202:205], v[16:31]
	v_mfma_f32_32x32x16_bf16 v[0:15], v[80:83], v[84:87], v[0:15]
	ds_read_b128 v[80:83], v166 offset:23072
	ds_read_b128 v[84:87], v147 offset:59936
	s_waitcnt vmcnt(15)
	ds_write_b128 v146, v[112:115]
	s_waitcnt vmcnt(14)
	ds_write_b128 v146, v[116:119] offset:4608
	s_waitcnt vmcnt(13)
	ds_write_b128 v146, v[120:123] offset:9216
	s_waitcnt vmcnt(12)
	ds_write_b128 v146, v[124:127] offset:13824
	s_waitcnt lgkmcnt(6)
	v_mfma_f32_32x32x16_bf16 v[48:63], v[92:95], v[196:199], v[48:63]
	s_waitcnt lgkmcnt(4)
	v_mfma_f32_32x32x16_bf16 v[32:47], v[92:95], v[84:87], v[32:47]
	v_mfma_f32_32x32x16_bf16 v[16:31], v[80:83], v[196:199], v[16:31]
	v_mfma_f32_32x32x16_bf16 v[0:15], v[80:83], v[84:87], v[0:15]
	ds_read_b128 v[80:83], v166 offset:18496
	ds_read_b128 v[84:87], v166 offset:23104
	ds_read_b128 v[88:91], v147 offset:55360
	ds_read_b128 v[92:95], v147 offset:59968
	s_waitcnt vmcnt(11)
	ds_write_b128 v146, v[96:99] offset:36864
	s_waitcnt vmcnt(10)
	ds_write_b128 v146, v[100:103] offset:41472
	s_waitcnt vmcnt(9)
	ds_write_b128 v146, v[104:107] offset:46080
	s_waitcnt vmcnt(8)
	ds_write_b128 v146, v[108:111] offset:50688
	s_waitcnt lgkmcnt(5)
	v_mfma_f32_32x32x16_bf16 v[48:63], v[80:83], v[88:91], v[48:63]
	s_waitcnt lgkmcnt(4)
	v_mfma_f32_32x32x16_bf16 v[32:47], v[80:83], v[92:95], v[32:47]
	v_mfma_f32_32x32x16_bf16 v[16:31], v[84:87], v[88:91], v[16:31]
	v_mfma_f32_32x32x16_bf16 v[0:15], v[84:87], v[92:95], v[0:15]
	ds_read_b128 v[80:83], v166 offset:18528
	ds_read_b128 v[84:87], v166 offset:23136
	ds_read_b128 v[88:91], v147 offset:55392
	ds_read_b128 v[92:95], v147 offset:60000
	s_waitcnt lgkmcnt(0)
	s_barrier
	v_mfma_f32_32x32x16_bf16 v[48:63], v[80:83], v[88:91], v[48:63]
	v_mfma_f32_32x32x16_bf16 v[32:47], v[80:83], v[92:95], v[32:47]
	v_mfma_f32_32x32x16_bf16 v[16:31], v[84:87], v[88:91], v[16:31]
	v_mfma_f32_32x32x16_bf16 v[0:15], v[84:87], v[92:95], v[0:15]
	global_load_dwordx4 v[96:99], v160, s[10:11] offset:512
	global_load_dwordx4 v[100:103], v148, s[10:11] offset:512
	global_load_dwordx4 v[104:107], v150, s[10:11] offset:512
	global_load_dwordx4 v[108:111], v152, s[10:11] offset:512
	global_load_dwordx4 v[80:83], v[154:155], off offset:512
	global_load_dwordx4 v[84:87], v[156:157], off offset:512
	global_load_dwordx4 v[88:91], v[158:159], off offset:512
	global_load_dwordx4 v[92:95], v[164:165], off offset:512
	ds_read_b128 v[112:115], v166 offset:4608
	ds_read_b128 v[116:119], v147 offset:41472
	ds_read_b128 v[120:123], v166
	ds_read_b128 v[124:127], v166 offset:32
	ds_read_b128 v[196:199], v147 offset:36864
	ds_read_b128 v[202:205], v147 offset:36896
	s_waitcnt lgkmcnt(1)
	v_mfma_f32_32x32x16_bf16 v[48:63], v[120:123], v[196:199], v[48:63]
	v_mfma_f32_32x32x16_bf16 v[32:47], v[120:123], v[116:119], v[32:47]
	v_mfma_f32_32x32x16_bf16 v[16:31], v[112:115], v[196:199], v[16:31]
	v_mfma_f32_32x32x16_bf16 v[0:15], v[112:115], v[116:119], v[0:15]
	ds_read_b128 v[112:115], v166 offset:4640
	ds_read_b128 v[116:119], v147 offset:41504
	s_waitcnt vmcnt(15)
	ds_write_b128 v146, v[128:131] offset:18432
	s_waitcnt vmcnt(14)
	ds_write_b128 v146, v[132:135] offset:23040
	s_waitcnt vmcnt(13)
	ds_write_b128 v146, v[136:139] offset:27648
	s_waitcnt vmcnt(12)
	ds_write_b128 v146, v[140:143] offset:32256
	s_waitcnt lgkmcnt(6)
	v_mfma_f32_32x32x16_bf16 v[48:63], v[124:127], v[202:205], v[48:63]
	s_waitcnt lgkmcnt(4)
	v_mfma_f32_32x32x16_bf16 v[32:47], v[124:127], v[116:119], v[32:47]
	v_mfma_f32_32x32x16_bf16 v[16:31], v[112:115], v[202:205], v[16:31]
	v_mfma_f32_32x32x16_bf16 v[0:15], v[112:115], v[116:119], v[0:15]
	ds_read_b128 v[112:115], v166 offset:64
	ds_read_b128 v[116:119], v166 offset:4672
	ds_read_b128 v[120:123], v147 offset:36928
	ds_read_b128 v[124:127], v147 offset:41536
	s_waitcnt vmcnt(11)
	ds_write_b128 v146, v[64:67] offset:55296
	s_waitcnt vmcnt(10)
	ds_write_b128 v146, v[68:71] offset:59904
	s_waitcnt vmcnt(9)
	ds_write_b128 v146, v[72:75] offset:64512
	s_waitcnt vmcnt(8)
	ds_write_b128 v149, v[76:79] offset:13824
	ds_read_b128 v[64:67], v166 offset:96
	ds_read_b128 v[68:71], v166 offset:4704
	ds_read_b128 v[72:75], v147 offset:36960
	ds_read_b128 v[76:79], v147 offset:41568
	s_waitcnt lgkmcnt(0)
	s_barrier
	v_mfma_f32_32x32x16_bf16 v[48:63], v[112:115], v[120:123], v[48:63]
	v_mfma_f32_32x32x16_bf16 v[32:47], v[112:115], v[124:127], v[32:47]
	v_mfma_f32_32x32x16_bf16 v[16:31], v[116:119], v[120:123], v[16:31]
	v_mfma_f32_32x32x16_bf16 v[0:15], v[116:119], v[124:127], v[0:15]
	v_mfma_f32_32x32x16_bf16 v[48:63], v[64:67], v[72:75], v[48:63]
	v_mfma_f32_32x32x16_bf16 v[32:47], v[64:67], v[76:79], v[32:47]
	v_mfma_f32_32x32x16_bf16 v[16:31], v[68:71], v[72:75], v[16:31]
	v_mfma_f32_32x32x16_bf16 v[0:15], v[68:71], v[76:79], v[0:15]
	global_load_dwordx4 v[112:115], v160, s[10:11] offset:640
	global_load_dwordx4 v[116:119], v148, s[10:11] offset:640
	global_load_dwordx4 v[120:123], v150, s[10:11] offset:640
	global_load_dwordx4 v[124:127], v152, s[10:11] offset:640
	global_load_dwordx4 v[64:67], v[154:155], off offset:640
	global_load_dwordx4 v[68:71], v[156:157], off offset:640
	global_load_dwordx4 v[72:75], v[158:159], off offset:640
	global_load_dwordx4 v[76:79], v[164:165], off offset:640
	ds_read_b128 v[128:131], v166 offset:23040
	ds_read_b128 v[132:135], v147 offset:59904
	ds_read_b128 v[136:139], v166 offset:18432
	ds_read_b128 v[140:143], v166 offset:18464
	ds_read_b128 v[196:199], v147 offset:55296
	ds_read_b128 v[202:205], v147 offset:55328
	s_waitcnt lgkmcnt(1)
	v_mfma_f32_32x32x16_bf16 v[48:63], v[136:139], v[196:199], v[48:63]
	v_mfma_f32_32x32x16_bf16 v[32:47], v[136:139], v[132:135], v[32:47]
	v_mfma_f32_32x32x16_bf16 v[16:31], v[128:131], v[196:199], v[16:31]
	v_mfma_f32_32x32x16_bf16 v[0:15], v[128:131], v[132:135], v[0:15]
	ds_read_b128 v[128:131], v166 offset:23072
	ds_read_b128 v[132:135], v147 offset:59936
	s_waitcnt vmcnt(15)
	ds_write_b128 v146, v[96:99]
	s_waitcnt vmcnt(14)
	ds_write_b128 v146, v[100:103] offset:4608
	s_waitcnt vmcnt(13)
	ds_write_b128 v146, v[104:107] offset:9216
	s_waitcnt vmcnt(12)
	ds_write_b128 v146, v[108:111] offset:13824
	ds_read_b128 v[96:99], v166 offset:18496
	ds_read_b128 v[100:103], v166 offset:23104
	ds_read_b128 v[104:107], v147 offset:55360
	ds_read_b128 v[108:111], v147 offset:59968
	s_waitcnt vmcnt(11)
	ds_write_b128 v146, v[80:83] offset:36864
	s_waitcnt vmcnt(10)
	ds_write_b128 v146, v[84:87] offset:41472
	s_waitcnt vmcnt(9)
	ds_write_b128 v146, v[88:91] offset:46080
	s_waitcnt vmcnt(8)
	ds_write_b128 v146, v[92:95] offset:50688
	ds_read_b128 v[80:83], v166 offset:18528
	ds_read_b128 v[84:87], v166 offset:23136
	ds_read_b128 v[88:91], v147 offset:55392
	ds_read_b128 v[92:95], v147 offset:60000
	s_waitcnt lgkmcnt(0)
	s_barrier
	v_mfma_f32_32x32x16_bf16 v[48:63], v[140:143], v[202:205], v[48:63]
	v_mfma_f32_32x32x16_bf16 v[32:47], v[140:143], v[132:135], v[32:47]
	v_mfma_f32_32x32x16_bf16 v[16:31], v[128:131], v[202:205], v[16:31]
	v_mfma_f32_32x32x16_bf16 v[0:15], v[128:131], v[132:135], v[0:15]
	v_mfma_f32_32x32x16_bf16 v[48:63], v[96:99], v[104:107], v[48:63]
	v_mfma_f32_32x32x16_bf16 v[32:47], v[96:99], v[108:111], v[32:47]
	v_mfma_f32_32x32x16_bf16 v[16:31], v[100:103], v[104:107], v[16:31]
	v_mfma_f32_32x32x16_bf16 v[0:15], v[100:103], v[108:111], v[0:15]
	v_mfma_f32_32x32x16_bf16 v[48:63], v[80:83], v[88:91], v[48:63]
	v_mfma_f32_32x32x16_bf16 v[32:47], v[80:83], v[92:95], v[32:47]
	v_mfma_f32_32x32x16_bf16 v[16:31], v[84:87], v[88:91], v[16:31]
	v_mfma_f32_32x32x16_bf16 v[0:15], v[84:87], v[92:95], v[0:15]
	global_load_dwordx4 v[96:99], v160, s[10:11] offset:768
	global_load_dwordx4 v[100:103], v148, s[10:11] offset:768
	global_load_dwordx4 v[104:107], v150, s[10:11] offset:768
	global_load_dwordx4 v[108:111], v152, s[10:11] offset:768
	global_load_dwordx4 v[80:83], v[154:155], off offset:768
	global_load_dwordx4 v[84:87], v[156:157], off offset:768
	global_load_dwordx4 v[88:91], v[158:159], off offset:768
	global_load_dwordx4 v[92:95], v[164:165], off offset:768
	ds_read_b128 v[128:131], v166 offset:4608
	ds_read_b128 v[132:135], v147 offset:41472
	ds_read_b128 v[136:139], v166
	ds_read_b128 v[140:143], v166 offset:32
	ds_read_b128 v[196:199], v147 offset:36864
	ds_read_b128 v[202:205], v147 offset:36896
	s_waitcnt lgkmcnt(1)
	v_mfma_f32_32x32x16_bf16 v[48:63], v[136:139], v[196:199], v[48:63]
	v_mfma_f32_32x32x16_bf16 v[32:47], v[136:139], v[132:135], v[32:47]
	v_mfma_f32_32x32x16_bf16 v[16:31], v[128:131], v[196:199], v[16:31]
	v_mfma_f32_32x32x16_bf16 v[0:15], v[128:131], v[132:135], v[0:15]
	ds_read_b128 v[128:131], v166 offset:4640
	ds_read_b128 v[132:135], v147 offset:41504
	s_waitcnt vmcnt(15)
	ds_write_b128 v146, v[112:115] offset:18432
	s_waitcnt vmcnt(14)
	ds_write_b128 v146, v[116:119] offset:23040
	s_waitcnt vmcnt(13)
	ds_write_b128 v146, v[120:123] offset:27648
	s_waitcnt vmcnt(12)
	ds_write_b128 v146, v[124:127] offset:32256
	ds_read_b128 v[112:115], v166 offset:64
	ds_read_b128 v[116:119], v166 offset:4672
	ds_read_b128 v[120:123], v147 offset:36928
	ds_read_b128 v[124:127], v147 offset:41536
	s_waitcnt vmcnt(11)
	ds_write_b128 v146, v[64:67] offset:55296
	s_waitcnt vmcnt(10)
	ds_write_b128 v146, v[68:71] offset:59904
	s_waitcnt vmcnt(9)
	ds_write_b128 v146, v[72:75] offset:64512
	s_waitcnt vmcnt(8)
	ds_write_b128 v149, v[76:79] offset:13824
	ds_read_b128 v[64:67], v166 offset:96
	ds_read_b128 v[68:71], v166 offset:4704
	ds_read_b128 v[72:75], v147 offset:36960
	ds_read_b128 v[76:79], v147 offset:41568
	s_waitcnt lgkmcnt(0)
	s_barrier
	v_mfma_f32_32x32x16_bf16 v[48:63], v[140:143], v[202:205], v[48:63]
	v_mfma_f32_32x32x16_bf16 v[32:47], v[140:143], v[132:135], v[32:47]
	v_mfma_f32_32x32x16_bf16 v[16:31], v[128:131], v[202:205], v[16:31]
	v_mfma_f32_32x32x16_bf16 v[0:15], v[128:131], v[132:135], v[0:15]
	v_mfma_f32_32x32x16_bf16 v[48:63], v[112:115], v[120:123], v[48:63]
	v_mfma_f32_32x32x16_bf16 v[32:47], v[112:115], v[124:127], v[32:47]
	v_mfma_f32_32x32x16_bf16 v[16:31], v[116:119], v[120:123], v[16:31]
	v_mfma_f32_32x32x16_bf16 v[0:15], v[116:119], v[124:127], v[0:15]
	v_mfma_f32_32x32x16_bf16 v[48:63], v[64:67], v[72:75], v[48:63]
	v_mfma_f32_32x32x16_bf16 v[32:47], v[64:67], v[76:79], v[32:47]
	v_mfma_f32_32x32x16_bf16 v[16:31], v[68:71], v[72:75], v[16:31]
	v_mfma_f32_32x32x16_bf16 v[0:15], v[68:71], v[76:79], v[0:15]
	global_load_dwordx4 v[112:115], v160, s[10:11] offset:896
	global_load_dwordx4 v[116:119], v148, s[10:11] offset:896
	global_load_dwordx4 v[120:123], v150, s[10:11] offset:896
	global_load_dwordx4 v[124:127], v152, s[10:11] offset:896
	global_load_dwordx4 v[64:67], v[154:155], off offset:896
	global_load_dwordx4 v[68:71], v[156:157], off offset:896
	global_load_dwordx4 v[72:75], v[158:159], off offset:896
	global_load_dwordx4 v[76:79], v[164:165], off offset:896
	ds_read_b128 v[128:131], v166 offset:23040
	ds_read_b128 v[132:135], v147 offset:59904
	ds_read_b128 v[136:139], v166 offset:18432
	ds_read_b128 v[140:143], v166 offset:18464
	ds_read_b128 v[196:199], v147 offset:55296
	ds_read_b128 v[202:205], v147 offset:55328
	s_waitcnt lgkmcnt(1)
	v_mfma_f32_32x32x16_bf16 v[48:63], v[136:139], v[196:199], v[48:63]
	v_mfma_f32_32x32x16_bf16 v[32:47], v[136:139], v[132:135], v[32:47]
	v_mfma_f32_32x32x16_bf16 v[16:31], v[128:131], v[196:199], v[16:31]
	v_mfma_f32_32x32x16_bf16 v[0:15], v[128:131], v[132:135], v[0:15]
	ds_read_b128 v[128:131], v166 offset:23072
	ds_read_b128 v[132:135], v147 offset:59936
	s_waitcnt vmcnt(15)
	ds_write_b128 v146, v[96:99]
	s_waitcnt vmcnt(14)
	ds_write_b128 v146, v[100:103] offset:4608
	s_waitcnt vmcnt(13)
	ds_write_b128 v146, v[104:107] offset:9216
	s_waitcnt vmcnt(12)
	ds_write_b128 v146, v[108:111] offset:13824
	ds_read_b128 v[96:99], v166 offset:18496
	ds_read_b128 v[100:103], v166 offset:23104
	ds_read_b128 v[104:107], v147 offset:55360
	ds_read_b128 v[108:111], v147 offset:59968
	s_waitcnt vmcnt(11)
	ds_write_b128 v146, v[80:83] offset:36864
	s_waitcnt vmcnt(10)
	ds_write_b128 v146, v[84:87] offset:41472
	s_waitcnt vmcnt(9)
	ds_write_b128 v146, v[88:91] offset:46080
	s_waitcnt vmcnt(8)
	ds_write_b128 v146, v[92:95] offset:50688
	ds_read_b128 v[80:83], v166 offset:18528
	ds_read_b128 v[84:87], v166 offset:23136
	ds_read_b128 v[88:91], v147 offset:55392
	ds_read_b128 v[92:95], v147 offset:60000
	s_waitcnt lgkmcnt(0)
	s_barrier
	v_mfma_f32_32x32x16_bf16 v[48:63], v[140:143], v[202:205], v[48:63]
	v_mfma_f32_32x32x16_bf16 v[32:47], v[140:143], v[132:135], v[32:47]
	v_mfma_f32_32x32x16_bf16 v[16:31], v[128:131], v[202:205], v[16:31]
	v_mfma_f32_32x32x16_bf16 v[0:15], v[128:131], v[132:135], v[0:15]
	v_mfma_f32_32x32x16_bf16 v[48:63], v[96:99], v[104:107], v[48:63]
	v_mfma_f32_32x32x16_bf16 v[32:47], v[96:99], v[108:111], v[32:47]
	v_mfma_f32_32x32x16_bf16 v[16:31], v[100:103], v[104:107], v[16:31]
	v_mfma_f32_32x32x16_bf16 v[0:15], v[100:103], v[108:111], v[0:15]
	v_mfma_f32_32x32x16_bf16 v[48:63], v[80:83], v[88:91], v[48:63]
	v_mfma_f32_32x32x16_bf16 v[32:47], v[80:83], v[92:95], v[32:47]
	v_mfma_f32_32x32x16_bf16 v[16:31], v[84:87], v[88:91], v[16:31]
	v_mfma_f32_32x32x16_bf16 v[0:15], v[84:87], v[92:95], v[0:15]
	global_load_dwordx4 v[96:99], v160, s[10:11] offset:1024
	global_load_dwordx4 v[100:103], v148, s[10:11] offset:1024
	global_load_dwordx4 v[104:107], v150, s[10:11] offset:1024
	global_load_dwordx4 v[108:111], v152, s[10:11] offset:1024
	global_load_dwordx4 v[80:83], v[154:155], off offset:1024
	global_load_dwordx4 v[84:87], v[156:157], off offset:1024
	global_load_dwordx4 v[88:91], v[158:159], off offset:1024
	global_load_dwordx4 v[92:95], v[164:165], off offset:1024
	ds_read_b128 v[128:131], v166 offset:4608
	ds_read_b128 v[132:135], v147 offset:41472
	ds_read_b128 v[136:139], v166
	ds_read_b128 v[140:143], v166 offset:32
	ds_read_b128 v[196:199], v147 offset:36864
	ds_read_b128 v[202:205], v147 offset:36896
	s_waitcnt lgkmcnt(1)
	v_mfma_f32_32x32x16_bf16 v[48:63], v[136:139], v[196:199], v[48:63]
	v_mfma_f32_32x32x16_bf16 v[32:47], v[136:139], v[132:135], v[32:47]
	v_mfma_f32_32x32x16_bf16 v[16:31], v[128:131], v[196:199], v[16:31]
	v_mfma_f32_32x32x16_bf16 v[0:15], v[128:131], v[132:135], v[0:15]
	ds_read_b128 v[128:131], v166 offset:4640
	ds_read_b128 v[132:135], v147 offset:41504
	s_waitcnt vmcnt(15)
	ds_write_b128 v146, v[112:115] offset:18432
	s_waitcnt vmcnt(14)
	ds_write_b128 v146, v[116:119] offset:23040
	s_waitcnt vmcnt(13)
	ds_write_b128 v146, v[120:123] offset:27648
	s_waitcnt vmcnt(12)
	ds_write_b128 v146, v[124:127] offset:32256
	ds_read_b128 v[112:115], v166 offset:64
	ds_read_b128 v[116:119], v166 offset:4672
	ds_read_b128 v[120:123], v147 offset:36928
	ds_read_b128 v[124:127], v147 offset:41536
	s_waitcnt vmcnt(11)
	ds_write_b128 v146, v[64:67] offset:55296
	s_waitcnt vmcnt(10)
	ds_write_b128 v146, v[68:71] offset:59904
	s_waitcnt vmcnt(9)
	ds_write_b128 v146, v[72:75] offset:64512
	s_waitcnt vmcnt(8)
	ds_write_b128 v149, v[76:79] offset:13824
	ds_read_b128 v[64:67], v166 offset:96
	ds_read_b128 v[68:71], v166 offset:4704
	ds_read_b128 v[72:75], v147 offset:36960
	ds_read_b128 v[76:79], v147 offset:41568
	s_waitcnt lgkmcnt(0)
	s_barrier
	v_mfma_f32_32x32x16_bf16 v[48:63], v[140:143], v[202:205], v[48:63]
	v_mfma_f32_32x32x16_bf16 v[32:47], v[140:143], v[132:135], v[32:47]
	v_mfma_f32_32x32x16_bf16 v[16:31], v[128:131], v[202:205], v[16:31]
	v_mfma_f32_32x32x16_bf16 v[0:15], v[128:131], v[132:135], v[0:15]
	v_mfma_f32_32x32x16_bf16 v[48:63], v[112:115], v[120:123], v[48:63]
	v_mfma_f32_32x32x16_bf16 v[32:47], v[112:115], v[124:127], v[32:47]
	v_mfma_f32_32x32x16_bf16 v[16:31], v[116:119], v[120:123], v[16:31]
	v_mfma_f32_32x32x16_bf16 v[0:15], v[116:119], v[124:127], v[0:15]
	v_mfma_f32_32x32x16_bf16 v[48:63], v[64:67], v[72:75], v[48:63]
	v_mfma_f32_32x32x16_bf16 v[32:47], v[64:67], v[76:79], v[32:47]
	v_mfma_f32_32x32x16_bf16 v[16:31], v[68:71], v[72:75], v[16:31]
	v_mfma_f32_32x32x16_bf16 v[0:15], v[68:71], v[76:79], v[0:15]
	global_load_dwordx4 v[112:115], v160, s[10:11] offset:1152
	global_load_dwordx4 v[116:119], v148, s[10:11] offset:1152
	global_load_dwordx4 v[120:123], v150, s[10:11] offset:1152
	global_load_dwordx4 v[124:127], v152, s[10:11] offset:1152
	global_load_dwordx4 v[64:67], v[154:155], off offset:1152
	global_load_dwordx4 v[68:71], v[156:157], off offset:1152
	global_load_dwordx4 v[72:75], v[158:159], off offset:1152
	global_load_dwordx4 v[76:79], v[164:165], off offset:1152
	ds_read_b128 v[128:131], v166 offset:23040
	ds_read_b128 v[132:135], v147 offset:59904
	ds_read_b128 v[136:139], v166 offset:18432
	ds_read_b128 v[140:143], v166 offset:18464
	ds_read_b128 v[196:199], v147 offset:55296
	ds_read_b128 v[202:205], v147 offset:55328
	s_waitcnt lgkmcnt(1)
	v_mfma_f32_32x32x16_bf16 v[48:63], v[136:139], v[196:199], v[48:63]
	v_mfma_f32_32x32x16_bf16 v[32:47], v[136:139], v[132:135], v[32:47]
	v_mfma_f32_32x32x16_bf16 v[16:31], v[128:131], v[196:199], v[16:31]
	v_mfma_f32_32x32x16_bf16 v[0:15], v[128:131], v[132:135], v[0:15]
	ds_read_b128 v[128:131], v166 offset:23072
	ds_read_b128 v[132:135], v147 offset:59936
	s_waitcnt vmcnt(15)
	ds_write_b128 v146, v[96:99]
	s_waitcnt vmcnt(14)
	ds_write_b128 v146, v[100:103] offset:4608
	s_waitcnt vmcnt(13)
	ds_write_b128 v146, v[104:107] offset:9216
	s_waitcnt vmcnt(12)
	ds_write_b128 v146, v[108:111] offset:13824
	ds_read_b128 v[96:99], v166 offset:18496
	ds_read_b128 v[100:103], v166 offset:23104
	ds_read_b128 v[104:107], v147 offset:55360
	ds_read_b128 v[108:111], v147 offset:59968
	s_waitcnt vmcnt(11)
	ds_write_b128 v146, v[80:83] offset:36864
	s_waitcnt vmcnt(10)
	ds_write_b128 v146, v[84:87] offset:41472
	s_waitcnt vmcnt(9)
	ds_write_b128 v146, v[88:91] offset:46080
	s_waitcnt vmcnt(8)
	ds_write_b128 v146, v[92:95] offset:50688
	ds_read_b128 v[80:83], v166 offset:18528
	ds_read_b128 v[84:87], v166 offset:23136
	ds_read_b128 v[88:91], v147 offset:55392
	ds_read_b128 v[92:95], v147 offset:60000
	s_waitcnt lgkmcnt(0)
	s_barrier
	v_mfma_f32_32x32x16_bf16 v[48:63], v[140:143], v[202:205], v[48:63]
	v_mfma_f32_32x32x16_bf16 v[32:47], v[140:143], v[132:135], v[32:47]
	v_mfma_f32_32x32x16_bf16 v[16:31], v[128:131], v[202:205], v[16:31]
	v_mfma_f32_32x32x16_bf16 v[0:15], v[128:131], v[132:135], v[0:15]
	v_mfma_f32_32x32x16_bf16 v[48:63], v[96:99], v[104:107], v[48:63]
	v_mfma_f32_32x32x16_bf16 v[32:47], v[96:99], v[108:111], v[32:47]
	v_mfma_f32_32x32x16_bf16 v[16:31], v[100:103], v[104:107], v[16:31]
	v_mfma_f32_32x32x16_bf16 v[0:15], v[100:103], v[108:111], v[0:15]
	v_mfma_f32_32x32x16_bf16 v[48:63], v[80:83], v[88:91], v[48:63]
	v_mfma_f32_32x32x16_bf16 v[32:47], v[80:83], v[92:95], v[32:47]
	v_mfma_f32_32x32x16_bf16 v[16:31], v[84:87], v[88:91], v[16:31]
	v_mfma_f32_32x32x16_bf16 v[0:15], v[84:87], v[92:95], v[0:15]
	global_load_dwordx4 v[96:99], v160, s[10:11] offset:1280
	global_load_dwordx4 v[100:103], v148, s[10:11] offset:1280
	global_load_dwordx4 v[104:107], v150, s[10:11] offset:1280
	global_load_dwordx4 v[108:111], v152, s[10:11] offset:1280
	global_load_dwordx4 v[80:83], v[154:155], off offset:1280
	global_load_dwordx4 v[84:87], v[156:157], off offset:1280
	global_load_dwordx4 v[88:91], v[158:159], off offset:1280
	global_load_dwordx4 v[92:95], v[164:165], off offset:1280
	ds_read_b128 v[128:131], v166 offset:4608
	ds_read_b128 v[132:135], v147 offset:41472
	ds_read_b128 v[136:139], v166
	ds_read_b128 v[140:143], v166 offset:32
	ds_read_b128 v[196:199], v147 offset:36864
	ds_read_b128 v[202:205], v147 offset:36896
	s_waitcnt lgkmcnt(1)
	v_mfma_f32_32x32x16_bf16 v[48:63], v[136:139], v[196:199], v[48:63]
	v_mfma_f32_32x32x16_bf16 v[32:47], v[136:139], v[132:135], v[32:47]
	v_mfma_f32_32x32x16_bf16 v[16:31], v[128:131], v[196:199], v[16:31]
	v_mfma_f32_32x32x16_bf16 v[0:15], v[128:131], v[132:135], v[0:15]
	ds_read_b128 v[128:131], v166 offset:4640
	ds_read_b128 v[132:135], v147 offset:41504
	s_waitcnt vmcnt(15)
	ds_write_b128 v146, v[112:115] offset:18432
	s_waitcnt vmcnt(14)
	ds_write_b128 v146, v[116:119] offset:23040
	s_waitcnt vmcnt(13)
	ds_write_b128 v146, v[120:123] offset:27648
	s_waitcnt vmcnt(12)
	ds_write_b128 v146, v[124:127] offset:32256
	ds_read_b128 v[112:115], v166 offset:64
	ds_read_b128 v[116:119], v166 offset:4672
	ds_read_b128 v[120:123], v147 offset:36928
	ds_read_b128 v[124:127], v147 offset:41536
	s_waitcnt vmcnt(11)
	ds_write_b128 v146, v[64:67] offset:55296
	s_waitcnt vmcnt(10)
	ds_write_b128 v146, v[68:71] offset:59904
	s_waitcnt vmcnt(9)
	ds_write_b128 v146, v[72:75] offset:64512
	s_waitcnt vmcnt(8)
	ds_write_b128 v149, v[76:79] offset:13824
	ds_read_b128 v[64:67], v166 offset:96
	ds_read_b128 v[68:71], v166 offset:4704
	ds_read_b128 v[72:75], v147 offset:36960
	ds_read_b128 v[76:79], v147 offset:41568
	s_waitcnt lgkmcnt(0)
	s_barrier
	v_mfma_f32_32x32x16_bf16 v[48:63], v[140:143], v[202:205], v[48:63]
	v_mfma_f32_32x32x16_bf16 v[32:47], v[140:143], v[132:135], v[32:47]
	v_mfma_f32_32x32x16_bf16 v[16:31], v[128:131], v[202:205], v[16:31]
	v_mfma_f32_32x32x16_bf16 v[0:15], v[128:131], v[132:135], v[0:15]
	v_mfma_f32_32x32x16_bf16 v[48:63], v[112:115], v[120:123], v[48:63]
	v_mfma_f32_32x32x16_bf16 v[32:47], v[112:115], v[124:127], v[32:47]
	v_mfma_f32_32x32x16_bf16 v[16:31], v[116:119], v[120:123], v[16:31]
	v_mfma_f32_32x32x16_bf16 v[0:15], v[116:119], v[124:127], v[0:15]
	v_mfma_f32_32x32x16_bf16 v[48:63], v[64:67], v[72:75], v[48:63]
	v_mfma_f32_32x32x16_bf16 v[32:47], v[64:67], v[76:79], v[32:47]
	v_mfma_f32_32x32x16_bf16 v[16:31], v[68:71], v[72:75], v[16:31]
	v_mfma_f32_32x32x16_bf16 v[0:15], v[68:71], v[76:79], v[0:15]
	global_load_dwordx4 v[112:115], v160, s[10:11] offset:1408
	global_load_dwordx4 v[116:119], v148, s[10:11] offset:1408
	global_load_dwordx4 v[120:123], v150, s[10:11] offset:1408
	global_load_dwordx4 v[124:127], v152, s[10:11] offset:1408
	global_load_dwordx4 v[64:67], v[154:155], off offset:1408
	global_load_dwordx4 v[68:71], v[156:157], off offset:1408
	global_load_dwordx4 v[72:75], v[158:159], off offset:1408
	global_load_dwordx4 v[76:79], v[164:165], off offset:1408
	ds_read_b128 v[128:131], v166 offset:23040
	ds_read_b128 v[132:135], v147 offset:59904
	ds_read_b128 v[136:139], v166 offset:18432
	ds_read_b128 v[140:143], v166 offset:18464
	ds_read_b128 v[196:199], v147 offset:55296
	ds_read_b128 v[202:205], v147 offset:55328
	s_waitcnt lgkmcnt(1)
	v_mfma_f32_32x32x16_bf16 v[48:63], v[136:139], v[196:199], v[48:63]
	v_mfma_f32_32x32x16_bf16 v[32:47], v[136:139], v[132:135], v[32:47]
	v_mfma_f32_32x32x16_bf16 v[16:31], v[128:131], v[196:199], v[16:31]
	v_mfma_f32_32x32x16_bf16 v[0:15], v[128:131], v[132:135], v[0:15]
	ds_read_b128 v[128:131], v166 offset:23072
	ds_read_b128 v[132:135], v147 offset:59936
	s_waitcnt vmcnt(15)
	ds_write_b128 v146, v[96:99]
	s_waitcnt vmcnt(14)
	ds_write_b128 v146, v[100:103] offset:4608
	s_waitcnt vmcnt(13)
	ds_write_b128 v146, v[104:107] offset:9216
	s_waitcnt vmcnt(12)
	ds_write_b128 v146, v[108:111] offset:13824
	ds_read_b128 v[96:99], v166 offset:18496
	ds_read_b128 v[100:103], v166 offset:23104
	ds_read_b128 v[104:107], v147 offset:55360
	ds_read_b128 v[108:111], v147 offset:59968
	s_waitcnt vmcnt(11)
	ds_write_b128 v146, v[80:83] offset:36864
	s_waitcnt vmcnt(10)
	ds_write_b128 v146, v[84:87] offset:41472
	s_waitcnt vmcnt(9)
	ds_write_b128 v146, v[88:91] offset:46080
	s_waitcnt vmcnt(8)
	ds_write_b128 v146, v[92:95] offset:50688
	ds_read_b128 v[80:83], v166 offset:18528
	ds_read_b128 v[84:87], v166 offset:23136
	ds_read_b128 v[88:91], v147 offset:55392
	ds_read_b128 v[92:95], v147 offset:60000
	s_waitcnt lgkmcnt(0)
	s_barrier
	v_mfma_f32_32x32x16_bf16 v[48:63], v[140:143], v[202:205], v[48:63]
	v_mfma_f32_32x32x16_bf16 v[32:47], v[140:143], v[132:135], v[32:47]
	v_mfma_f32_32x32x16_bf16 v[16:31], v[128:131], v[202:205], v[16:31]
	v_mfma_f32_32x32x16_bf16 v[0:15], v[128:131], v[132:135], v[0:15]
	v_mfma_f32_32x32x16_bf16 v[48:63], v[96:99], v[104:107], v[48:63]
	v_mfma_f32_32x32x16_bf16 v[32:47], v[96:99], v[108:111], v[32:47]
	v_mfma_f32_32x32x16_bf16 v[16:31], v[100:103], v[104:107], v[16:31]
	v_mfma_f32_32x32x16_bf16 v[0:15], v[100:103], v[108:111], v[0:15]
	v_mfma_f32_32x32x16_bf16 v[48:63], v[80:83], v[88:91], v[48:63]
	v_mfma_f32_32x32x16_bf16 v[32:47], v[80:83], v[92:95], v[32:47]
	v_mfma_f32_32x32x16_bf16 v[16:31], v[84:87], v[88:91], v[16:31]
	v_mfma_f32_32x32x16_bf16 v[0:15], v[84:87], v[92:95], v[0:15]
	global_load_dwordx4 v[80:83], v160, s[10:11] offset:1536
	global_load_dwordx4 v[84:87], v148, s[10:11] offset:1536
	global_load_dwordx4 v[88:91], v150, s[10:11] offset:1536
	global_load_dwordx4 v[92:95], v152, s[10:11] offset:1536
	global_load_dwordx4 v[96:99], v[154:155], off offset:1536
	global_load_dwordx4 v[100:103], v[156:157], off offset:1536
	global_load_dwordx4 v[104:107], v[158:159], off offset:1536
	global_load_dwordx4 v[108:111], v[164:165], off offset:1536
	ds_read_b128 v[128:131], v166 offset:4608
	ds_read_b128 v[132:135], v147 offset:41472
	ds_read_b128 v[136:139], v166
	ds_read_b128 v[140:143], v166 offset:32
	ds_read_b128 v[196:199], v147 offset:36864
	ds_read_b128 v[202:205], v147 offset:36896
	s_waitcnt lgkmcnt(1)
	v_mfma_f32_32x32x16_bf16 v[48:63], v[136:139], v[196:199], v[48:63]
	v_mfma_f32_32x32x16_bf16 v[32:47], v[136:139], v[132:135], v[32:47]
	v_mfma_f32_32x32x16_bf16 v[16:31], v[128:131], v[196:199], v[16:31]
	v_mfma_f32_32x32x16_bf16 v[0:15], v[128:131], v[132:135], v[0:15]
	ds_read_b128 v[128:131], v166 offset:4640
	ds_read_b128 v[132:135], v147 offset:41504
	s_waitcnt vmcnt(15)
	ds_write_b128 v146, v[112:115] offset:18432
	s_waitcnt vmcnt(14)
	ds_write_b128 v146, v[116:119] offset:23040
	s_waitcnt vmcnt(13)
	ds_write_b128 v146, v[120:123] offset:27648
	s_waitcnt vmcnt(12)
	ds_write_b128 v146, v[124:127] offset:32256
	ds_read_b128 v[112:115], v166 offset:64
	ds_read_b128 v[116:119], v166 offset:4672
	ds_read_b128 v[120:123], v147 offset:36928
	ds_read_b128 v[124:127], v147 offset:41536
	s_waitcnt vmcnt(11)
	ds_write_b128 v146, v[64:67] offset:55296
	s_waitcnt vmcnt(10)
	ds_write_b128 v146, v[68:71] offset:59904
	s_waitcnt vmcnt(9)
	ds_write_b128 v146, v[72:75] offset:64512
	s_waitcnt vmcnt(8)
	ds_write_b128 v149, v[76:79] offset:13824
	ds_read_b128 v[64:67], v166 offset:96
	ds_read_b128 v[68:71], v166 offset:4704
	ds_read_b128 v[72:75], v147 offset:36960
	ds_read_b128 v[76:79], v147 offset:41568
	s_waitcnt lgkmcnt(0)
	s_barrier
	v_mfma_f32_32x32x16_bf16 v[48:63], v[140:143], v[202:205], v[48:63]
	v_mfma_f32_32x32x16_bf16 v[32:47], v[140:143], v[132:135], v[32:47]
	v_mfma_f32_32x32x16_bf16 v[16:31], v[128:131], v[202:205], v[16:31]
	v_mfma_f32_32x32x16_bf16 v[0:15], v[128:131], v[132:135], v[0:15]
	v_mfma_f32_32x32x16_bf16 v[48:63], v[112:115], v[120:123], v[48:63]
	v_mfma_f32_32x32x16_bf16 v[32:47], v[112:115], v[124:127], v[32:47]
	v_mfma_f32_32x32x16_bf16 v[16:31], v[116:119], v[120:123], v[16:31]
	v_mfma_f32_32x32x16_bf16 v[0:15], v[116:119], v[124:127], v[0:15]
	v_mfma_f32_32x32x16_bf16 v[48:63], v[64:67], v[72:75], v[48:63]
	v_mfma_f32_32x32x16_bf16 v[32:47], v[64:67], v[76:79], v[32:47]
	v_mfma_f32_32x32x16_bf16 v[16:31], v[68:71], v[72:75], v[16:31]
	v_mfma_f32_32x32x16_bf16 v[0:15], v[68:71], v[76:79], v[0:15]
	global_load_dwordx4 v[64:67], v160, s[10:11] offset:1664
	global_load_dwordx4 v[68:71], v148, s[10:11] offset:1664
	global_load_dwordx4 v[72:75], v150, s[10:11] offset:1664
	global_load_dwordx4 v[76:79], v152, s[10:11] offset:1664
	global_load_dwordx4 v[112:115], v[154:155], off offset:1664
	global_load_dwordx4 v[116:119], v[156:157], off offset:1664
	global_load_dwordx4 v[120:123], v[158:159], off offset:1664
	global_load_dwordx4 v[124:127], v[164:165], off offset:1664
	ds_read_b128 v[128:131], v166 offset:23040
	ds_read_b128 v[132:135], v147 offset:59904
	ds_read_b128 v[136:139], v166 offset:18432
	ds_read_b128 v[140:143], v166 offset:18464
	ds_read_b128 v[196:199], v147 offset:55296
	ds_read_b128 v[202:205], v147 offset:55328
	s_waitcnt lgkmcnt(1)
	v_mfma_f32_32x32x16_bf16 v[48:63], v[136:139], v[196:199], v[48:63]
	v_mfma_f32_32x32x16_bf16 v[32:47], v[136:139], v[132:135], v[32:47]
	v_mfma_f32_32x32x16_bf16 v[16:31], v[128:131], v[196:199], v[16:31]
	v_mfma_f32_32x32x16_bf16 v[0:15], v[128:131], v[132:135], v[0:15]
	ds_read_b128 v[128:131], v166 offset:23072
	ds_read_b128 v[132:135], v147 offset:59936
	s_waitcnt vmcnt(15)
	ds_write_b128 v146, v[80:83]
	s_waitcnt vmcnt(14)
	ds_write_b128 v146, v[84:87] offset:4608
	s_waitcnt vmcnt(13)
	ds_write_b128 v146, v[88:91] offset:9216
	s_waitcnt vmcnt(12)
	ds_write_b128 v146, v[92:95] offset:13824
	ds_read_b128 v[80:83], v166 offset:18496
	ds_read_b128 v[84:87], v166 offset:23104
	ds_read_b128 v[88:91], v147 offset:55360
	ds_read_b128 v[92:95], v147 offset:59968
	s_waitcnt vmcnt(11)
	ds_write_b128 v146, v[96:99] offset:36864
	s_waitcnt vmcnt(10)
	ds_write_b128 v146, v[100:103] offset:41472
	s_waitcnt vmcnt(9)
	ds_write_b128 v146, v[104:107] offset:46080
	s_waitcnt vmcnt(8)
	ds_write_b128 v146, v[108:111] offset:50688
	s_waitcnt lgkmcnt(14)
	v_mfma_f32_32x32x16_bf16 v[48:63], v[140:143], v[202:205], v[48:63]
	s_waitcnt lgkmcnt(12)
	v_mfma_f32_32x32x16_bf16 v[32:47], v[140:143], v[132:135], v[32:47]
	v_mfma_f32_32x32x16_bf16 v[16:31], v[128:131], v[202:205], v[16:31]
	v_mfma_f32_32x32x16_bf16 v[0:15], v[128:131], v[132:135], v[0:15]
	s_waitcnt lgkmcnt(5)
	v_mfma_f32_32x32x16_bf16 v[48:63], v[80:83], v[88:91], v[48:63]
	s_waitcnt lgkmcnt(4)
	v_mfma_f32_32x32x16_bf16 v[32:47], v[80:83], v[92:95], v[32:47]
	v_mfma_f32_32x32x16_bf16 v[16:31], v[84:87], v[88:91], v[16:31]
	v_mfma_f32_32x32x16_bf16 v[0:15], v[84:87], v[92:95], v[0:15]
	ds_read_b128 v[80:83], v166 offset:18528
	ds_read_b128 v[84:87], v166 offset:23136
	ds_read_b128 v[88:91], v147 offset:55392
	ds_read_b128 v[92:95], v147 offset:60000
	s_waitcnt lgkmcnt(0)
	s_barrier
	v_mfma_f32_32x32x16_bf16 v[48:63], v[80:83], v[88:91], v[48:63]
	v_mfma_f32_32x32x16_bf16 v[32:47], v[80:83], v[92:95], v[32:47]
	v_mfma_f32_32x32x16_bf16 v[16:31], v[84:87], v[88:91], v[16:31]
	v_mfma_f32_32x32x16_bf16 v[0:15], v[84:87], v[92:95], v[0:15]
	global_load_dwordx4 v[80:83], v160, s[10:11] offset:1792
	global_load_dwordx4 v[84:87], v148, s[10:11] offset:1792
	global_load_dwordx4 v[88:91], v150, s[10:11] offset:1792
	global_load_dwordx4 v[92:95], v152, s[10:11] offset:1792
	global_load_dwordx4 v[96:99], v[154:155], off offset:1792
	global_load_dwordx4 v[100:103], v[156:157], off offset:1792
	global_load_dwordx4 v[104:107], v[158:159], off offset:1792
	global_load_dwordx4 v[108:111], v[164:165], off offset:1792
	ds_read_b128 v[128:131], v166 offset:4608
	ds_read_b128 v[132:135], v147 offset:41472
	ds_read_b128 v[136:139], v166
	ds_read_b128 v[140:143], v166 offset:32
	ds_read_b128 v[196:199], v147 offset:36864
	ds_read_b128 v[202:205], v147 offset:36896
	s_waitcnt lgkmcnt(1)
	v_mfma_f32_32x32x16_bf16 v[48:63], v[136:139], v[196:199], v[48:63]
	v_mfma_f32_32x32x16_bf16 v[32:47], v[136:139], v[132:135], v[32:47]
	v_mfma_f32_32x32x16_bf16 v[16:31], v[128:131], v[196:199], v[16:31]
	v_mfma_f32_32x32x16_bf16 v[0:15], v[128:131], v[132:135], v[0:15]
	ds_read_b128 v[128:131], v166 offset:4640
	ds_read_b128 v[132:135], v147 offset:41504
	s_waitcnt vmcnt(15)
	ds_write_b128 v146, v[64:67] offset:18432
	s_waitcnt vmcnt(14)
	ds_write_b128 v146, v[68:71] offset:23040
	s_waitcnt vmcnt(13)
	ds_write_b128 v146, v[72:75] offset:27648
	s_waitcnt vmcnt(12)
	ds_write_b128 v146, v[76:79] offset:32256
	ds_read_b128 v[64:67], v166 offset:64
	ds_read_b128 v[68:71], v166 offset:4672
	ds_read_b128 v[72:75], v147 offset:36928
	ds_read_b128 v[76:79], v147 offset:41536
	s_waitcnt vmcnt(11)
	ds_write_b128 v146, v[112:115] offset:55296
	s_waitcnt vmcnt(10)
	ds_write_b128 v146, v[116:119] offset:59904
	s_waitcnt vmcnt(9)
	ds_write_b128 v146, v[120:123] offset:64512
	s_waitcnt vmcnt(8)
	ds_write_b128 v149, v[124:127] offset:13824
	s_waitcnt lgkmcnt(14)
	v_mfma_f32_32x32x16_bf16 v[48:63], v[140:143], v[202:205], v[48:63]
	s_waitcnt lgkmcnt(12)
	v_mfma_f32_32x32x16_bf16 v[32:47], v[140:143], v[132:135], v[32:47]
	v_mfma_f32_32x32x16_bf16 v[16:31], v[128:131], v[202:205], v[16:31]
	v_mfma_f32_32x32x16_bf16 v[0:15], v[128:131], v[132:135], v[0:15]
	s_waitcnt lgkmcnt(5)
	v_mfma_f32_32x32x16_bf16 v[48:63], v[64:67], v[72:75], v[48:63]
	s_waitcnt lgkmcnt(4)
	v_mfma_f32_32x32x16_bf16 v[32:47], v[64:67], v[76:79], v[32:47]
	v_mfma_f32_32x32x16_bf16 v[16:31], v[68:71], v[72:75], v[16:31]
	v_mfma_f32_32x32x16_bf16 v[0:15], v[68:71], v[76:79], v[0:15]
	ds_read_b128 v[64:67], v166 offset:96
	ds_read_b128 v[68:71], v166 offset:4704
	ds_read_b128 v[72:75], v147 offset:36960
	ds_read_b128 v[76:79], v147 offset:41568
	s_waitcnt lgkmcnt(0)
	s_barrier
	v_mfma_f32_32x32x16_bf16 v[48:63], v[64:67], v[72:75], v[48:63]
	v_mfma_f32_32x32x16_bf16 v[32:47], v[64:67], v[76:79], v[32:47]
	v_mfma_f32_32x32x16_bf16 v[16:31], v[68:71], v[72:75], v[16:31]
	v_mfma_f32_32x32x16_bf16 v[0:15], v[68:71], v[76:79], v[0:15]
	global_load_dwordx4 v[64:67], v160, s[10:11] offset:1920
	global_load_dwordx4 v[68:71], v148, s[10:11] offset:1920
	global_load_dwordx4 v[72:75], v150, s[10:11] offset:1920
	global_load_dwordx4 v[76:79], v152, s[10:11] offset:1920
	global_load_dwordx4 v[112:115], v[154:155], off offset:1920
	global_load_dwordx4 v[116:119], v[156:157], off offset:1920
	global_load_dwordx4 v[120:123], v[158:159], off offset:1920
	global_load_dwordx4 v[124:127], v[164:165], off offset:1920
	ds_read_b128 v[128:131], v166 offset:23040
	ds_read_b128 v[132:135], v147 offset:59904
	ds_read_b128 v[136:139], v166 offset:18432
	ds_read_b128 v[140:143], v166 offset:18464
	ds_read_b128 v[150:153], v147 offset:55296
	ds_read_b128 v[154:157], v147 offset:55328
	s_waitcnt lgkmcnt(1)
	v_mfma_f32_32x32x16_bf16 v[48:63], v[136:139], v[150:153], v[48:63]
	v_mfma_f32_32x32x16_bf16 v[32:47], v[136:139], v[132:135], v[32:47]
	v_mfma_f32_32x32x16_bf16 v[16:31], v[128:131], v[150:153], v[16:31]
	v_mfma_f32_32x32x16_bf16 v[0:15], v[128:131], v[132:135], v[0:15]
	ds_read_b128 v[128:131], v166 offset:23072
	ds_read_b128 v[132:135], v147 offset:59936
	s_waitcnt vmcnt(15)
	ds_write_b128 v146, v[80:83]
	s_waitcnt vmcnt(14)
	ds_write_b128 v146, v[84:87] offset:4608
	s_waitcnt vmcnt(13)
	ds_write_b128 v146, v[88:91] offset:9216
	s_waitcnt vmcnt(12)
	ds_write_b128 v146, v[92:95] offset:13824
	ds_read_b128 v[80:83], v166 offset:18496
	ds_read_b128 v[84:87], v166 offset:23104
	ds_read_b128 v[88:91], v147 offset:55360
	ds_read_b128 v[92:95], v147 offset:59968
	s_waitcnt vmcnt(11)
	ds_write_b128 v146, v[96:99] offset:36864
	s_waitcnt vmcnt(10)
	ds_write_b128 v146, v[100:103] offset:41472
	s_waitcnt vmcnt(9)
	ds_write_b128 v146, v[104:107] offset:46080
	s_waitcnt vmcnt(8)
	ds_write_b128 v146, v[108:111] offset:50688
	s_waitcnt lgkmcnt(14)
	v_mfma_f32_32x32x16_bf16 v[48:63], v[140:143], v[154:157], v[48:63]
	s_waitcnt lgkmcnt(12)
	v_mfma_f32_32x32x16_bf16 v[32:47], v[140:143], v[132:135], v[32:47]
	v_mfma_f32_32x32x16_bf16 v[16:31], v[128:131], v[154:157], v[16:31]
	v_mfma_f32_32x32x16_bf16 v[0:15], v[128:131], v[132:135], v[0:15]
	s_waitcnt lgkmcnt(5)
	v_mfma_f32_32x32x16_bf16 v[48:63], v[80:83], v[88:91], v[48:63]
	s_waitcnt lgkmcnt(4)
	v_mfma_f32_32x32x16_bf16 v[32:47], v[80:83], v[92:95], v[32:47]
	v_mfma_f32_32x32x16_bf16 v[16:31], v[84:87], v[88:91], v[16:31]
	v_mfma_f32_32x32x16_bf16 v[0:15], v[84:87], v[92:95], v[0:15]
	ds_read_b128 v[80:83], v166 offset:18528
	ds_read_b128 v[84:87], v166 offset:23136
	ds_read_b128 v[88:91], v147 offset:55392
	ds_read_b128 v[92:95], v147 offset:60000
	s_waitcnt lgkmcnt(0)
	s_barrier
	v_mfma_f32_32x32x16_bf16 v[48:63], v[80:83], v[88:91], v[48:63]
	v_mfma_f32_32x32x16_bf16 v[32:47], v[80:83], v[92:95], v[32:47]
	v_mfma_f32_32x32x16_bf16 v[16:31], v[84:87], v[88:91], v[16:31]
	v_mfma_f32_32x32x16_bf16 v[0:15], v[84:87], v[92:95], v[0:15]
	ds_read_b128 v[80:83], v166 offset:4608
	ds_read_b128 v[84:87], v147 offset:41472
	ds_read_b128 v[88:91], v166
	ds_read_b128 v[92:95], v166 offset:32
	ds_read_b128 v[96:99], v147 offset:36864
	ds_read_b128 v[100:103], v147 offset:36896
	s_waitcnt lgkmcnt(1)
	v_mfma_f32_32x32x16_bf16 v[48:63], v[88:91], v[96:99], v[48:63]
	v_mfma_f32_32x32x16_bf16 v[32:47], v[88:91], v[84:87], v[32:47]
	v_mfma_f32_32x32x16_bf16 v[16:31], v[80:83], v[96:99], v[16:31]
	v_mfma_f32_32x32x16_bf16 v[0:15], v[80:83], v[84:87], v[0:15]
	ds_read_b128 v[80:83], v166 offset:4640
	ds_read_b128 v[84:87], v147 offset:41504
	s_waitcnt vmcnt(7)
	ds_write_b128 v146, v[64:67] offset:18432
	s_waitcnt vmcnt(6)
	ds_write_b128 v146, v[68:71] offset:23040
	s_waitcnt vmcnt(5)
	ds_write_b128 v146, v[72:75] offset:27648
	s_waitcnt vmcnt(4)
	ds_write_b128 v146, v[76:79] offset:32256
	ds_read_b128 v[64:67], v166 offset:64
	ds_read_b128 v[68:71], v166 offset:4672
	ds_read_b128 v[72:75], v147 offset:36928
	ds_read_b128 v[76:79], v147 offset:41536
	s_waitcnt vmcnt(3)
	ds_write_b128 v146, v[112:115] offset:55296
	s_waitcnt vmcnt(2)
	ds_write_b128 v146, v[116:119] offset:59904
	s_waitcnt vmcnt(1)
	ds_write_b128 v146, v[120:123] offset:64512
	s_waitcnt vmcnt(0)
	ds_write_b128 v149, v[124:127] offset:13824
	s_waitcnt lgkmcnt(14)
	v_mfma_f32_32x32x16_bf16 v[48:63], v[92:95], v[100:103], v[48:63]
	s_waitcnt lgkmcnt(12)
	v_mfma_f32_32x32x16_bf16 v[32:47], v[92:95], v[84:87], v[32:47]
	v_mfma_f32_32x32x16_bf16 v[16:31], v[80:83], v[100:103], v[16:31]
	v_mfma_f32_32x32x16_bf16 v[0:15], v[80:83], v[84:87], v[0:15]
	s_waitcnt lgkmcnt(5)
	v_mfma_f32_32x32x16_bf16 v[48:63], v[64:67], v[72:75], v[48:63]
	s_waitcnt lgkmcnt(4)
	v_mfma_f32_32x32x16_bf16 v[32:47], v[64:67], v[76:79], v[32:47]
	v_mfma_f32_32x32x16_bf16 v[16:31], v[68:71], v[72:75], v[16:31]
	v_mfma_f32_32x32x16_bf16 v[0:15], v[68:71], v[76:79], v[0:15]
	ds_read_b128 v[64:67], v166 offset:96
	ds_read_b128 v[68:71], v166 offset:4704
	ds_read_b128 v[72:75], v147 offset:36960
	ds_read_b128 v[76:79], v147 offset:41568
	s_waitcnt lgkmcnt(0)
	s_barrier
	v_mfma_f32_32x32x16_bf16 v[48:63], v[64:67], v[72:75], v[48:63]
	v_mfma_f32_32x32x16_bf16 v[32:47], v[64:67], v[76:79], v[32:47]
	v_mfma_f32_32x32x16_bf16 v[16:31], v[68:71], v[72:75], v[16:31]
	v_mfma_f32_32x32x16_bf16 v[0:15], v[68:71], v[76:79], v[0:15]
	ds_read_b128 v[64:67], v166 offset:23040
	ds_read_b128 v[68:71], v147 offset:59904
	ds_read_b128 v[72:75], v166 offset:18432
	ds_read_b128 v[76:79], v166 offset:18464
	ds_read_b128 v[80:83], v147 offset:55296
	ds_read_b128 v[84:87], v147 offset:55328
	s_waitcnt lgkmcnt(1)
	v_mfma_f32_32x32x16_bf16 v[48:63], v[72:75], v[80:83], v[48:63]
	v_mfma_f32_32x32x16_bf16 v[32:47], v[72:75], v[68:71], v[32:47]
	v_mfma_f32_32x32x16_bf16 v[16:31], v[64:67], v[80:83], v[16:31]
	v_mfma_f32_32x32x16_bf16 v[0:15], v[64:67], v[68:71], v[0:15]
	ds_read_b128 v[64:67], v166 offset:23072
	ds_read_b128 v[68:71], v147 offset:59936
	s_waitcnt lgkmcnt(2)
	v_mfma_f32_32x32x16_bf16 v[48:63], v[76:79], v[84:87], v[48:63]
	s_waitcnt lgkmcnt(0)
	v_mfma_f32_32x32x16_bf16 v[32:47], v[76:79], v[68:71], v[32:47]
	v_mfma_f32_32x32x16_bf16 v[16:31], v[64:67], v[84:87], v[16:31]
	v_mfma_f32_32x32x16_bf16 v[0:15], v[64:67], v[68:71], v[0:15]
	ds_read_b128 v[64:67], v147 offset:59968
	ds_read_b128 v[68:71], v147 offset:55360
	ds_read_b128 v[72:75], v166 offset:23104
	ds_read_b128 v[76:79], v166 offset:18496
	s_waitcnt lgkmcnt(0)
	v_mfma_f32_32x32x16_bf16 v[48:63], v[76:79], v[68:71], v[48:63]
	v_mfma_f32_32x32x16_bf16 v[32:47], v[76:79], v[64:67], v[32:47]
	v_mfma_f32_32x32x16_bf16 v[16:31], v[72:75], v[68:71], v[16:31]
	v_mfma_f32_32x32x16_bf16 v[0:15], v[72:75], v[64:67], v[0:15]
	ds_read_b128 v[64:67], v147 offset:60000
	ds_read_b128 v[68:71], v147 offset:55392
	ds_read_b128 v[72:75], v166 offset:23136
	ds_read_b128 v[76:79], v166 offset:18528
	s_waitcnt lgkmcnt(0)
	s_barrier
	v_mfma_f32_32x32x16_bf16 v[48:63], v[76:79], v[68:71], v[48:63]
	v_mfma_f32_32x32x16_bf16 v[16:31], v[72:75], v[68:71], v[16:31]
	s_nop 10
	v_mul_f32_e32 v48, 0xbfb8aa3b, v48
	v_mul_f32_e32 v49, 0xbfb8aa3b, v49
	v_exp_f32_e32 v48, v48
	v_exp_f32_e32 v49, v49
	v_mul_f32_e32 v51, 0xbfb8aa3b, v51
	v_exp_f32_e32 v51, v51
	v_pk_add_f32 v[48:49], v[48:49], 1.0 op_sel_hi:[1,0]
	s_nop 0
	v_div_scale_f32 v68, s[12:13], v49, v49, 1.0
	v_rcp_f32_e32 v69, v68
	v_mfma_f32_32x32x16_bf16 v[0:15], v[72:75], v[64:67], v[0:15]
	v_mul_f32_e32 v16, 0xbfb8aa3b, v16
	v_mul_f32_e32 v17, 0xbfb8aa3b, v17
	v_fma_f32 v70, -v68, v69, 1.0
	v_fmac_f32_e32 v69, v70, v69
	v_div_scale_f32 v70, vcc, 1.0, v49, 1.0
	v_mul_f32_e32 v71, v70, v69
	v_fma_f32 v72, -v68, v71, v70
	v_fmac_f32_e32 v71, v72, v69
	v_fma_f32 v68, -v68, v71, v70
	v_div_fmas_f32 v68, v68, v69, v71
	v_div_fixup_f32 v49, v68, v49, 1.0
	v_div_scale_f32 v68, s[12:13], v48, v48, 1.0
	v_rcp_f32_e32 v69, v68
	v_mfma_f32_32x32x16_bf16 v[32:47], v[76:79], v[64:67], v[32:47]
	v_lshlrev_b32_e32 v64, 16, v223
	v_lshlrev_b32_e32 v66, 16, v200
	v_fma_f32 v70, -v68, v69, 1.0
	v_fmac_f32_e32 v69, v70, v69
	v_div_scale_f32 v70, vcc, 1.0, v48, 1.0
	v_mul_f32_e32 v71, v70, v69
	v_fma_f32 v72, -v68, v71, v70
	v_fmac_f32_e32 v71, v72, v69
	v_fma_f32 v68, -v68, v71, v70
	v_div_fmas_f32 v68, v68, v69, v71
	v_and_b32_e32 v65, 0xffff0000, v223
	v_and_b32_e32 v67, 0xffff0000, v200
	v_div_fixup_f32 v48, v68, v48, 1.0
	v_pk_fma_f32 v[48:49], v[48:49], v[66:67], v[64:65]
	v_lshlrev_b32_e32 v64, 16, v189
	v_cvt_pk_bf16_f32 v223, v48, v49
	v_mul_f32_e32 v49, 0xbfb8aa3b, v50
	v_exp_f32_e32 v50, v49
	v_lshlrev_b32_e32 v48, 16, v222
	v_and_b32_e32 v49, 0xffff0000, v222
	v_and_b32_e32 v65, 0xffff0000, v189
	v_pk_add_f32 v[50:51], v[50:51], 1.0 op_sel_hi:[1,0]
	v_mul_f32_e32 v32, 0xbfb8aa3b, v32
	v_div_scale_f32 v66, s[12:13], v51, v51, 1.0
	v_rcp_f32_e32 v67, v66
	v_mul_f32_e32 v33, 0xbfb8aa3b, v33
	v_exp_f32_e32 v32, v32
	v_exp_f32_e32 v33, v33
	v_fma_f32 v68, -v66, v67, 1.0
	v_fmac_f32_e32 v67, v68, v67
	v_div_scale_f32 v68, vcc, 1.0, v51, 1.0
	v_mul_f32_e32 v69, v68, v67
	v_fma_f32 v70, -v66, v69, v68
	v_fmac_f32_e32 v69, v70, v67
	v_fma_f32 v66, -v66, v69, v68
	v_div_fmas_f32 v66, v66, v67, v69
	v_div_fixup_f32 v51, v66, v51, 1.0
	v_div_scale_f32 v66, s[12:13], v50, v50, 1.0
	v_rcp_f32_e32 v67, v66
	v_pk_add_f32 v[32:33], v[32:33], 1.0 op_sel_hi:[1,0]
	v_mul_f32_e32 v35, 0xbfb8aa3b, v35
	v_exp_f32_e32 v35, v35
	v_fma_f32 v68, -v66, v67, 1.0
	v_fmac_f32_e32 v67, v68, v67
	v_div_scale_f32 v68, vcc, 1.0, v50, 1.0
	v_mul_f32_e32 v69, v68, v67
	v_fma_f32 v70, -v66, v69, v68
	v_fmac_f32_e32 v69, v70, v67
	v_fma_f32 v66, -v66, v69, v68
	v_div_fmas_f32 v66, v66, v67, v69
	v_div_fixup_f32 v50, v66, v50, 1.0
	v_pk_fma_f32 v[48:49], v[50:51], v[64:65], v[48:49]
	v_mul_f32_e32 v51, 0xbfb8aa3b, v53
	v_cvt_pk_bf16_f32 v222, v48, v49
	v_mul_f32_e32 v49, 0xbfb8aa3b, v52
	v_exp_f32_e32 v50, v49
	v_exp_f32_e32 v51, v51
	v_lshlrev_b32_e32 v48, 16, v221
	v_lshlrev_b32_e32 v52, 16, v188
	v_and_b32_e32 v49, 0xffff0000, v221
	v_pk_add_f32 v[50:51], v[50:51], 1.0 op_sel_hi:[1,0]
	v_and_b32_e32 v53, 0xffff0000, v188
	v_div_scale_f32 v64, s[12:13], v51, v51, 1.0
	v_rcp_f32_e32 v65, v64
	v_exp_f32_e32 v16, v16
	v_exp_f32_e32 v17, v17
	v_mul_f32_e32 v19, 0xbfb8aa3b, v19
	v_fma_f32 v66, -v64, v65, 1.0
	v_fmac_f32_e32 v65, v66, v65
	v_div_scale_f32 v66, vcc, 1.0, v51, 1.0
	v_mul_f32_e32 v67, v66, v65
	v_fma_f32 v68, -v64, v67, v66
	v_fmac_f32_e32 v67, v68, v65
	v_fma_f32 v64, -v64, v67, v66
	v_div_fmas_f32 v64, v64, v65, v67
	v_div_fixup_f32 v51, v64, v51, 1.0
	v_div_scale_f32 v64, s[12:13], v50, v50, 1.0
	v_rcp_f32_e32 v65, v64
	v_pk_add_f32 v[16:17], v[16:17], 1.0 op_sel_hi:[1,0]
	v_exp_f32_e32 v19, v19
	v_mul_f32_e32 v0, 0xbfb8aa3b, v0
	v_fma_f32 v66, -v64, v65, 1.0
	v_fmac_f32_e32 v65, v66, v65
	v_div_scale_f32 v66, vcc, 1.0, v50, 1.0
	v_mul_f32_e32 v67, v66, v65
	v_fma_f32 v68, -v64, v67, v66
	v_fmac_f32_e32 v67, v68, v65
	v_fma_f32 v64, -v64, v67, v66
	v_div_fmas_f32 v64, v64, v65, v67
	v_div_fixup_f32 v50, v64, v50, 1.0
	v_pk_fma_f32 v[48:49], v[50:51], v[52:53], v[48:49]
	v_mul_f32_e32 v51, 0xbfb8aa3b, v55
	v_cvt_pk_bf16_f32 v221, v48, v49
	v_mul_f32_e32 v49, 0xbfb8aa3b, v54
	v_exp_f32_e32 v50, v49
	v_exp_f32_e32 v51, v51
	v_lshlrev_b32_e32 v48, 16, v220
	v_lshlrev_b32_e32 v52, 16, v208
	v_and_b32_e32 v49, 0xffff0000, v220
	v_pk_add_f32 v[50:51], v[50:51], 1.0 op_sel_hi:[1,0]
	v_and_b32_e32 v53, 0xffff0000, v208
	v_div_scale_f32 v54, s[12:13], v51, v51, 1.0
	v_rcp_f32_e32 v55, v54
	v_mul_f32_e32 v1, 0xbfb8aa3b, v1
	v_exp_f32_e32 v0, v0
	v_exp_f32_e32 v1, v1
	v_fma_f32 v64, -v54, v55, 1.0
	v_fmac_f32_e32 v55, v64, v55
	v_div_scale_f32 v64, vcc, 1.0, v51, 1.0
	v_mul_f32_e32 v65, v64, v55
	v_fma_f32 v66, -v54, v65, v64
	v_fmac_f32_e32 v65, v66, v55
	v_fma_f32 v54, -v54, v65, v64
	v_div_fmas_f32 v54, v54, v55, v65
	v_div_fixup_f32 v51, v54, v51, 1.0
	v_div_scale_f32 v54, s[12:13], v50, v50, 1.0
	v_rcp_f32_e32 v55, v54
	v_pk_add_f32 v[0:1], v[0:1], 1.0 op_sel_hi:[1,0]
	v_mul_f32_e32 v3, 0xbfb8aa3b, v3
	v_exp_f32_e32 v3, v3
	v_fma_f32 v64, -v54, v55, 1.0
	v_fmac_f32_e32 v55, v64, v55
	v_div_scale_f32 v64, vcc, 1.0, v50, 1.0
	v_mul_f32_e32 v65, v64, v55
	v_fma_f32 v66, -v54, v65, v64
	v_fmac_f32_e32 v65, v66, v55
	v_fma_f32 v54, -v54, v65, v64
	v_div_fmas_f32 v54, v54, v55, v65
	v_div_fixup_f32 v50, v54, v50, 1.0
	v_pk_fma_f32 v[48:49], v[50:51], v[52:53], v[48:49]
	v_mul_f32_e32 v51, 0xbfb8aa3b, v57
	v_cvt_pk_bf16_f32 v220, v48, v49
	v_mul_f32_e32 v49, 0xbfb8aa3b, v56
	v_exp_f32_e32 v50, v49
	v_exp_f32_e32 v51, v51
	v_lshlrev_b32_e32 v48, 16, v219
	v_lshlrev_b32_e32 v52, 16, v195
	v_and_b32_e32 v49, 0xffff0000, v219
	v_pk_add_f32 v[50:51], v[50:51], 1.0 op_sel_hi:[1,0]
	v_and_b32_e32 v53, 0xffff0000, v195
	v_rcp_f32_e32 v51, v51
	s_nop 0
	v_rcp_f32_e32 v50, v50
	s_nop 0
	v_pk_fma_f32 v[48:49], v[50:51], v[52:53], v[48:49]
	v_mul_f32_e32 v51, 0xbfb8aa3b, v59
	v_cvt_pk_bf16_f32 v219, v48, v49
	v_mul_f32_e32 v49, 0xbfb8aa3b, v58
	v_exp_f32_e32 v50, v49
	v_exp_f32_e32 v51, v51
	v_lshlrev_b32_e32 v48, 16, v218
	v_lshlrev_b32_e32 v52, 16, v192
	v_and_b32_e32 v49, 0xffff0000, v218
	v_pk_add_f32 v[50:51], v[50:51], 1.0 op_sel_hi:[1,0]
	v_and_b32_e32 v53, 0xffff0000, v192
	v_rcp_f32_e32 v51, v51
	s_nop 0
	v_rcp_f32_e32 v50, v50
	s_nop 0
	v_pk_fma_f32 v[48:49], v[50:51], v[52:53], v[48:49]
	v_mul_f32_e32 v51, 0xbfb8aa3b, v61
	v_cvt_pk_bf16_f32 v218, v48, v49
	v_mul_f32_e32 v49, 0xbfb8aa3b, v60
	v_exp_f32_e32 v50, v49
	v_exp_f32_e32 v51, v51
	v_lshlrev_b32_e32 v48, 16, v217
	v_lshlrev_b32_e32 v52, 16, v250
	v_and_b32_e32 v49, 0xffff0000, v217
	v_pk_add_f32 v[50:51], v[50:51], 1.0 op_sel_hi:[1,0]
	v_and_b32_e32 v53, 0xffff0000, v250
	v_rcp_f32_e32 v51, v51
	s_nop 0
	v_rcp_f32_e32 v50, v50
	s_nop 0
	v_pk_fma_f32 v[48:49], v[50:51], v[52:53], v[48:49]
	v_mul_f32_e32 v51, 0xbfb8aa3b, v63
	v_cvt_pk_bf16_f32 v217, v48, v49
	v_mul_f32_e32 v49, 0xbfb8aa3b, v62
	v_exp_f32_e32 v50, v49
	v_exp_f32_e32 v51, v51
	v_lshlrev_b32_e32 v48, 16, v216
	v_lshlrev_b32_e32 v52, 16, v249
	v_and_b32_e32 v49, 0xffff0000, v216
	v_pk_add_f32 v[50:51], v[50:51], 1.0 op_sel_hi:[1,0]
	v_and_b32_e32 v53, 0xffff0000, v249
	v_rcp_f32_e32 v51, v51
	s_nop 0
	v_rcp_f32_e32 v50, v50
	s_nop 0
	v_pk_fma_f32 v[48:49], v[50:51], v[52:53], v[48:49]
	v_div_scale_f32 v52, s[12:13], v33, v33, 1.0
	v_rcp_f32_e32 v53, v52
	v_cvt_pk_bf16_f32 v216, v48, v49
	v_lshlrev_b32_e32 v48, 16, v215
	v_lshlrev_b32_e32 v50, 16, v248
	v_fma_f32 v54, -v52, v53, 1.0
	v_fmac_f32_e32 v53, v54, v53
	v_div_scale_f32 v54, vcc, 1.0, v33, 1.0
	v_mul_f32_e32 v55, v54, v53
	v_fma_f32 v56, -v52, v55, v54
	v_fmac_f32_e32 v55, v56, v53
	v_fma_f32 v52, -v52, v55, v54
	v_div_fmas_f32 v52, v52, v53, v55
	v_div_fixup_f32 v33, v52, v33, 1.0
	v_div_scale_f32 v52, s[12:13], v32, v32, 1.0
	v_rcp_f32_e32 v53, v52
	v_and_b32_e32 v49, 0xffff0000, v215
	v_and_b32_e32 v51, 0xffff0000, v248
	v_fma_f32 v54, -v52, v53, 1.0
	v_fmac_f32_e32 v53, v54, v53
	v_div_scale_f32 v54, vcc, 1.0, v32, 1.0
	v_mul_f32_e32 v55, v54, v53
	v_fma_f32 v56, -v52, v55, v54
	v_fmac_f32_e32 v55, v56, v53
	v_fma_f32 v52, -v52, v55, v54
	v_div_fmas_f32 v52, v52, v53, v55
	v_div_fixup_f32 v32, v52, v32, 1.0
	v_pk_fma_f32 v[32:33], v[32:33], v[50:51], v[48:49]
	v_lshlrev_b32_e32 v48, 16, v247
	v_cvt_pk_bf16_f32 v215, v32, v33
	v_mul_f32_e32 v33, 0xbfb8aa3b, v34
	v_exp_f32_e32 v34, v33
	v_lshlrev_b32_e32 v32, 16, v214
	v_and_b32_e32 v33, 0xffff0000, v214
	v_and_b32_e32 v49, 0xffff0000, v247
	v_pk_add_f32 v[34:35], v[34:35], 1.0 op_sel_hi:[1,0]
	s_nop 0
	v_rcp_f32_e32 v35, v35
	s_nop 0
	v_rcp_f32_e32 v34, v34
	s_nop 0
	v_pk_fma_f32 v[32:33], v[34:35], v[48:49], v[32:33]
	v_mul_f32_e32 v35, 0xbfb8aa3b, v37
	v_cvt_pk_bf16_f32 v214, v32, v33
	v_mul_f32_e32 v33, 0xbfb8aa3b, v36
	v_exp_f32_e32 v34, v33
	v_exp_f32_e32 v35, v35
	v_lshlrev_b32_e32 v32, 16, v213
	v_lshlrev_b32_e32 v36, 16, v246
	v_and_b32_e32 v33, 0xffff0000, v213
	v_pk_add_f32 v[34:35], v[34:35], 1.0 op_sel_hi:[1,0]
	v_and_b32_e32 v37, 0xffff0000, v246
	v_rcp_f32_e32 v35, v35
	s_nop 0
	v_rcp_f32_e32 v34, v34
	s_nop 0
	v_pk_fma_f32 v[32:33], v[34:35], v[36:37], v[32:33]
	v_mul_f32_e32 v35, 0xbfb8aa3b, v39
	v_cvt_pk_bf16_f32 v213, v32, v33
	v_mul_f32_e32 v33, 0xbfb8aa3b, v38
	v_exp_f32_e32 v34, v33
	v_exp_f32_e32 v35, v35
	v_lshlrev_b32_e32 v32, 16, v212
	v_lshlrev_b32_e32 v36, 16, v245
	v_and_b32_e32 v33, 0xffff0000, v212
	v_pk_add_f32 v[34:35], v[34:35], 1.0 op_sel_hi:[1,0]
	v_and_b32_e32 v37, 0xffff0000, v245
	v_rcp_f32_e32 v35, v35
	s_nop 0
	v_rcp_f32_e32 v34, v34
	s_nop 0
	v_pk_fma_f32 v[32:33], v[34:35], v[36:37], v[32:33]
	v_mul_f32_e32 v35, 0xbfb8aa3b, v41
	v_cvt_pk_bf16_f32 v212, v32, v33
	v_mul_f32_e32 v33, 0xbfb8aa3b, v40
	v_exp_f32_e32 v34, v33
	v_exp_f32_e32 v35, v35
	v_lshlrev_b32_e32 v32, 16, v211
	v_lshlrev_b32_e32 v36, 16, v244
	v_and_b32_e32 v33, 0xffff0000, v211
	v_pk_add_f32 v[34:35], v[34:35], 1.0 op_sel_hi:[1,0]
	v_and_b32_e32 v37, 0xffff0000, v244
	v_rcp_f32_e32 v35, v35
	s_nop 0
	v_rcp_f32_e32 v34, v34
	s_nop 0
	v_pk_fma_f32 v[32:33], v[34:35], v[36:37], v[32:33]
	v_mul_f32_e32 v35, 0xbfb8aa3b, v43
	v_cvt_pk_bf16_f32 v211, v32, v33
	v_mul_f32_e32 v33, 0xbfb8aa3b, v42
	v_exp_f32_e32 v34, v33
	v_exp_f32_e32 v35, v35
	v_lshlrev_b32_e32 v32, 16, v210
	v_lshlrev_b32_e32 v36, 16, v243
	v_and_b32_e32 v33, 0xffff0000, v210
	v_pk_add_f32 v[34:35], v[34:35], 1.0 op_sel_hi:[1,0]
	v_and_b32_e32 v37, 0xffff0000, v243
	v_rcp_f32_e32 v35, v35
	s_nop 0
	v_rcp_f32_e32 v34, v34
	s_nop 0
	v_pk_fma_f32 v[32:33], v[34:35], v[36:37], v[32:33]
	v_mul_f32_e32 v35, 0xbfb8aa3b, v45
	v_cvt_pk_bf16_f32 v210, v32, v33
	v_mul_f32_e32 v33, 0xbfb8aa3b, v44
	v_exp_f32_e32 v34, v33
	v_exp_f32_e32 v35, v35
	v_lshlrev_b32_e32 v32, 16, v185
	v_lshlrev_b32_e32 v36, 16, v242
	v_and_b32_e32 v33, 0xffff0000, v185
	v_pk_add_f32 v[34:35], v[34:35], 1.0 op_sel_hi:[1,0]
	v_and_b32_e32 v37, 0xffff0000, v242
	v_rcp_f32_e32 v35, v35
	s_nop 0
	v_rcp_f32_e32 v34, v34
	s_nop 0
	v_pk_fma_f32 v[32:33], v[34:35], v[36:37], v[32:33]
	v_mul_f32_e32 v35, 0xbfb8aa3b, v47
	v_cvt_pk_bf16_f32 v185, v32, v33
	v_mul_f32_e32 v33, 0xbfb8aa3b, v46
	v_exp_f32_e32 v34, v33
	v_exp_f32_e32 v35, v35
	v_lshlrev_b32_e32 v32, 16, v184
	v_lshlrev_b32_e32 v36, 16, v241
	v_and_b32_e32 v33, 0xffff0000, v184
	v_pk_add_f32 v[34:35], v[34:35], 1.0 op_sel_hi:[1,0]
	v_and_b32_e32 v37, 0xffff0000, v241
	v_rcp_f32_e32 v35, v35
	s_nop 0
	v_rcp_f32_e32 v34, v34
	s_nop 0
	v_pk_fma_f32 v[32:33], v[34:35], v[36:37], v[32:33]
	v_div_scale_f32 v36, s[12:13], v17, v17, 1.0
	v_rcp_f32_e32 v37, v36
	v_cvt_pk_bf16_f32 v184, v32, v33
	v_lshlrev_b32_e32 v32, 16, v183
	v_lshlrev_b32_e32 v34, 16, v240
	v_fma_f32 v38, -v36, v37, 1.0
	v_fmac_f32_e32 v37, v38, v37
	v_div_scale_f32 v38, vcc, 1.0, v17, 1.0
	v_mul_f32_e32 v39, v38, v37
	v_fma_f32 v40, -v36, v39, v38
	v_fmac_f32_e32 v39, v40, v37
	v_fma_f32 v36, -v36, v39, v38
	v_div_fmas_f32 v36, v36, v37, v39
	v_div_fixup_f32 v17, v36, v17, 1.0
	v_div_scale_f32 v36, s[12:13], v16, v16, 1.0
	v_rcp_f32_e32 v37, v36
	v_and_b32_e32 v33, 0xffff0000, v183
	v_and_b32_e32 v35, 0xffff0000, v240
	v_fma_f32 v38, -v36, v37, 1.0
	v_fmac_f32_e32 v37, v38, v37
	v_div_scale_f32 v38, vcc, 1.0, v16, 1.0
	v_mul_f32_e32 v39, v38, v37
	v_fma_f32 v40, -v36, v39, v38
	v_fmac_f32_e32 v39, v40, v37
	v_fma_f32 v36, -v36, v39, v38
	v_div_fmas_f32 v36, v36, v37, v39
	v_div_fixup_f32 v16, v36, v16, 1.0
	v_pk_fma_f32 v[16:17], v[16:17], v[34:35], v[32:33]
	v_lshlrev_b32_e32 v32, 16, v239
	v_cvt_pk_bf16_f32 v183, v16, v17
	v_mul_f32_e32 v17, 0xbfb8aa3b, v18
	v_exp_f32_e32 v18, v17
	v_lshlrev_b32_e32 v16, 16, v182
	v_and_b32_e32 v17, 0xffff0000, v182
	v_and_b32_e32 v33, 0xffff0000, v239
	v_pk_add_f32 v[18:19], v[18:19], 1.0 op_sel_hi:[1,0]
	s_nop 0
	v_rcp_f32_e32 v19, v19
	s_nop 0
	v_rcp_f32_e32 v18, v18
	s_nop 0
	v_pk_fma_f32 v[16:17], v[18:19], v[32:33], v[16:17]
	v_mul_f32_e32 v19, 0xbfb8aa3b, v21
	v_cvt_pk_bf16_f32 v182, v16, v17
	v_mul_f32_e32 v17, 0xbfb8aa3b, v20
	v_exp_f32_e32 v18, v17
	v_exp_f32_e32 v19, v19
	v_lshlrev_b32_e32 v16, 16, v181
	v_lshlrev_b32_e32 v20, 16, v238
	v_and_b32_e32 v17, 0xffff0000, v181
	v_pk_add_f32 v[18:19], v[18:19], 1.0 op_sel_hi:[1,0]
	v_and_b32_e32 v21, 0xffff0000, v238
	v_rcp_f32_e32 v19, v19
	s_nop 0
	v_rcp_f32_e32 v18, v18
	s_nop 0
	v_pk_fma_f32 v[16:17], v[18:19], v[20:21], v[16:17]
	v_mul_f32_e32 v19, 0xbfb8aa3b, v23
	v_cvt_pk_bf16_f32 v181, v16, v17
	v_mul_f32_e32 v17, 0xbfb8aa3b, v22
	v_exp_f32_e32 v18, v17
	v_exp_f32_e32 v19, v19
	v_lshlrev_b32_e32 v16, 16, v180
	v_lshlrev_b32_e32 v20, 16, v237
	v_and_b32_e32 v17, 0xffff0000, v180
	v_pk_add_f32 v[18:19], v[18:19], 1.0 op_sel_hi:[1,0]
	v_and_b32_e32 v21, 0xffff0000, v237
	v_rcp_f32_e32 v19, v19
	s_nop 0
	v_rcp_f32_e32 v18, v18
	s_nop 0
	v_pk_fma_f32 v[16:17], v[18:19], v[20:21], v[16:17]
	v_mul_f32_e32 v19, 0xbfb8aa3b, v25
	v_cvt_pk_bf16_f32 v180, v16, v17
	v_mul_f32_e32 v17, 0xbfb8aa3b, v24
	v_exp_f32_e32 v18, v17
	v_exp_f32_e32 v19, v19
	v_lshlrev_b32_e32 v16, 16, v179
	v_lshlrev_b32_e32 v20, 16, v236
	v_and_b32_e32 v17, 0xffff0000, v179
	v_pk_add_f32 v[18:19], v[18:19], 1.0 op_sel_hi:[1,0]
	v_and_b32_e32 v21, 0xffff0000, v236
	v_rcp_f32_e32 v19, v19
	s_nop 0
	v_rcp_f32_e32 v18, v18
	s_nop 0
	v_pk_fma_f32 v[16:17], v[18:19], v[20:21], v[16:17]
	v_mul_f32_e32 v19, 0xbfb8aa3b, v27
	v_cvt_pk_bf16_f32 v179, v16, v17
	v_mul_f32_e32 v17, 0xbfb8aa3b, v26
	v_exp_f32_e32 v18, v17
	v_exp_f32_e32 v19, v19
	v_lshlrev_b32_e32 v16, 16, v178
	v_lshlrev_b32_e32 v20, 16, v235
	v_and_b32_e32 v17, 0xffff0000, v178
	v_pk_add_f32 v[18:19], v[18:19], 1.0 op_sel_hi:[1,0]
	v_and_b32_e32 v21, 0xffff0000, v235
	v_rcp_f32_e32 v19, v19
	s_nop 0
	v_rcp_f32_e32 v18, v18
	s_nop 0
	v_pk_fma_f32 v[16:17], v[18:19], v[20:21], v[16:17]
	v_mul_f32_e32 v19, 0xbfb8aa3b, v29
	v_cvt_pk_bf16_f32 v178, v16, v17
	v_mul_f32_e32 v17, 0xbfb8aa3b, v28
	v_exp_f32_e32 v18, v17
	v_exp_f32_e32 v19, v19
	v_lshlrev_b32_e32 v16, 16, v177
	v_lshlrev_b32_e32 v20, 16, v234
	v_and_b32_e32 v17, 0xffff0000, v177
	v_pk_add_f32 v[18:19], v[18:19], 1.0 op_sel_hi:[1,0]
	v_and_b32_e32 v21, 0xffff0000, v234
	v_rcp_f32_e32 v19, v19
	s_nop 0
	v_rcp_f32_e32 v18, v18
	s_nop 0
	v_pk_fma_f32 v[16:17], v[18:19], v[20:21], v[16:17]
	v_mul_f32_e32 v19, 0xbfb8aa3b, v31
	v_cvt_pk_bf16_f32 v177, v16, v17
	v_mul_f32_e32 v17, 0xbfb8aa3b, v30
	v_exp_f32_e32 v18, v17
	v_exp_f32_e32 v19, v19
	v_lshlrev_b32_e32 v16, 16, v176
	v_lshlrev_b32_e32 v20, 16, v233
	v_and_b32_e32 v17, 0xffff0000, v176
	v_pk_add_f32 v[18:19], v[18:19], 1.0 op_sel_hi:[1,0]
	v_and_b32_e32 v21, 0xffff0000, v233
	v_rcp_f32_e32 v19, v19
	s_nop 0
	v_rcp_f32_e32 v18, v18
	s_nop 0
	v_pk_fma_f32 v[16:17], v[18:19], v[20:21], v[16:17]
	v_div_scale_f32 v20, s[12:13], v1, v1, 1.0
	v_rcp_f32_e32 v21, v20
	v_cvt_pk_bf16_f32 v176, v16, v17
	v_lshlrev_b32_e32 v16, 16, v175
	v_lshlrev_b32_e32 v18, 16, v232
	v_fma_f32 v22, -v20, v21, 1.0
	v_fmac_f32_e32 v21, v22, v21
	v_div_scale_f32 v22, vcc, 1.0, v1, 1.0
	v_mul_f32_e32 v23, v22, v21
	v_fma_f32 v24, -v20, v23, v22
	v_fmac_f32_e32 v23, v24, v21
	v_fma_f32 v20, -v20, v23, v22
	v_div_fmas_f32 v20, v20, v21, v23
	v_div_fixup_f32 v1, v20, v1, 1.0
	v_div_scale_f32 v20, s[12:13], v0, v0, 1.0
	v_rcp_f32_e32 v21, v20
	v_and_b32_e32 v17, 0xffff0000, v175
	v_and_b32_e32 v19, 0xffff0000, v232
	v_fma_f32 v22, -v20, v21, 1.0
	v_fmac_f32_e32 v21, v22, v21
	v_div_scale_f32 v22, vcc, 1.0, v0, 1.0
	v_mul_f32_e32 v23, v22, v21
	v_fma_f32 v24, -v20, v23, v22
	v_fmac_f32_e32 v23, v24, v21
	v_fma_f32 v20, -v20, v23, v22
	v_div_fmas_f32 v20, v20, v21, v23
	v_div_fixup_f32 v0, v20, v0, 1.0
	v_pk_fma_f32 v[0:1], v[0:1], v[18:19], v[16:17]
	v_lshlrev_b32_e32 v16, 16, v231
	v_cvt_pk_bf16_f32 v175, v0, v1
	v_mul_f32_e32 v1, 0xbfb8aa3b, v2
	v_exp_f32_e32 v2, v1
	v_lshlrev_b32_e32 v0, 16, v174
	v_and_b32_e32 v1, 0xffff0000, v174
	v_and_b32_e32 v17, 0xffff0000, v231
	v_pk_add_f32 v[2:3], v[2:3], 1.0 op_sel_hi:[1,0]
	s_nop 0
	v_rcp_f32_e32 v3, v3
	s_nop 0
	v_rcp_f32_e32 v2, v2
	s_nop 0
	v_pk_fma_f32 v[0:1], v[2:3], v[16:17], v[0:1]
	v_mul_f32_e32 v3, 0xbfb8aa3b, v5
	v_cvt_pk_bf16_f32 v174, v0, v1
	v_mul_f32_e32 v1, 0xbfb8aa3b, v4
	v_exp_f32_e32 v2, v1
	v_exp_f32_e32 v3, v3
	v_lshlrev_b32_e32 v0, 16, v173
	v_lshlrev_b32_e32 v4, 16, v230
	v_and_b32_e32 v1, 0xffff0000, v173
	v_pk_add_f32 v[2:3], v[2:3], 1.0 op_sel_hi:[1,0]
	v_and_b32_e32 v5, 0xffff0000, v230
	v_rcp_f32_e32 v3, v3
	s_nop 0
	v_rcp_f32_e32 v2, v2
	s_nop 0
	v_pk_fma_f32 v[0:1], v[2:3], v[4:5], v[0:1]
	v_mul_f32_e32 v3, 0xbfb8aa3b, v7
	v_cvt_pk_bf16_f32 v173, v0, v1
	v_mul_f32_e32 v1, 0xbfb8aa3b, v6
	v_exp_f32_e32 v2, v1
	v_exp_f32_e32 v3, v3
	v_lshlrev_b32_e32 v0, 16, v172
	v_lshlrev_b32_e32 v4, 16, v229
	v_and_b32_e32 v1, 0xffff0000, v172
	v_pk_add_f32 v[2:3], v[2:3], 1.0 op_sel_hi:[1,0]
	v_and_b32_e32 v5, 0xffff0000, v229
	v_rcp_f32_e32 v3, v3
	s_nop 0
	v_rcp_f32_e32 v2, v2
	s_nop 0
	v_pk_fma_f32 v[0:1], v[2:3], v[4:5], v[0:1]
	v_mul_f32_e32 v3, 0xbfb8aa3b, v9
	v_cvt_pk_bf16_f32 v172, v0, v1
	v_mul_f32_e32 v1, 0xbfb8aa3b, v8
	v_exp_f32_e32 v2, v1
	v_exp_f32_e32 v3, v3
	v_lshlrev_b32_e32 v0, 16, v171
	v_lshlrev_b32_e32 v4, 16, v228
	v_and_b32_e32 v1, 0xffff0000, v171
	v_pk_add_f32 v[2:3], v[2:3], 1.0 op_sel_hi:[1,0]
	v_and_b32_e32 v5, 0xffff0000, v228
	v_rcp_f32_e32 v3, v3
	s_nop 0
	v_rcp_f32_e32 v2, v2
	s_nop 0
	v_pk_fma_f32 v[0:1], v[2:3], v[4:5], v[0:1]
	v_mul_f32_e32 v3, 0xbfb8aa3b, v11
	v_cvt_pk_bf16_f32 v171, v0, v1
	v_mul_f32_e32 v1, 0xbfb8aa3b, v10
	v_exp_f32_e32 v2, v1
	v_exp_f32_e32 v3, v3
	v_lshlrev_b32_e32 v0, 16, v170
	v_lshlrev_b32_e32 v4, 16, v227
	v_and_b32_e32 v1, 0xffff0000, v170
	v_pk_add_f32 v[2:3], v[2:3], 1.0 op_sel_hi:[1,0]
	v_and_b32_e32 v5, 0xffff0000, v227
	v_rcp_f32_e32 v3, v3
	s_nop 0
	v_rcp_f32_e32 v2, v2
	s_nop 0
	v_pk_fma_f32 v[0:1], v[2:3], v[4:5], v[0:1]
	v_mul_f32_e32 v3, 0xbfb8aa3b, v13
	v_cvt_pk_bf16_f32 v170, v0, v1
	v_mul_f32_e32 v1, 0xbfb8aa3b, v12
	v_exp_f32_e32 v2, v1
	v_exp_f32_e32 v3, v3
	v_lshlrev_b32_e32 v0, 16, v169
	v_lshlrev_b32_e32 v4, 16, v226
	v_and_b32_e32 v1, 0xffff0000, v169
	v_pk_add_f32 v[2:3], v[2:3], 1.0 op_sel_hi:[1,0]
	v_and_b32_e32 v5, 0xffff0000, v226
	v_rcp_f32_e32 v3, v3
	s_nop 0
	v_rcp_f32_e32 v2, v2
	s_nop 0
	v_pk_fma_f32 v[0:1], v[2:3], v[4:5], v[0:1]
	v_mul_f32_e32 v3, 0xbfb8aa3b, v15
	v_cvt_pk_bf16_f32 v169, v0, v1
	v_mul_f32_e32 v1, 0xbfb8aa3b, v14
	v_exp_f32_e32 v4, v1
	v_exp_f32_e32 v5, v3
	v_lshlrev_b32_e32 v0, 16, v224
	v_lshlrev_b32_e32 v2, 16, v225
	v_and_b32_e32 v1, 0xffff0000, v224
	v_pk_add_f32 v[4:5], v[4:5], 1.0 op_sel_hi:[1,0]
	v_and_b32_e32 v3, 0xffff0000, v225
	v_rcp_f32_e32 v5, v5
	s_nop 0
	v_rcp_f32_e32 v4, v4
	s_nop 0
	v_pk_fma_f32 v[0:1], v[4:5], v[2:3], v[0:1]
	s_nop 0
	v_cvt_pk_bf16_f32 v224, v0, v1
	s_cbranch_scc0 .LBB0_2087
	v_add_u32_e32 v18, s4, v163
	v_or_b32_e32 v4, 2, v168
	v_or_b32_e32 v6, 8, v168
	v_or_b32_e32 v8, 10, v168
	v_or_b32_e32 v10, 16, v168
	v_or_b32_e32 v12, 18, v168
	v_or_b32_e32 v14, 24, v168
	v_or_b32_e32 v16, 26, v168
	v_or_b32_e32 v2, v18, v168
	v_or_b32_e32 v4, v18, v4
	v_or_b32_e32 v6, v18, v6
	v_or_b32_e32 v8, v18, v8
	v_or_b32_e32 v10, v18, v10
	v_or_b32_e32 v12, v18, v12
	v_or_b32_e32 v14, v18, v14
	v_or_b32_e32 v16, v18, v16
	v_ashrrev_i32_e32 v3, 31, v2
	v_ashrrev_i32_e32 v5, 31, v4
	v_ashrrev_i32_e32 v7, 31, v6
	v_ashrrev_i32_e32 v9, 31, v8
	v_ashrrev_i32_e32 v11, 31, v10
	v_ashrrev_i32_e32 v13, 31, v12
	v_ashrrev_i32_e32 v15, 31, v14
	v_ashrrev_i32_e32 v17, 31, v16
	v_lshl_add_u64 v[0:1], s[6:7], 1, v[144:145]
	v_lshlrev_b64 v[2:3], 11, v[2:3]
	v_lshlrev_b64 v[4:5], 11, v[4:5]
	v_lshlrev_b64 v[6:7], 11, v[6:7]
	v_lshlrev_b64 v[8:9], 11, v[8:9]
	v_lshlrev_b64 v[10:11], 11, v[10:11]
	v_lshlrev_b64 v[12:13], 11, v[12:13]
	v_lshlrev_b64 v[14:15], 11, v[14:15]
	v_lshlrev_b64 v[16:17], 11, v[16:17]
	v_lshl_add_u64 v[2:3], v[0:1], 0, v[2:3]
	v_lshl_add_u64 v[4:5], v[0:1], 0, v[4:5]
	v_lshl_add_u64 v[6:7], v[0:1], 0, v[6:7]
	v_lshl_add_u64 v[8:9], v[0:1], 0, v[8:9]
	v_lshl_add_u64 v[10:11], v[0:1], 0, v[10:11]
	v_lshl_add_u64 v[12:13], v[0:1], 0, v[12:13]
	v_lshl_add_u64 v[14:15], v[0:1], 0, v[14:15]
	v_lshl_add_u64 v[16:17], v[0:1], 0, v[16:17]
	global_store_short v[2:3], v223, off
	global_store_short_d16_hi v[2:3], v223, off offset:2048
	global_store_short v[4:5], v222, off
	global_store_short_d16_hi v[4:5], v222, off offset:2048
	global_store_short v[6:7], v221, off
	global_store_short_d16_hi v[6:7], v221, off offset:2048
	global_store_short v[8:9], v220, off
	global_store_short_d16_hi v[8:9], v220, off offset:2048
	global_store_short v[10:11], v219, off
	global_store_short_d16_hi v[10:11], v219, off offset:2048
	global_store_short v[12:13], v218, off
	global_store_short_d16_hi v[12:13], v218, off offset:2048
	global_store_short v[14:15], v217, off
	global_store_short_d16_hi v[14:15], v217, off offset:2048
	global_store_short v[16:17], v216, off
	global_store_short_d16_hi v[16:17], v216, off offset:2048
	global_store_short v[2:3], v215, off offset:64
	global_store_short_d16_hi v[2:3], v215, off offset:2112
	global_store_short v[4:5], v214, off offset:64
	global_store_short_d16_hi v[4:5], v214, off offset:2112
	global_store_short v[6:7], v213, off offset:64
	global_store_short_d16_hi v[6:7], v213, off offset:2112
	global_store_short v[8:9], v212, off offset:64
	global_store_short_d16_hi v[8:9], v212, off offset:2112
	global_store_short v[10:11], v211, off offset:64
	global_store_short_d16_hi v[10:11], v211, off offset:2112
	global_store_short v[12:13], v210, off offset:64
	global_store_short_d16_hi v[12:13], v210, off offset:2112
	global_store_short v[14:15], v185, off offset:64
	global_store_short_d16_hi v[14:15], v185, off offset:2112
	global_store_short v[16:17], v184, off offset:64
	global_store_short_d16_hi v[16:17], v184, off offset:2112
	v_or_b32_e32 v2, 32, v168
	v_or_b32_e32 v4, 34, v168
	v_or_b32_e32 v6, 40, v168
	v_or_b32_e32 v8, 42, v168
	v_or_b32_e32 v10, 48, v168
	v_or_b32_e32 v12, 50, v168
	v_or_b32_e32 v14, 56, v168
	v_or_b32_e32 v16, 58, v168
	v_or_b32_e32 v2, v18, v2
	v_or_b32_e32 v4, v18, v4
	v_or_b32_e32 v6, v18, v6
	v_or_b32_e32 v8, v18, v8
	v_or_b32_e32 v10, v18, v10
	v_or_b32_e32 v12, v18, v12
	v_or_b32_e32 v14, v18, v14
	v_or_b32_e32 v16, v18, v16
	v_ashrrev_i32_e32 v3, 31, v2
	v_ashrrev_i32_e32 v5, 31, v4
	v_ashrrev_i32_e32 v7, 31, v6
	v_ashrrev_i32_e32 v9, 31, v8
	v_ashrrev_i32_e32 v11, 31, v10
	v_ashrrev_i32_e32 v13, 31, v12
	v_ashrrev_i32_e32 v15, 31, v14
	v_ashrrev_i32_e32 v17, 31, v16
	v_readlane_b32 s4, v252, 22
	v_lshlrev_b64 v[2:3], 11, v[2:3]
	v_lshlrev_b64 v[4:5], 11, v[4:5]
	v_lshlrev_b64 v[6:7], 11, v[6:7]
	v_lshlrev_b64 v[8:9], 11, v[8:9]
	v_lshlrev_b64 v[10:11], 11, v[10:11]
	v_lshlrev_b64 v[12:13], 11, v[12:13]
	v_lshlrev_b64 v[14:15], 11, v[14:15]
	v_lshlrev_b64 v[16:17], 11, v[16:17]
	s_add_i32 s18, s18, s4
	v_lshl_add_u64 v[2:3], v[0:1], 0, v[2:3]
	v_lshl_add_u64 v[4:5], v[0:1], 0, v[4:5]
	v_lshl_add_u64 v[6:7], v[0:1], 0, v[6:7]
	v_lshl_add_u64 v[8:9], v[0:1], 0, v[8:9]
	v_lshl_add_u64 v[10:11], v[0:1], 0, v[10:11]
	v_lshl_add_u64 v[12:13], v[0:1], 0, v[12:13]
	v_lshl_add_u64 v[14:15], v[0:1], 0, v[14:15]
	v_lshl_add_u64 v[0:1], v[0:1], 0, v[16:17]
	s_cmp_ge_i32 s18, s24
	global_store_short v[2:3], v183, off
	global_store_short_d16_hi v[2:3], v183, off offset:2048
	global_store_short v[4:5], v182, off
	global_store_short_d16_hi v[4:5], v182, off offset:2048
	global_store_short v[6:7], v181, off
	global_store_short_d16_hi v[6:7], v181, off offset:2048
	global_store_short v[8:9], v180, off
	global_store_short_d16_hi v[8:9], v180, off offset:2048
	global_store_short v[10:11], v179, off
	global_store_short_d16_hi v[10:11], v179, off offset:2048
	global_store_short v[12:13], v178, off
	global_store_short_d16_hi v[12:13], v178, off offset:2048
	global_store_short v[14:15], v177, off
	global_store_short_d16_hi v[14:15], v177, off offset:2048
	global_store_short v[0:1], v176, off
	global_store_short_d16_hi v[0:1], v176, off offset:2048
	global_store_short v[2:3], v175, off offset:64
	global_store_short_d16_hi v[2:3], v175, off offset:2112
	global_store_short v[4:5], v174, off offset:64
	global_store_short_d16_hi v[4:5], v174, off offset:2112
	global_store_short v[6:7], v173, off offset:64
	global_store_short_d16_hi v[6:7], v173, off offset:2112
	global_store_short v[8:9], v172, off offset:64
	global_store_short_d16_hi v[8:9], v172, off offset:2112
	global_store_short v[10:11], v171, off offset:64
	global_store_short_d16_hi v[10:11], v171, off offset:2112
	global_store_short v[12:13], v170, off offset:64
	global_store_short_d16_hi v[12:13], v170, off offset:2112
	global_store_short v[14:15], v169, off offset:64
	global_store_short_d16_hi v[14:15], v169, off offset:2112
	global_store_short v[0:1], v224, off offset:64
	global_store_short_d16_hi v[0:1], v224, off offset:2112
	s_cbranch_scc0 .LBB0_2078

.LBB0_2262:
	s_lshl_b32 s6, s5, 7
	s_ashr_i32 s7, s6, 31
	s_lshl_b64 s[8:9], s[6:7], 11
	v_mov_b32_e32 v0, v161
	s_add_u32 s8, s12, s8
	s_waitcnt vmcnt(8)
	v_mov_b32_e32 v49, v186
	s_addc_u32 s9, s13, s9
	s_ashr_i32 s5, s4, 31
	s_lshl_b64 s[10:11], s[4:5], 18
	v_lshlrev_b32_e32 v16, 4, v49
	v_ashrrev_i32_e32 v50, 3, v49
	v_and_b32_e32 v48, 0x70, v16
	s_add_u32 s10, s14, s10
	v_lshl_or_b32 v168, v50, 11, v48
	s_addc_u32 s11, s15, s11
	v_add_u32_e32 v169, 0x10000, v168
	v_add_u32_e32 v170, 0x20000, v168
	v_add_u32_e32 v171, 0x30000, v168
	s_barrier
	global_load_dwordx4 v[16:19], v168, s[8:9]
	global_load_dwordx4 v[20:23], v169, s[8:9]
	global_load_dwordx4 v[24:27], v170, s[8:9]
	global_load_dwordx4 v[28:31], v171, s[8:9]
	global_load_dwordx4 v[32:35], v168, s[10:11]
	global_load_dwordx4 v[36:39], v169, s[10:11]
	global_load_dwordx4 v[40:43], v170, s[10:11]
	global_load_dwordx4 v[44:47], v171, s[10:11]
	v_mad_u64_u32 v[130:131], s[18:19], v50, s43, v[48:49]
	v_mov_b32_e32 v1, v0
	v_mov_b32_e32 v2, v0
	v_mov_b32_e32 v3, v0
	v_mov_b32_e32 v4, v0
	v_mov_b32_e32 v5, v0
	v_mov_b32_e32 v6, v0
	v_mov_b32_e32 v7, v0
	s_waitcnt vmcnt(8)
	v_mov_b32_e32 v8, v0
	v_mov_b32_e32 v9, v0
	v_mov_b32_e32 v10, v0
	v_mov_b32_e32 v11, v0
	v_mov_b32_e32 v12, v0
	v_mov_b32_e32 v13, v0
	v_mov_b32_e32 v14, v0
	v_mov_b32_e32 v15, v0
	s_waitcnt vmcnt(7)
	ds_write_b128 v130, v[16:19]
	s_waitcnt vmcnt(6)
	ds_write_b128 v130, v[20:23] offset:4608
	s_waitcnt vmcnt(5)
	ds_write_b128 v130, v[24:27] offset:9216
	s_waitcnt vmcnt(4)
	ds_write_b128 v130, v[28:31] offset:13824
	s_waitcnt vmcnt(3)
	ds_write_b128 v130, v[32:35] offset:36864
	s_waitcnt vmcnt(2)
	ds_write_b128 v130, v[36:39] offset:41472
	s_waitcnt vmcnt(1)
	ds_write_b128 v130, v[40:43] offset:46080
	s_waitcnt vmcnt(0)
	ds_write_b128 v130, v[44:47] offset:50688
	global_load_dwordx4 v[96:99], v168, s[8:9] offset:128
	global_load_dwordx4 v[100:103], v169, s[8:9] offset:128
	global_load_dwordx4 v[104:107], v170, s[8:9] offset:128
	global_load_dwordx4 v[108:111], v171, s[8:9] offset:128
	global_load_dwordx4 v[64:67], v168, s[10:11] offset:128
	global_load_dwordx4 v[68:71], v169, s[10:11] offset:128
	global_load_dwordx4 v[72:75], v170, s[10:11] offset:128
	global_load_dwordx4 v[76:79], v171, s[10:11] offset:128
	v_lshrrev_b32_e32 v18, 1, v49
	v_and_b32_e32 v17, 0x5f, v49
	v_and_b32_e32 v16, 16, v18
	v_mad_u32_u24 v131, v17, s43, v16
	v_and_b32_e32 v17, 31, v49
	v_and_or_b32 v17, v18, s44, v17
	v_mad_u64_u32 v[128:129], s[18:19], v17, s43, v[16:17]
	s_waitcnt lgkmcnt(0)
	s_barrier
	ds_read_b128 v[16:19], v128
	ds_read_b128 v[84:87], v131 offset:41472
	ds_read_b128 v[80:83], v128 offset:4608
	ds_read_b128 v[172:175], v128 offset:32
	s_waitcnt lgkmcnt(2)
	v_mfma_f32_32x32x16_bf16 v[48:63], v[16:19], v[84:87], v[0:15]
	ds_read_b128 v[88:91], v131 offset:36864
	ds_read_b128 v[176:179], v128 offset:4640
	ds_read_b128 v[180:183], v131 offset:36896
	ds_read_b128 v[196:199], v131 offset:41504
	v_add_u32_e32 v129, 0xd800, v130
	s_waitcnt lgkmcnt(3)
	v_mfma_f32_32x32x16_bf16 v[32:47], v[16:19], v[88:91], v[0:15]
	v_mfma_f32_32x32x16_bf16 v[16:31], v[80:83], v[88:91], v[0:15]
	v_mfma_f32_32x32x16_bf16 v[0:15], v[80:83], v[84:87], v[0:15]
	s_waitcnt lgkmcnt(1)
	v_mfma_f32_32x32x16_bf16 v[32:47], v[172:175], v[180:183], v[32:47]
	s_waitcnt lgkmcnt(0)
	v_mfma_f32_32x32x16_bf16 v[48:63], v[172:175], v[196:199], v[48:63]
	v_mfma_f32_32x32x16_bf16 v[16:31], v[176:179], v[180:183], v[16:31]
	v_mfma_f32_32x32x16_bf16 v[0:15], v[176:179], v[196:199], v[0:15]
	ds_read_b128 v[200:203], v128 offset:64
	ds_read_b128 v[210:213], v128 offset:4672
	ds_read_b128 v[214:217], v131 offset:36928
	ds_read_b128 v[218:221], v131 offset:41536
	s_waitcnt lgkmcnt(1)
	v_mfma_f32_32x32x16_bf16 v[32:47], v[200:203], v[214:217], v[32:47]
	s_waitcnt lgkmcnt(0)
	v_mfma_f32_32x32x16_bf16 v[48:63], v[200:203], v[218:221], v[48:63]
	v_mfma_f32_32x32x16_bf16 v[16:31], v[210:213], v[214:217], v[16:31]
	v_mfma_f32_32x32x16_bf16 v[0:15], v[210:213], v[218:221], v[0:15]
	global_load_dwordx4 v[112:115], v168, s[8:9] offset:256
	global_load_dwordx4 v[116:119], v169, s[8:9] offset:256
	global_load_dwordx4 v[120:123], v170, s[8:9] offset:256
	global_load_dwordx4 v[124:127], v171, s[8:9] offset:256
	global_load_dwordx4 v[80:83], v168, s[10:11] offset:256
	global_load_dwordx4 v[84:87], v169, s[10:11] offset:256
	global_load_dwordx4 v[88:91], v170, s[10:11] offset:256
	global_load_dwordx4 v[92:95], v171, s[10:11] offset:256
	s_waitcnt vmcnt(15)
	ds_write_b128 v130, v[96:99] offset:18432
	s_waitcnt vmcnt(14)
	ds_write_b128 v130, v[100:103] offset:23040
	s_waitcnt vmcnt(13)
	ds_write_b128 v130, v[104:107] offset:27648
	s_waitcnt vmcnt(12)
	ds_write_b128 v130, v[108:111] offset:32256
	ds_read_b128 v[96:99], v128 offset:96
	ds_read_b128 v[100:103], v128 offset:4704
	ds_read_b128 v[104:107], v131 offset:36960
	ds_read_b128 v[108:111], v131 offset:41568
	s_waitcnt vmcnt(11)
	ds_write_b128 v130, v[64:67] offset:55296
	s_waitcnt vmcnt(10)
	ds_write_b128 v130, v[68:71] offset:59904
	s_waitcnt vmcnt(9)
	ds_write_b128 v130, v[72:75] offset:64512
	s_waitcnt vmcnt(8)
	ds_write_b128 v129, v[76:79] offset:13824
	s_waitcnt lgkmcnt(5)
	v_mfma_f32_32x32x16_bf16 v[32:47], v[96:99], v[104:107], v[32:47]
	s_waitcnt lgkmcnt(0)
	s_barrier
	v_mfma_f32_32x32x16_bf16 v[48:63], v[96:99], v[108:111], v[48:63]
	v_mfma_f32_32x32x16_bf16 v[16:31], v[100:103], v[104:107], v[16:31]
	v_mfma_f32_32x32x16_bf16 v[0:15], v[100:103], v[108:111], v[0:15]
	ds_read_b128 v[64:67], v128 offset:23040
	ds_read_b128 v[72:75], v128 offset:18432
	ds_read_b128 v[68:71], v131 offset:59904
	ds_read_b128 v[100:103], v131 offset:55296
	ds_read_b128 v[76:79], v128 offset:18464
	ds_read_b128 v[96:99], v128 offset:23072
	ds_read_b128 v[104:107], v131 offset:55328
	ds_read_b128 v[108:111], v131 offset:59936
	s_waitcnt lgkmcnt(4)
	v_mfma_f32_32x32x16_bf16 v[32:47], v[72:75], v[100:103], v[32:47]
	v_mfma_f32_32x32x16_bf16 v[48:63], v[72:75], v[68:71], v[48:63]
	v_mfma_f32_32x32x16_bf16 v[16:31], v[64:67], v[100:103], v[16:31]
	v_mfma_f32_32x32x16_bf16 v[0:15], v[64:67], v[68:71], v[0:15]
	global_load_dwordx4 v[64:67], v168, s[8:9] offset:384
	global_load_dwordx4 v[68:71], v169, s[8:9] offset:384
	global_load_dwordx4 v[72:75], v170, s[8:9] offset:384
	global_load_dwordx4 v[100:103], v171, s[8:9] offset:384
	global_load_dwordx4 v[172:175], v168, s[10:11] offset:384
	global_load_dwordx4 v[176:179], v169, s[10:11] offset:384
	global_load_dwordx4 v[180:183], v170, s[10:11] offset:384
	global_load_dwordx4 v[196:199], v171, s[10:11] offset:384
	ds_read_b128 v[200:203], v128 offset:18496
	ds_read_b128 v[210:213], v128 offset:23104
	ds_read_b128 v[214:217], v131 offset:55360
	ds_read_b128 v[218:221], v131 offset:59968
	s_waitcnt vmcnt(15)
	ds_write_b128 v130, v[112:115]
	s_waitcnt vmcnt(14)
	ds_write_b128 v130, v[116:119] offset:4608
	s_waitcnt vmcnt(13)
	ds_write_b128 v130, v[120:123] offset:9216
	s_waitcnt vmcnt(12)
	ds_write_b128 v130, v[124:127] offset:13824
	s_waitcnt lgkmcnt(9)
	v_mfma_f32_32x32x16_bf16 v[32:47], v[76:79], v[104:107], v[32:47]
	s_waitcnt lgkmcnt(8)
	v_mfma_f32_32x32x16_bf16 v[48:63], v[76:79], v[108:111], v[48:63]
	v_mfma_f32_32x32x16_bf16 v[16:31], v[96:99], v[104:107], v[16:31]
	v_mfma_f32_32x32x16_bf16 v[0:15], v[96:99], v[108:111], v[0:15]
	ds_read_b128 v[76:79], v128 offset:18528
	ds_read_b128 v[96:99], v128 offset:23136
	ds_read_b128 v[104:107], v131 offset:55392
	ds_read_b128 v[108:111], v131 offset:60000
	s_waitcnt vmcnt(11)
	ds_write_b128 v130, v[80:83] offset:36864
	s_waitcnt vmcnt(10)
	ds_write_b128 v130, v[84:87] offset:41472
	s_waitcnt vmcnt(9)
	ds_write_b128 v130, v[88:91] offset:46080
	s_waitcnt vmcnt(8)
	ds_write_b128 v130, v[92:95] offset:50688
	s_waitcnt lgkmcnt(13)
	v_mfma_f32_32x32x16_bf16 v[32:47], v[200:203], v[214:217], v[32:47]
	s_waitcnt lgkmcnt(0)
	s_barrier
	v_mfma_f32_32x32x16_bf16 v[48:63], v[200:203], v[218:221], v[48:63]
	v_mfma_f32_32x32x16_bf16 v[16:31], v[210:213], v[214:217], v[16:31]
	v_mfma_f32_32x32x16_bf16 v[0:15], v[210:213], v[218:221], v[0:15]
	v_mfma_f32_32x32x16_bf16 v[32:47], v[76:79], v[104:107], v[32:47]
	v_mfma_f32_32x32x16_bf16 v[48:63], v[76:79], v[108:111], v[48:63]
	v_mfma_f32_32x32x16_bf16 v[16:31], v[96:99], v[104:107], v[16:31]
	v_mfma_f32_32x32x16_bf16 v[0:15], v[96:99], v[108:111], v[0:15]
	ds_read_b128 v[76:79], v128 offset:4608
	ds_read_b128 v[84:87], v128
	ds_read_b128 v[80:83], v131 offset:41472
	ds_read_b128 v[96:99], v131 offset:36864
	ds_read_b128 v[88:91], v128 offset:32
	ds_read_b128 v[92:95], v128 offset:4640
	ds_read_b128 v[104:107], v131 offset:36896
	ds_read_b128 v[108:111], v131 offset:41504
	s_waitcnt lgkmcnt(4)
	v_mfma_f32_32x32x16_bf16 v[32:47], v[84:87], v[96:99], v[32:47]
	v_mfma_f32_32x32x16_bf16 v[48:63], v[84:87], v[80:83], v[48:63]
	v_mfma_f32_32x32x16_bf16 v[16:31], v[76:79], v[96:99], v[16:31]
	v_mfma_f32_32x32x16_bf16 v[0:15], v[76:79], v[80:83], v[0:15]
	global_load_dwordx4 v[76:79], v168, s[8:9] offset:512
	global_load_dwordx4 v[80:83], v169, s[8:9] offset:512
	global_load_dwordx4 v[84:87], v170, s[8:9] offset:512
	global_load_dwordx4 v[96:99], v171, s[8:9] offset:512
	global_load_dwordx4 v[112:115], v168, s[10:11] offset:512
	global_load_dwordx4 v[116:119], v169, s[10:11] offset:512
	global_load_dwordx4 v[120:123], v170, s[10:11] offset:512
	global_load_dwordx4 v[124:127], v171, s[10:11] offset:512
	ds_read_b128 v[200:203], v128 offset:64
	ds_read_b128 v[210:213], v128 offset:4672
	ds_read_b128 v[214:217], v131 offset:36928
	ds_read_b128 v[218:221], v131 offset:41536
	s_waitcnt vmcnt(15)
	ds_write_b128 v130, v[64:67] offset:18432
	s_waitcnt vmcnt(14)
	ds_write_b128 v130, v[68:71] offset:23040
	s_waitcnt vmcnt(13)
	ds_write_b128 v130, v[72:75] offset:27648
	s_waitcnt vmcnt(12)
	ds_write_b128 v130, v[100:103] offset:32256
	s_waitcnt lgkmcnt(9)
	v_mfma_f32_32x32x16_bf16 v[32:47], v[88:91], v[104:107], v[32:47]
	s_waitcnt lgkmcnt(8)
	v_mfma_f32_32x32x16_bf16 v[48:63], v[88:91], v[108:111], v[48:63]
	v_mfma_f32_32x32x16_bf16 v[16:31], v[92:95], v[104:107], v[16:31]
	v_mfma_f32_32x32x16_bf16 v[0:15], v[92:95], v[108:111], v[0:15]
	ds_read_b128 v[64:67], v128 offset:96
	ds_read_b128 v[68:71], v128 offset:4704
	ds_read_b128 v[72:75], v131 offset:36960
	ds_read_b128 v[88:91], v131 offset:41568
	s_waitcnt vmcnt(11)
	ds_write_b128 v130, v[172:175] offset:55296
	s_waitcnt vmcnt(10)
	ds_write_b128 v130, v[176:179] offset:59904
	s_waitcnt vmcnt(9)
	ds_write_b128 v130, v[180:183] offset:64512
	s_waitcnt vmcnt(8)
	ds_write_b128 v129, v[196:199] offset:13824
	s_waitcnt lgkmcnt(13)
	v_mfma_f32_32x32x16_bf16 v[32:47], v[200:203], v[214:217], v[32:47]
	s_waitcnt lgkmcnt(0)
	s_barrier
	v_mfma_f32_32x32x16_bf16 v[48:63], v[200:203], v[218:221], v[48:63]
	v_mfma_f32_32x32x16_bf16 v[16:31], v[210:213], v[214:217], v[16:31]
	v_mfma_f32_32x32x16_bf16 v[0:15], v[210:213], v[218:221], v[0:15]
	v_mfma_f32_32x32x16_bf16 v[32:47], v[64:67], v[72:75], v[32:47]
	v_mfma_f32_32x32x16_bf16 v[48:63], v[64:67], v[88:91], v[48:63]
	v_mfma_f32_32x32x16_bf16 v[16:31], v[68:71], v[72:75], v[16:31]
	v_mfma_f32_32x32x16_bf16 v[0:15], v[68:71], v[88:91], v[0:15]
	ds_read_b128 v[64:67], v128 offset:23040
	ds_read_b128 v[72:75], v128 offset:18432
	ds_read_b128 v[68:71], v131 offset:59904
	ds_read_b128 v[100:103], v131 offset:55296
	ds_read_b128 v[88:91], v128 offset:18464
	ds_read_b128 v[92:95], v128 offset:23072
	ds_read_b128 v[104:107], v131 offset:55328
	ds_read_b128 v[108:111], v131 offset:59936
	s_waitcnt lgkmcnt(4)
	v_mfma_f32_32x32x16_bf16 v[32:47], v[72:75], v[100:103], v[32:47]
	v_mfma_f32_32x32x16_bf16 v[48:63], v[72:75], v[68:71], v[48:63]
	v_mfma_f32_32x32x16_bf16 v[16:31], v[64:67], v[100:103], v[16:31]
	v_mfma_f32_32x32x16_bf16 v[0:15], v[64:67], v[68:71], v[0:15]
	global_load_dwordx4 v[64:67], v168, s[8:9] offset:640
	global_load_dwordx4 v[68:71], v169, s[8:9] offset:640
	global_load_dwordx4 v[72:75], v170, s[8:9] offset:640
	global_load_dwordx4 v[100:103], v171, s[8:9] offset:640
	global_load_dwordx4 v[172:175], v168, s[10:11] offset:640
	global_load_dwordx4 v[176:179], v169, s[10:11] offset:640
	global_load_dwordx4 v[180:183], v170, s[10:11] offset:640
	global_load_dwordx4 v[196:199], v171, s[10:11] offset:640
	ds_read_b128 v[200:203], v128 offset:18496
	ds_read_b128 v[210:213], v128 offset:23104
	ds_read_b128 v[214:217], v131 offset:55360
	ds_read_b128 v[218:221], v131 offset:59968
	s_waitcnt vmcnt(15)
	ds_write_b128 v130, v[76:79]
	s_waitcnt vmcnt(14)
	ds_write_b128 v130, v[80:83] offset:4608
	s_waitcnt vmcnt(13)
	ds_write_b128 v130, v[84:87] offset:9216
	s_waitcnt vmcnt(12)
	ds_write_b128 v130, v[96:99] offset:13824
	s_waitcnt lgkmcnt(9)
	v_mfma_f32_32x32x16_bf16 v[32:47], v[88:91], v[104:107], v[32:47]
	s_waitcnt lgkmcnt(8)
	v_mfma_f32_32x32x16_bf16 v[48:63], v[88:91], v[108:111], v[48:63]
	v_mfma_f32_32x32x16_bf16 v[16:31], v[92:95], v[104:107], v[16:31]
	v_mfma_f32_32x32x16_bf16 v[0:15], v[92:95], v[108:111], v[0:15]
	ds_read_b128 v[76:79], v128 offset:18528
	ds_read_b128 v[80:83], v128 offset:23136
	ds_read_b128 v[84:87], v131 offset:55392
	ds_read_b128 v[88:91], v131 offset:60000
	s_waitcnt vmcnt(11)
	ds_write_b128 v130, v[112:115] offset:36864
	s_waitcnt vmcnt(10)
	ds_write_b128 v130, v[116:119] offset:41472
	s_waitcnt vmcnt(9)
	ds_write_b128 v130, v[120:123] offset:46080
	s_waitcnt vmcnt(8)
	ds_write_b128 v130, v[124:127] offset:50688
	s_waitcnt lgkmcnt(13)
	v_mfma_f32_32x32x16_bf16 v[32:47], v[200:203], v[214:217], v[32:47]
	s_waitcnt lgkmcnt(0)
	s_barrier
	v_mfma_f32_32x32x16_bf16 v[48:63], v[200:203], v[218:221], v[48:63]
	v_mfma_f32_32x32x16_bf16 v[16:31], v[210:213], v[214:217], v[16:31]
	v_mfma_f32_32x32x16_bf16 v[0:15], v[210:213], v[218:221], v[0:15]
	v_mfma_f32_32x32x16_bf16 v[32:47], v[76:79], v[84:87], v[32:47]
	v_mfma_f32_32x32x16_bf16 v[48:63], v[76:79], v[88:91], v[48:63]
	v_mfma_f32_32x32x16_bf16 v[16:31], v[80:83], v[84:87], v[16:31]
	v_mfma_f32_32x32x16_bf16 v[0:15], v[80:83], v[88:91], v[0:15]
	ds_read_b128 v[76:79], v128 offset:4608
	ds_read_b128 v[84:87], v128
	ds_read_b128 v[80:83], v131 offset:41472
	ds_read_b128 v[96:99], v131 offset:36864
	ds_read_b128 v[88:91], v128 offset:32
	ds_read_b128 v[92:95], v128 offset:4640
	ds_read_b128 v[104:107], v131 offset:36896
	ds_read_b128 v[108:111], v131 offset:41504
	s_waitcnt lgkmcnt(4)
	v_mfma_f32_32x32x16_bf16 v[32:47], v[84:87], v[96:99], v[32:47]
	v_mfma_f32_32x32x16_bf16 v[48:63], v[84:87], v[80:83], v[48:63]
	v_mfma_f32_32x32x16_bf16 v[16:31], v[76:79], v[96:99], v[16:31]
	v_mfma_f32_32x32x16_bf16 v[0:15], v[76:79], v[80:83], v[0:15]
	global_load_dwordx4 v[76:79], v168, s[8:9] offset:768
	global_load_dwordx4 v[80:83], v169, s[8:9] offset:768
	global_load_dwordx4 v[84:87], v170, s[8:9] offset:768
	global_load_dwordx4 v[96:99], v171, s[8:9] offset:768
	global_load_dwordx4 v[112:115], v168, s[10:11] offset:768
	global_load_dwordx4 v[116:119], v169, s[10:11] offset:768
	global_load_dwordx4 v[120:123], v170, s[10:11] offset:768
	global_load_dwordx4 v[124:127], v171, s[10:11] offset:768
	ds_read_b128 v[200:203], v128 offset:64
	ds_read_b128 v[210:213], v128 offset:4672
	ds_read_b128 v[214:217], v131 offset:36928
	ds_read_b128 v[218:221], v131 offset:41536
	s_waitcnt vmcnt(15)
	ds_write_b128 v130, v[64:67] offset:18432
	s_waitcnt vmcnt(14)
	ds_write_b128 v130, v[68:71] offset:23040
	s_waitcnt vmcnt(13)
	ds_write_b128 v130, v[72:75] offset:27648
	s_waitcnt vmcnt(12)
	ds_write_b128 v130, v[100:103] offset:32256
	s_waitcnt lgkmcnt(9)
	v_mfma_f32_32x32x16_bf16 v[32:47], v[88:91], v[104:107], v[32:47]
	s_waitcnt lgkmcnt(8)
	v_mfma_f32_32x32x16_bf16 v[48:63], v[88:91], v[108:111], v[48:63]
	v_mfma_f32_32x32x16_bf16 v[16:31], v[92:95], v[104:107], v[16:31]
	v_mfma_f32_32x32x16_bf16 v[0:15], v[92:95], v[108:111], v[0:15]
	ds_read_b128 v[64:67], v128 offset:96
	ds_read_b128 v[68:71], v128 offset:4704
	ds_read_b128 v[72:75], v131 offset:36960
	ds_read_b128 v[88:91], v131 offset:41568
	s_waitcnt vmcnt(11)
	ds_write_b128 v130, v[172:175] offset:55296
	s_waitcnt vmcnt(10)
	ds_write_b128 v130, v[176:179] offset:59904
	s_waitcnt vmcnt(9)
	ds_write_b128 v130, v[180:183] offset:64512
	s_waitcnt vmcnt(8)
	ds_write_b128 v129, v[196:199] offset:13824
	s_waitcnt lgkmcnt(13)
	v_mfma_f32_32x32x16_bf16 v[32:47], v[200:203], v[214:217], v[32:47]
	s_waitcnt lgkmcnt(0)
	s_barrier
	v_mfma_f32_32x32x16_bf16 v[48:63], v[200:203], v[218:221], v[48:63]
	v_mfma_f32_32x32x16_bf16 v[16:31], v[210:213], v[214:217], v[16:31]
	v_mfma_f32_32x32x16_bf16 v[0:15], v[210:213], v[218:221], v[0:15]
	v_mfma_f32_32x32x16_bf16 v[32:47], v[64:67], v[72:75], v[32:47]
	v_mfma_f32_32x32x16_bf16 v[48:63], v[64:67], v[88:91], v[48:63]
	v_mfma_f32_32x32x16_bf16 v[16:31], v[68:71], v[72:75], v[16:31]
	v_mfma_f32_32x32x16_bf16 v[0:15], v[68:71], v[88:91], v[0:15]
	ds_read_b128 v[64:67], v128 offset:23040
	ds_read_b128 v[72:75], v128 offset:18432
	ds_read_b128 v[68:71], v131 offset:59904
	ds_read_b128 v[100:103], v131 offset:55296
	ds_read_b128 v[88:91], v128 offset:18464
	ds_read_b128 v[92:95], v128 offset:23072
	ds_read_b128 v[104:107], v131 offset:55328
	ds_read_b128 v[108:111], v131 offset:59936
	s_waitcnt lgkmcnt(4)
	v_mfma_f32_32x32x16_bf16 v[32:47], v[72:75], v[100:103], v[32:47]
	v_mfma_f32_32x32x16_bf16 v[48:63], v[72:75], v[68:71], v[48:63]
	v_mfma_f32_32x32x16_bf16 v[16:31], v[64:67], v[100:103], v[16:31]
	v_mfma_f32_32x32x16_bf16 v[0:15], v[64:67], v[68:71], v[0:15]
	global_load_dwordx4 v[64:67], v168, s[8:9] offset:896
	global_load_dwordx4 v[68:71], v169, s[8:9] offset:896
	global_load_dwordx4 v[72:75], v170, s[8:9] offset:896
	global_load_dwordx4 v[100:103], v171, s[8:9] offset:896
	global_load_dwordx4 v[172:175], v168, s[10:11] offset:896
	global_load_dwordx4 v[176:179], v169, s[10:11] offset:896
	global_load_dwordx4 v[180:183], v170, s[10:11] offset:896
	global_load_dwordx4 v[196:199], v171, s[10:11] offset:896
	ds_read_b128 v[200:203], v128 offset:18496
	ds_read_b128 v[210:213], v128 offset:23104
	ds_read_b128 v[214:217], v131 offset:55360
	ds_read_b128 v[218:221], v131 offset:59968
	s_waitcnt vmcnt(15)
	ds_write_b128 v130, v[76:79]
	s_waitcnt vmcnt(14)
	ds_write_b128 v130, v[80:83] offset:4608
	s_waitcnt vmcnt(13)
	ds_write_b128 v130, v[84:87] offset:9216
	s_waitcnt vmcnt(12)
	ds_write_b128 v130, v[96:99] offset:13824
	s_waitcnt lgkmcnt(9)
	v_mfma_f32_32x32x16_bf16 v[32:47], v[88:91], v[104:107], v[32:47]
	s_waitcnt lgkmcnt(8)
	v_mfma_f32_32x32x16_bf16 v[48:63], v[88:91], v[108:111], v[48:63]
	v_mfma_f32_32x32x16_bf16 v[16:31], v[92:95], v[104:107], v[16:31]
	v_mfma_f32_32x32x16_bf16 v[0:15], v[92:95], v[108:111], v[0:15]
	ds_read_b128 v[76:79], v128 offset:18528
	ds_read_b128 v[80:83], v128 offset:23136
	ds_read_b128 v[84:87], v131 offset:55392
	ds_read_b128 v[88:91], v131 offset:60000
	s_waitcnt vmcnt(11)
	ds_write_b128 v130, v[112:115] offset:36864
	s_waitcnt vmcnt(10)
	ds_write_b128 v130, v[116:119] offset:41472
	s_waitcnt vmcnt(9)
	ds_write_b128 v130, v[120:123] offset:46080
	s_waitcnt vmcnt(8)
	ds_write_b128 v130, v[124:127] offset:50688
	s_waitcnt lgkmcnt(13)
	v_mfma_f32_32x32x16_bf16 v[32:47], v[200:203], v[214:217], v[32:47]
	s_waitcnt lgkmcnt(0)
	s_barrier
	v_mfma_f32_32x32x16_bf16 v[48:63], v[200:203], v[218:221], v[48:63]
	v_mfma_f32_32x32x16_bf16 v[16:31], v[210:213], v[214:217], v[16:31]
	v_mfma_f32_32x32x16_bf16 v[0:15], v[210:213], v[218:221], v[0:15]
	v_mfma_f32_32x32x16_bf16 v[32:47], v[76:79], v[84:87], v[32:47]
	v_mfma_f32_32x32x16_bf16 v[48:63], v[76:79], v[88:91], v[48:63]
	v_mfma_f32_32x32x16_bf16 v[16:31], v[80:83], v[84:87], v[16:31]
	v_mfma_f32_32x32x16_bf16 v[0:15], v[80:83], v[88:91], v[0:15]
	ds_read_b128 v[76:79], v128 offset:4608
	ds_read_b128 v[84:87], v128
	ds_read_b128 v[80:83], v131 offset:41472
	ds_read_b128 v[96:99], v131 offset:36864
	ds_read_b128 v[88:91], v128 offset:32
	ds_read_b128 v[92:95], v128 offset:4640
	ds_read_b128 v[104:107], v131 offset:36896
	ds_read_b128 v[108:111], v131 offset:41504
	s_waitcnt lgkmcnt(4)
	v_mfma_f32_32x32x16_bf16 v[32:47], v[84:87], v[96:99], v[32:47]
	v_mfma_f32_32x32x16_bf16 v[48:63], v[84:87], v[80:83], v[48:63]
	v_mfma_f32_32x32x16_bf16 v[16:31], v[76:79], v[96:99], v[16:31]
	v_mfma_f32_32x32x16_bf16 v[0:15], v[76:79], v[80:83], v[0:15]
	global_load_dwordx4 v[76:79], v168, s[8:9] offset:1024
	global_load_dwordx4 v[80:83], v169, s[8:9] offset:1024
	global_load_dwordx4 v[84:87], v170, s[8:9] offset:1024
	global_load_dwordx4 v[96:99], v171, s[8:9] offset:1024
	global_load_dwordx4 v[112:115], v168, s[10:11] offset:1024
	global_load_dwordx4 v[116:119], v169, s[10:11] offset:1024
	global_load_dwordx4 v[120:123], v170, s[10:11] offset:1024
	global_load_dwordx4 v[124:127], v171, s[10:11] offset:1024
	ds_read_b128 v[200:203], v128 offset:64
	ds_read_b128 v[210:213], v128 offset:4672
	ds_read_b128 v[214:217], v131 offset:36928
	ds_read_b128 v[218:221], v131 offset:41536
	s_waitcnt vmcnt(15)
	ds_write_b128 v130, v[64:67] offset:18432
	s_waitcnt vmcnt(14)
	ds_write_b128 v130, v[68:71] offset:23040
	s_waitcnt vmcnt(13)
	ds_write_b128 v130, v[72:75] offset:27648
	s_waitcnt vmcnt(12)
	ds_write_b128 v130, v[100:103] offset:32256
	s_waitcnt lgkmcnt(9)
	v_mfma_f32_32x32x16_bf16 v[32:47], v[88:91], v[104:107], v[32:47]
	s_waitcnt lgkmcnt(8)
	v_mfma_f32_32x32x16_bf16 v[48:63], v[88:91], v[108:111], v[48:63]
	v_mfma_f32_32x32x16_bf16 v[16:31], v[92:95], v[104:107], v[16:31]
	v_mfma_f32_32x32x16_bf16 v[0:15], v[92:95], v[108:111], v[0:15]
	ds_read_b128 v[64:67], v128 offset:96
	ds_read_b128 v[68:71], v128 offset:4704
	ds_read_b128 v[72:75], v131 offset:36960
	ds_read_b128 v[88:91], v131 offset:41568
	s_waitcnt vmcnt(11)
	ds_write_b128 v130, v[172:175] offset:55296
	s_waitcnt vmcnt(10)
	ds_write_b128 v130, v[176:179] offset:59904
	s_waitcnt vmcnt(9)
	ds_write_b128 v130, v[180:183] offset:64512
	s_waitcnt vmcnt(8)
	ds_write_b128 v129, v[196:199] offset:13824
	s_waitcnt lgkmcnt(13)
	v_mfma_f32_32x32x16_bf16 v[32:47], v[200:203], v[214:217], v[32:47]
	s_waitcnt lgkmcnt(0)
	s_barrier
	v_mfma_f32_32x32x16_bf16 v[48:63], v[200:203], v[218:221], v[48:63]
	v_mfma_f32_32x32x16_bf16 v[16:31], v[210:213], v[214:217], v[16:31]
	v_mfma_f32_32x32x16_bf16 v[0:15], v[210:213], v[218:221], v[0:15]
	v_mfma_f32_32x32x16_bf16 v[32:47], v[64:67], v[72:75], v[32:47]
	v_mfma_f32_32x32x16_bf16 v[48:63], v[64:67], v[88:91], v[48:63]
	v_mfma_f32_32x32x16_bf16 v[16:31], v[68:71], v[72:75], v[16:31]
	v_mfma_f32_32x32x16_bf16 v[0:15], v[68:71], v[88:91], v[0:15]
	ds_read_b128 v[64:67], v128 offset:23040
	ds_read_b128 v[72:75], v128 offset:18432
	ds_read_b128 v[68:71], v131 offset:59904
	ds_read_b128 v[100:103], v131 offset:55296
	ds_read_b128 v[88:91], v128 offset:18464
	ds_read_b128 v[92:95], v128 offset:23072
	ds_read_b128 v[104:107], v131 offset:55328
	ds_read_b128 v[108:111], v131 offset:59936
	s_waitcnt lgkmcnt(4)
	v_mfma_f32_32x32x16_bf16 v[32:47], v[72:75], v[100:103], v[32:47]
	v_mfma_f32_32x32x16_bf16 v[48:63], v[72:75], v[68:71], v[48:63]
	v_mfma_f32_32x32x16_bf16 v[16:31], v[64:67], v[100:103], v[16:31]
	v_mfma_f32_32x32x16_bf16 v[0:15], v[64:67], v[68:71], v[0:15]
	global_load_dwordx4 v[64:67], v168, s[8:9] offset:1152
	global_load_dwordx4 v[68:71], v169, s[8:9] offset:1152
	global_load_dwordx4 v[72:75], v170, s[8:9] offset:1152
	global_load_dwordx4 v[100:103], v171, s[8:9] offset:1152
	global_load_dwordx4 v[172:175], v168, s[10:11] offset:1152
	global_load_dwordx4 v[176:179], v169, s[10:11] offset:1152
	global_load_dwordx4 v[180:183], v170, s[10:11] offset:1152
	global_load_dwordx4 v[196:199], v171, s[10:11] offset:1152
	ds_read_b128 v[200:203], v128 offset:18496
	ds_read_b128 v[210:213], v128 offset:23104
	ds_read_b128 v[214:217], v131 offset:55360
	ds_read_b128 v[218:221], v131 offset:59968
	s_waitcnt vmcnt(15)
	ds_write_b128 v130, v[76:79]
	s_waitcnt vmcnt(14)
	ds_write_b128 v130, v[80:83] offset:4608
	s_waitcnt vmcnt(13)
	ds_write_b128 v130, v[84:87] offset:9216
	s_waitcnt vmcnt(12)
	ds_write_b128 v130, v[96:99] offset:13824
	s_waitcnt lgkmcnt(9)
	v_mfma_f32_32x32x16_bf16 v[32:47], v[88:91], v[104:107], v[32:47]
	s_waitcnt lgkmcnt(8)
	v_mfma_f32_32x32x16_bf16 v[48:63], v[88:91], v[108:111], v[48:63]
	v_mfma_f32_32x32x16_bf16 v[16:31], v[92:95], v[104:107], v[16:31]
	v_mfma_f32_32x32x16_bf16 v[0:15], v[92:95], v[108:111], v[0:15]
	ds_read_b128 v[76:79], v128 offset:18528
	ds_read_b128 v[80:83], v128 offset:23136
	ds_read_b128 v[84:87], v131 offset:55392
	ds_read_b128 v[88:91], v131 offset:60000
	s_waitcnt vmcnt(11)
	ds_write_b128 v130, v[112:115] offset:36864
	s_waitcnt vmcnt(10)
	ds_write_b128 v130, v[116:119] offset:41472
	s_waitcnt vmcnt(9)
	ds_write_b128 v130, v[120:123] offset:46080
	s_waitcnt vmcnt(8)
	ds_write_b128 v130, v[124:127] offset:50688
	s_waitcnt lgkmcnt(13)
	v_mfma_f32_32x32x16_bf16 v[32:47], v[200:203], v[214:217], v[32:47]
	s_waitcnt lgkmcnt(0)
	s_barrier
	v_mfma_f32_32x32x16_bf16 v[48:63], v[200:203], v[218:221], v[48:63]
	v_mfma_f32_32x32x16_bf16 v[16:31], v[210:213], v[214:217], v[16:31]
	v_mfma_f32_32x32x16_bf16 v[0:15], v[210:213], v[218:221], v[0:15]
	v_mfma_f32_32x32x16_bf16 v[32:47], v[76:79], v[84:87], v[32:47]
	v_mfma_f32_32x32x16_bf16 v[48:63], v[76:79], v[88:91], v[48:63]
	v_mfma_f32_32x32x16_bf16 v[16:31], v[80:83], v[84:87], v[16:31]
	v_mfma_f32_32x32x16_bf16 v[0:15], v[80:83], v[88:91], v[0:15]
	ds_read_b128 v[76:79], v128 offset:4608
	ds_read_b128 v[84:87], v128
	ds_read_b128 v[80:83], v131 offset:41472
	ds_read_b128 v[96:99], v131 offset:36864
	ds_read_b128 v[88:91], v128 offset:32
	ds_read_b128 v[92:95], v128 offset:4640
	ds_read_b128 v[104:107], v131 offset:36896
	ds_read_b128 v[108:111], v131 offset:41504
	s_waitcnt lgkmcnt(4)
	v_mfma_f32_32x32x16_bf16 v[32:47], v[84:87], v[96:99], v[32:47]
	v_mfma_f32_32x32x16_bf16 v[48:63], v[84:87], v[80:83], v[48:63]
	v_mfma_f32_32x32x16_bf16 v[16:31], v[76:79], v[96:99], v[16:31]
	v_mfma_f32_32x32x16_bf16 v[0:15], v[76:79], v[80:83], v[0:15]
	global_load_dwordx4 v[76:79], v168, s[8:9] offset:1280
	global_load_dwordx4 v[80:83], v169, s[8:9] offset:1280
	global_load_dwordx4 v[84:87], v170, s[8:9] offset:1280
	global_load_dwordx4 v[96:99], v171, s[8:9] offset:1280
	global_load_dwordx4 v[112:115], v168, s[10:11] offset:1280
	global_load_dwordx4 v[116:119], v169, s[10:11] offset:1280
	global_load_dwordx4 v[120:123], v170, s[10:11] offset:1280
	global_load_dwordx4 v[124:127], v171, s[10:11] offset:1280
	ds_read_b128 v[200:203], v128 offset:64
	ds_read_b128 v[210:213], v128 offset:4672
	ds_read_b128 v[214:217], v131 offset:36928
	ds_read_b128 v[218:221], v131 offset:41536
	s_waitcnt vmcnt(15)
	ds_write_b128 v130, v[64:67] offset:18432
	s_waitcnt vmcnt(14)
	ds_write_b128 v130, v[68:71] offset:23040
	s_waitcnt vmcnt(13)
	ds_write_b128 v130, v[72:75] offset:27648
	s_waitcnt vmcnt(12)
	ds_write_b128 v130, v[100:103] offset:32256
	s_waitcnt lgkmcnt(9)
	v_mfma_f32_32x32x16_bf16 v[32:47], v[88:91], v[104:107], v[32:47]
	s_waitcnt lgkmcnt(8)
	v_mfma_f32_32x32x16_bf16 v[48:63], v[88:91], v[108:111], v[48:63]
	v_mfma_f32_32x32x16_bf16 v[16:31], v[92:95], v[104:107], v[16:31]
	v_mfma_f32_32x32x16_bf16 v[0:15], v[92:95], v[108:111], v[0:15]
	ds_read_b128 v[64:67], v128 offset:96
	ds_read_b128 v[68:71], v128 offset:4704
	ds_read_b128 v[72:75], v131 offset:36960
	ds_read_b128 v[88:91], v131 offset:41568
	s_waitcnt vmcnt(11)
	ds_write_b128 v130, v[172:175] offset:55296
	s_waitcnt vmcnt(10)
	ds_write_b128 v130, v[176:179] offset:59904
	s_waitcnt vmcnt(9)
	ds_write_b128 v130, v[180:183] offset:64512
	s_waitcnt vmcnt(8)
	ds_write_b128 v129, v[196:199] offset:13824
	s_waitcnt lgkmcnt(13)
	v_mfma_f32_32x32x16_bf16 v[32:47], v[200:203], v[214:217], v[32:47]
	s_waitcnt lgkmcnt(0)
	s_barrier
	v_mfma_f32_32x32x16_bf16 v[48:63], v[200:203], v[218:221], v[48:63]
	v_mfma_f32_32x32x16_bf16 v[16:31], v[210:213], v[214:217], v[16:31]
	v_mfma_f32_32x32x16_bf16 v[0:15], v[210:213], v[218:221], v[0:15]
	v_mfma_f32_32x32x16_bf16 v[32:47], v[64:67], v[72:75], v[32:47]
	v_mfma_f32_32x32x16_bf16 v[48:63], v[64:67], v[88:91], v[48:63]
	v_mfma_f32_32x32x16_bf16 v[16:31], v[68:71], v[72:75], v[16:31]
	v_mfma_f32_32x32x16_bf16 v[0:15], v[68:71], v[88:91], v[0:15]
	ds_read_b128 v[64:67], v128 offset:23040
	ds_read_b128 v[72:75], v128 offset:18432
	ds_read_b128 v[68:71], v131 offset:59904
	ds_read_b128 v[100:103], v131 offset:55296
	ds_read_b128 v[88:91], v128 offset:18464
	ds_read_b128 v[92:95], v128 offset:23072
	ds_read_b128 v[104:107], v131 offset:55328
	ds_read_b128 v[108:111], v131 offset:59936
	s_waitcnt lgkmcnt(4)
	v_mfma_f32_32x32x16_bf16 v[32:47], v[72:75], v[100:103], v[32:47]
	v_mfma_f32_32x32x16_bf16 v[48:63], v[72:75], v[68:71], v[48:63]
	v_mfma_f32_32x32x16_bf16 v[16:31], v[64:67], v[100:103], v[16:31]
	v_mfma_f32_32x32x16_bf16 v[0:15], v[64:67], v[68:71], v[0:15]
	global_load_dwordx4 v[64:67], v168, s[8:9] offset:1408
	global_load_dwordx4 v[68:71], v169, s[8:9] offset:1408
	global_load_dwordx4 v[72:75], v170, s[8:9] offset:1408
	global_load_dwordx4 v[100:103], v171, s[8:9] offset:1408
	global_load_dwordx4 v[172:175], v168, s[10:11] offset:1408
	global_load_dwordx4 v[176:179], v169, s[10:11] offset:1408
	global_load_dwordx4 v[180:183], v170, s[10:11] offset:1408
	global_load_dwordx4 v[196:199], v171, s[10:11] offset:1408
	ds_read_b128 v[200:203], v128 offset:18496
	ds_read_b128 v[210:213], v128 offset:23104
	ds_read_b128 v[214:217], v131 offset:55360
	ds_read_b128 v[218:221], v131 offset:59968
	s_waitcnt vmcnt(15)
	ds_write_b128 v130, v[76:79]
	s_waitcnt vmcnt(14)
	ds_write_b128 v130, v[80:83] offset:4608
	s_waitcnt vmcnt(13)
	ds_write_b128 v130, v[84:87] offset:9216
	s_waitcnt vmcnt(12)
	ds_write_b128 v130, v[96:99] offset:13824
	s_waitcnt lgkmcnt(9)
	v_mfma_f32_32x32x16_bf16 v[32:47], v[88:91], v[104:107], v[32:47]
	s_waitcnt lgkmcnt(8)
	v_mfma_f32_32x32x16_bf16 v[48:63], v[88:91], v[108:111], v[48:63]
	v_mfma_f32_32x32x16_bf16 v[16:31], v[92:95], v[104:107], v[16:31]
	v_mfma_f32_32x32x16_bf16 v[0:15], v[92:95], v[108:111], v[0:15]
	ds_read_b128 v[76:79], v128 offset:18528
	ds_read_b128 v[80:83], v128 offset:23136
	ds_read_b128 v[84:87], v131 offset:55392
	ds_read_b128 v[88:91], v131 offset:60000
	s_waitcnt vmcnt(11)
	ds_write_b128 v130, v[112:115] offset:36864
	s_waitcnt vmcnt(10)
	ds_write_b128 v130, v[116:119] offset:41472
	s_waitcnt vmcnt(9)
	ds_write_b128 v130, v[120:123] offset:46080
	s_waitcnt vmcnt(8)
	ds_write_b128 v130, v[124:127] offset:50688
	s_waitcnt lgkmcnt(13)
	v_mfma_f32_32x32x16_bf16 v[32:47], v[200:203], v[214:217], v[32:47]
	s_waitcnt lgkmcnt(0)
	s_barrier
	v_mfma_f32_32x32x16_bf16 v[48:63], v[200:203], v[218:221], v[48:63]
	v_mfma_f32_32x32x16_bf16 v[16:31], v[210:213], v[214:217], v[16:31]
	v_mfma_f32_32x32x16_bf16 v[0:15], v[210:213], v[218:221], v[0:15]
	v_mfma_f32_32x32x16_bf16 v[32:47], v[76:79], v[84:87], v[32:47]
	v_mfma_f32_32x32x16_bf16 v[48:63], v[76:79], v[88:91], v[48:63]
	v_mfma_f32_32x32x16_bf16 v[16:31], v[80:83], v[84:87], v[16:31]
	v_mfma_f32_32x32x16_bf16 v[0:15], v[80:83], v[88:91], v[0:15]
	ds_read_b128 v[76:79], v128 offset:4608
	ds_read_b128 v[84:87], v128
	ds_read_b128 v[80:83], v131 offset:41472
	ds_read_b128 v[96:99], v131 offset:36864
	ds_read_b128 v[88:91], v128 offset:32
	ds_read_b128 v[92:95], v128 offset:4640
	ds_read_b128 v[104:107], v131 offset:36896
	ds_read_b128 v[108:111], v131 offset:41504
	s_waitcnt lgkmcnt(4)
	v_mfma_f32_32x32x16_bf16 v[32:47], v[84:87], v[96:99], v[32:47]
	v_mfma_f32_32x32x16_bf16 v[48:63], v[84:87], v[80:83], v[48:63]
	v_mfma_f32_32x32x16_bf16 v[16:31], v[76:79], v[96:99], v[16:31]
	v_mfma_f32_32x32x16_bf16 v[0:15], v[76:79], v[80:83], v[0:15]
	global_load_dwordx4 v[76:79], v168, s[8:9] offset:1536
	global_load_dwordx4 v[80:83], v169, s[8:9] offset:1536
	global_load_dwordx4 v[84:87], v170, s[8:9] offset:1536
	global_load_dwordx4 v[96:99], v171, s[8:9] offset:1536
	global_load_dwordx4 v[112:115], v168, s[10:11] offset:1536
	global_load_dwordx4 v[116:119], v169, s[10:11] offset:1536
	global_load_dwordx4 v[120:123], v170, s[10:11] offset:1536
	global_load_dwordx4 v[124:127], v171, s[10:11] offset:1536
	ds_read_b128 v[200:203], v128 offset:64
	ds_read_b128 v[210:213], v128 offset:4672
	ds_read_b128 v[214:217], v131 offset:36928
	ds_read_b128 v[218:221], v131 offset:41536
	s_waitcnt vmcnt(15)
	ds_write_b128 v130, v[64:67] offset:18432
	s_waitcnt vmcnt(14)
	ds_write_b128 v130, v[68:71] offset:23040
	s_waitcnt vmcnt(13)
	ds_write_b128 v130, v[72:75] offset:27648
	s_waitcnt vmcnt(12)
	ds_write_b128 v130, v[100:103] offset:32256
	s_waitcnt lgkmcnt(9)
	v_mfma_f32_32x32x16_bf16 v[32:47], v[88:91], v[104:107], v[32:47]
	s_waitcnt lgkmcnt(8)
	v_mfma_f32_32x32x16_bf16 v[48:63], v[88:91], v[108:111], v[48:63]
	v_mfma_f32_32x32x16_bf16 v[16:31], v[92:95], v[104:107], v[16:31]
	v_mfma_f32_32x32x16_bf16 v[0:15], v[92:95], v[108:111], v[0:15]
	ds_read_b128 v[64:67], v128 offset:96
	ds_read_b128 v[68:71], v128 offset:4704
	ds_read_b128 v[72:75], v131 offset:36960
	ds_read_b128 v[88:91], v131 offset:41568
	s_waitcnt vmcnt(11)
	ds_write_b128 v130, v[172:175] offset:55296
	s_waitcnt vmcnt(10)
	ds_write_b128 v130, v[176:179] offset:59904
	s_waitcnt vmcnt(9)
	ds_write_b128 v130, v[180:183] offset:64512
	s_waitcnt vmcnt(8)
	ds_write_b128 v129, v[196:199] offset:13824
	s_waitcnt lgkmcnt(13)
	v_mfma_f32_32x32x16_bf16 v[32:47], v[200:203], v[214:217], v[32:47]
	s_waitcnt lgkmcnt(0)
	s_barrier
	v_mfma_f32_32x32x16_bf16 v[48:63], v[200:203], v[218:221], v[48:63]
	v_mfma_f32_32x32x16_bf16 v[16:31], v[210:213], v[214:217], v[16:31]
	v_mfma_f32_32x32x16_bf16 v[0:15], v[210:213], v[218:221], v[0:15]
	v_mfma_f32_32x32x16_bf16 v[32:47], v[64:67], v[72:75], v[32:47]
	v_mfma_f32_32x32x16_bf16 v[48:63], v[64:67], v[88:91], v[48:63]
	v_mfma_f32_32x32x16_bf16 v[16:31], v[68:71], v[72:75], v[16:31]
	v_mfma_f32_32x32x16_bf16 v[0:15], v[68:71], v[88:91], v[0:15]
	ds_read_b128 v[64:67], v128 offset:23040
	ds_read_b128 v[72:75], v128 offset:18432
	ds_read_b128 v[68:71], v131 offset:59904
	ds_read_b128 v[100:103], v131 offset:55296
	ds_read_b128 v[88:91], v128 offset:18464
	ds_read_b128 v[92:95], v128 offset:23072
	ds_read_b128 v[104:107], v131 offset:55328
	ds_read_b128 v[108:111], v131 offset:59936
	s_waitcnt lgkmcnt(4)
	v_mfma_f32_32x32x16_bf16 v[32:47], v[72:75], v[100:103], v[32:47]
	v_mfma_f32_32x32x16_bf16 v[48:63], v[72:75], v[68:71], v[48:63]
	v_mfma_f32_32x32x16_bf16 v[16:31], v[64:67], v[100:103], v[16:31]
	v_mfma_f32_32x32x16_bf16 v[0:15], v[64:67], v[68:71], v[0:15]
	global_load_dwordx4 v[64:67], v168, s[8:9] offset:1664
	global_load_dwordx4 v[68:71], v169, s[8:9] offset:1664
	global_load_dwordx4 v[72:75], v170, s[8:9] offset:1664
	global_load_dwordx4 v[100:103], v171, s[8:9] offset:1664
	global_load_dwordx4 v[172:175], v168, s[10:11] offset:1664
	global_load_dwordx4 v[176:179], v169, s[10:11] offset:1664
	global_load_dwordx4 v[180:183], v170, s[10:11] offset:1664
	global_load_dwordx4 v[196:199], v171, s[10:11] offset:1664
	ds_read_b128 v[200:203], v128 offset:18496
	ds_read_b128 v[210:213], v128 offset:23104
	ds_read_b128 v[214:217], v131 offset:55360
	ds_read_b128 v[218:221], v131 offset:59968
	s_waitcnt vmcnt(15)
	ds_write_b128 v130, v[76:79]
	s_waitcnt vmcnt(14)
	ds_write_b128 v130, v[80:83] offset:4608
	s_waitcnt vmcnt(13)
	ds_write_b128 v130, v[84:87] offset:9216
	s_waitcnt vmcnt(12)
	ds_write_b128 v130, v[96:99] offset:13824
	s_waitcnt lgkmcnt(9)
	v_mfma_f32_32x32x16_bf16 v[32:47], v[88:91], v[104:107], v[32:47]
	s_waitcnt lgkmcnt(8)
	v_mfma_f32_32x32x16_bf16 v[48:63], v[88:91], v[108:111], v[48:63]
	v_mfma_f32_32x32x16_bf16 v[16:31], v[92:95], v[104:107], v[16:31]
	v_mfma_f32_32x32x16_bf16 v[0:15], v[92:95], v[108:111], v[0:15]
	ds_read_b128 v[76:79], v128 offset:18528
	ds_read_b128 v[80:83], v128 offset:23136
	ds_read_b128 v[84:87], v131 offset:55392
	ds_read_b128 v[88:91], v131 offset:60000
	s_waitcnt vmcnt(11)
	ds_write_b128 v130, v[112:115] offset:36864
	s_waitcnt vmcnt(10)
	ds_write_b128 v130, v[116:119] offset:41472
	s_waitcnt vmcnt(9)
	ds_write_b128 v130, v[120:123] offset:46080
	s_waitcnt vmcnt(8)
	ds_write_b128 v130, v[124:127] offset:50688
	s_waitcnt lgkmcnt(13)
	v_mfma_f32_32x32x16_bf16 v[32:47], v[200:203], v[214:217], v[32:47]
	s_waitcnt lgkmcnt(0)
	s_barrier
	v_mfma_f32_32x32x16_bf16 v[48:63], v[200:203], v[218:221], v[48:63]
	v_mfma_f32_32x32x16_bf16 v[16:31], v[210:213], v[214:217], v[16:31]
	v_mfma_f32_32x32x16_bf16 v[0:15], v[210:213], v[218:221], v[0:15]
	v_mfma_f32_32x32x16_bf16 v[32:47], v[76:79], v[84:87], v[32:47]
	v_mfma_f32_32x32x16_bf16 v[48:63], v[76:79], v[88:91], v[48:63]
	v_mfma_f32_32x32x16_bf16 v[16:31], v[80:83], v[84:87], v[16:31]
	v_mfma_f32_32x32x16_bf16 v[0:15], v[80:83], v[88:91], v[0:15]
	ds_read_b128 v[76:79], v128 offset:4608
	ds_read_b128 v[84:87], v128
	ds_read_b128 v[80:83], v131 offset:41472
	ds_read_b128 v[96:99], v131 offset:36864
	ds_read_b128 v[88:91], v128 offset:32
	ds_read_b128 v[92:95], v128 offset:4640
	ds_read_b128 v[104:107], v131 offset:36896
	ds_read_b128 v[108:111], v131 offset:41504
	s_waitcnt lgkmcnt(4)
	v_mfma_f32_32x32x16_bf16 v[32:47], v[84:87], v[96:99], v[32:47]
	v_mfma_f32_32x32x16_bf16 v[48:63], v[84:87], v[80:83], v[48:63]
	v_mfma_f32_32x32x16_bf16 v[16:31], v[76:79], v[96:99], v[16:31]
	v_mfma_f32_32x32x16_bf16 v[0:15], v[76:79], v[80:83], v[0:15]
	global_load_dwordx4 v[76:79], v168, s[8:9] offset:1792
	global_load_dwordx4 v[80:83], v169, s[8:9] offset:1792
	global_load_dwordx4 v[84:87], v170, s[8:9] offset:1792
	global_load_dwordx4 v[96:99], v171, s[8:9] offset:1792
	global_load_dwordx4 v[112:115], v168, s[10:11] offset:1792
	global_load_dwordx4 v[116:119], v169, s[10:11] offset:1792
	global_load_dwordx4 v[120:123], v170, s[10:11] offset:1792
	global_load_dwordx4 v[124:127], v171, s[10:11] offset:1792
	ds_read_b128 v[200:203], v128 offset:64
	ds_read_b128 v[210:213], v128 offset:4672
	ds_read_b128 v[214:217], v131 offset:36928
	ds_read_b128 v[218:221], v131 offset:41536
	s_waitcnt vmcnt(15)
	ds_write_b128 v130, v[64:67] offset:18432
	s_waitcnt vmcnt(14)
	ds_write_b128 v130, v[68:71] offset:23040
	s_waitcnt vmcnt(13)
	ds_write_b128 v130, v[72:75] offset:27648
	s_waitcnt vmcnt(12)
	ds_write_b128 v130, v[100:103] offset:32256
	s_waitcnt lgkmcnt(9)
	v_mfma_f32_32x32x16_bf16 v[32:47], v[88:91], v[104:107], v[32:47]
	s_waitcnt lgkmcnt(8)
	v_mfma_f32_32x32x16_bf16 v[48:63], v[88:91], v[108:111], v[48:63]
	v_mfma_f32_32x32x16_bf16 v[16:31], v[92:95], v[104:107], v[16:31]
	v_mfma_f32_32x32x16_bf16 v[0:15], v[92:95], v[108:111], v[0:15]
	ds_read_b128 v[64:67], v128 offset:96
	ds_read_b128 v[68:71], v128 offset:4704
	ds_read_b128 v[72:75], v131 offset:36960
	ds_read_b128 v[88:91], v131 offset:41568
	s_waitcnt vmcnt(11)
	ds_write_b128 v130, v[172:175] offset:55296
	s_waitcnt vmcnt(10)
	ds_write_b128 v130, v[176:179] offset:59904
	s_waitcnt vmcnt(9)
	ds_write_b128 v130, v[180:183] offset:64512
	s_waitcnt vmcnt(8)
	ds_write_b128 v129, v[196:199] offset:13824
	s_waitcnt lgkmcnt(13)
	v_mfma_f32_32x32x16_bf16 v[32:47], v[200:203], v[214:217], v[32:47]
	s_waitcnt lgkmcnt(0)
	s_barrier
	v_mfma_f32_32x32x16_bf16 v[48:63], v[200:203], v[218:221], v[48:63]
	v_mfma_f32_32x32x16_bf16 v[16:31], v[210:213], v[214:217], v[16:31]
	v_mfma_f32_32x32x16_bf16 v[0:15], v[210:213], v[218:221], v[0:15]
	v_mfma_f32_32x32x16_bf16 v[32:47], v[64:67], v[72:75], v[32:47]
	v_mfma_f32_32x32x16_bf16 v[48:63], v[64:67], v[88:91], v[48:63]
	v_mfma_f32_32x32x16_bf16 v[16:31], v[68:71], v[72:75], v[16:31]
	v_mfma_f32_32x32x16_bf16 v[0:15], v[68:71], v[88:91], v[0:15]
	ds_read_b128 v[64:67], v128 offset:23040
	ds_read_b128 v[72:75], v128 offset:18432
	ds_read_b128 v[68:71], v131 offset:59904
	ds_read_b128 v[100:103], v131 offset:55296
	ds_read_b128 v[88:91], v128 offset:18464
	ds_read_b128 v[92:95], v128 offset:23072
	ds_read_b128 v[104:107], v131 offset:55328
	ds_read_b128 v[108:111], v131 offset:59936
	s_waitcnt lgkmcnt(4)
	v_mfma_f32_32x32x16_bf16 v[32:47], v[72:75], v[100:103], v[32:47]
	v_mfma_f32_32x32x16_bf16 v[48:63], v[72:75], v[68:71], v[48:63]
	v_mfma_f32_32x32x16_bf16 v[16:31], v[64:67], v[100:103], v[16:31]
	v_mfma_f32_32x32x16_bf16 v[0:15], v[64:67], v[68:71], v[0:15]
	global_load_dwordx4 v[64:67], v168, s[8:9] offset:1920
	global_load_dwordx4 v[68:71], v169, s[8:9] offset:1920
	global_load_dwordx4 v[72:75], v170, s[8:9] offset:1920
	global_load_dwordx4 v[100:103], v171, s[8:9] offset:1920
	global_load_dwordx4 v[172:175], v168, s[10:11] offset:1920
	global_load_dwordx4 v[176:179], v169, s[10:11] offset:1920
	global_load_dwordx4 v[180:183], v170, s[10:11] offset:1920
	s_nop 0
	global_load_dwordx4 v[168:171], v171, s[10:11] offset:1920
	ds_read_b128 v[196:199], v128 offset:18496
	ds_read_b128 v[200:203], v128 offset:23104
	ds_read_b128 v[210:213], v131 offset:55360
	ds_read_b128 v[214:217], v131 offset:59968
	s_waitcnt vmcnt(15)
	ds_write_b128 v130, v[76:79]
	s_waitcnt vmcnt(14)
	ds_write_b128 v130, v[80:83] offset:4608
	s_waitcnt vmcnt(13)
	ds_write_b128 v130, v[84:87] offset:9216
	s_waitcnt vmcnt(12)
	ds_write_b128 v130, v[96:99] offset:13824
	s_waitcnt lgkmcnt(9)
	v_mfma_f32_32x32x16_bf16 v[32:47], v[88:91], v[104:107], v[32:47]
	s_waitcnt lgkmcnt(8)
	v_mfma_f32_32x32x16_bf16 v[48:63], v[88:91], v[108:111], v[48:63]
	v_mfma_f32_32x32x16_bf16 v[0:15], v[92:95], v[108:111], v[0:15]
	v_mfma_f32_32x32x16_bf16 v[16:31], v[92:95], v[104:107], v[16:31]
	ds_read_b128 v[76:79], v128 offset:18528
	ds_read_b128 v[80:83], v128 offset:23136
	ds_read_b128 v[84:87], v131 offset:55392
	ds_read_b128 v[88:91], v131 offset:60000
	s_waitcnt vmcnt(11)
	ds_write_b128 v130, v[112:115] offset:36864
	s_waitcnt vmcnt(10)
	ds_write_b128 v130, v[116:119] offset:41472
	s_waitcnt vmcnt(9)
	ds_write_b128 v130, v[120:123] offset:46080
	s_waitcnt vmcnt(8)
	ds_write_b128 v130, v[124:127] offset:50688
	s_waitcnt lgkmcnt(13)
	v_mfma_f32_32x32x16_bf16 v[32:47], v[196:199], v[210:213], v[32:47]
	s_waitcnt lgkmcnt(0)
	s_barrier
	ds_read_b128 v[92:95], v128
	ds_read_b128 v[96:99], v128 offset:32
	ds_read_b128 v[104:107], v131 offset:36928
	ds_read_b128 v[108:111], v131 offset:41536
	v_mfma_f32_32x32x16_bf16 v[48:63], v[196:199], v[214:217], v[48:63]
	v_mfma_f32_32x32x16_bf16 v[0:15], v[200:203], v[214:217], v[0:15]
	v_mfma_f32_32x32x16_bf16 v[16:31], v[200:203], v[210:213], v[16:31]
	v_mfma_f32_32x32x16_bf16 v[32:47], v[76:79], v[84:87], v[32:47]
	v_mfma_f32_32x32x16_bf16 v[48:63], v[76:79], v[88:91], v[48:63]
	ds_read_b128 v[76:79], v128 offset:4608
	v_mfma_f32_32x32x16_bf16 v[0:15], v[80:83], v[88:91], v[0:15]
	ds_read_b128 v[88:91], v131 offset:36896
	v_mfma_f32_32x32x16_bf16 v[16:31], v[80:83], v[84:87], v[16:31]
	ds_read_b128 v[80:83], v131 offset:41472
	ds_read_b128 v[84:87], v131 offset:36864
	s_waitcnt lgkmcnt(1)
	v_mfma_f32_32x32x16_bf16 v[48:63], v[92:95], v[80:83], v[48:63]
	v_mfma_f32_32x32x16_bf16 v[0:15], v[76:79], v[80:83], v[0:15]
	ds_read_b128 v[80:83], v128 offset:4640
	s_waitcnt lgkmcnt(1)
	v_mfma_f32_32x32x16_bf16 v[32:47], v[92:95], v[84:87], v[32:47]
	ds_read_b128 v[92:95], v128 offset:4672
	v_mfma_f32_32x32x16_bf16 v[16:31], v[76:79], v[84:87], v[16:31]
	ds_read_b128 v[76:79], v131 offset:41504
	ds_read_b128 v[84:87], v128 offset:64
	s_waitcnt vmcnt(7)
	ds_write_b128 v130, v[64:67] offset:18432
	s_waitcnt vmcnt(6)
	ds_write_b128 v130, v[68:71] offset:23040
	s_waitcnt vmcnt(5)
	ds_write_b128 v130, v[72:75] offset:27648
	s_waitcnt vmcnt(4)
	ds_write_b128 v130, v[100:103] offset:32256
	ds_read_b128 v[64:67], v128 offset:96
	v_mfma_f32_32x32x16_bf16 v[32:47], v[96:99], v[88:91], v[32:47]
	ds_read_b128 v[68:71], v128 offset:4704
	ds_read_b128 v[72:75], v131 offset:36960
	s_waitcnt lgkmcnt(10)
	v_mfma_f32_32x32x16_bf16 v[16:31], v[80:83], v[88:91], v[16:31]
	s_waitcnt lgkmcnt(8)
	v_mfma_f32_32x32x16_bf16 v[48:63], v[96:99], v[76:79], v[48:63]
	v_mfma_f32_32x32x16_bf16 v[0:15], v[80:83], v[76:79], v[0:15]
	ds_read_b128 v[76:79], v131 offset:41568
	s_waitcnt vmcnt(3)
	ds_write_b128 v130, v[172:175] offset:55296
	s_waitcnt vmcnt(2)
	ds_write_b128 v130, v[176:179] offset:59904
	s_waitcnt vmcnt(1)
	ds_write_b128 v130, v[180:183] offset:64512
	s_waitcnt vmcnt(0)
	ds_write_b128 v129, v[168:171] offset:13824
	s_waitcnt lgkmcnt(0)
	s_barrier
	v_mfma_f32_32x32x16_bf16 v[32:47], v[84:87], v[104:107], v[32:47]
	ds_read_b128 v[96:99], v128 offset:18464
	ds_read_b128 v[100:103], v128 offset:23072
	ds_read_b128 v[80:83], v131 offset:55360
	ds_read_b128 v[88:91], v131 offset:55392
	v_mfma_f32_32x32x16_bf16 v[16:31], v[92:95], v[104:107], v[16:31]
	ds_read_b128 v[104:107], v131 offset:55328
	v_mfma_f32_32x32x16_bf16 v[48:63], v[84:87], v[108:111], v[48:63]
	ds_read_b128 v[84:87], v131 offset:59968
	v_mfma_f32_32x32x16_bf16 v[0:15], v[92:95], v[108:111], v[0:15]
	ds_read_b128 v[108:111], v131 offset:59936
	ds_read_b128 v[92:95], v131 offset:60000
	v_mfma_f32_32x32x16_bf16 v[32:47], v[64:67], v[72:75], v[32:47]
	v_mfma_f32_32x32x16_bf16 v[16:31], v[68:71], v[72:75], v[16:31]
	ds_read_b128 v[72:75], v128 offset:18432
	v_mfma_f32_32x32x16_bf16 v[48:63], v[64:67], v[76:79], v[48:63]
	ds_read_b128 v[64:67], v128 offset:23040
	v_mfma_f32_32x32x16_bf16 v[0:15], v[68:71], v[76:79], v[0:15]
	ds_read_b128 v[76:79], v131 offset:55296
	ds_read_b128 v[68:71], v131 offset:59904
	s_waitcnt lgkmcnt(1)
	v_mfma_f32_32x32x16_bf16 v[32:47], v[72:75], v[76:79], v[32:47]
	s_waitcnt lgkmcnt(0)
	v_mfma_f32_32x32x16_bf16 v[48:63], v[72:75], v[68:71], v[48:63]
	ds_read_b128 v[72:75], v128 offset:18496
	v_mfma_f32_32x32x16_bf16 v[16:31], v[64:67], v[76:79], v[16:31]
	ds_read_b128 v[76:79], v128 offset:18528
	v_mfma_f32_32x32x16_bf16 v[0:15], v[64:67], v[68:71], v[0:15]
	ds_read_b128 v[64:67], v128 offset:23104
	ds_read_b128 v[68:71], v128 offset:23136
	s_waitcnt lgkmcnt(0)
	s_barrier
	v_mfma_f32_32x32x16_bf16 v[32:47], v[96:99], v[104:107], v[32:47]
	v_mfma_f32_32x32x16_bf16 v[16:31], v[100:103], v[104:107], v[16:31]
	v_mfma_f32_32x32x16_bf16 v[0:15], v[100:103], v[108:111], v[0:15]
	v_mfma_f32_32x32x16_bf16 v[32:47], v[72:75], v[80:83], v[32:47]
	v_mfma_f32_32x32x16_bf16 v[16:31], v[64:67], v[80:83], v[16:31]
	v_mfma_f32_32x32x16_bf16 v[0:15], v[64:67], v[84:87], v[0:15]
	v_lshl_or_b32 v64, s4, 6, v132
	v_add_u32_e32 v66, s6, v133
	v_ashrrev_i32_e32 v65, 31, v64
	v_lshl_add_u64 v[64:65], v[64:65], 1, s[0:1]
	v_or_b32_e32 v67, v66, v134
	v_mfma_f32_32x32x16_bf16 v[32:47], v[76:79], v[88:91], v[32:47]
	v_mfma_f32_32x32x16_bf16 v[48:63], v[96:99], v[108:111], v[48:63]
	v_mfma_f32_32x32x16_bf16 v[16:31], v[68:71], v[88:91], v[16:31]
	v_mfma_f32_32x32x16_bf16 v[0:15], v[68:71], v[92:95], v[0:15]
	s_nop 8
	v_mul_f32_e32 v68, 0xbfb8aa3b, v32
	v_exp_f32_e32 v68, v68
	s_nop 0
	v_add_f32_e32 v68, 1.0, v68
	v_div_scale_f32 v69, s[4:5], v68, v68, 1.0
	v_mfma_f32_32x32x16_bf16 v[48:63], v[72:75], v[84:87], v[48:63]
	v_rcp_f32_e32 v70, v69
	s_nop 0
	v_fma_f32 v71, -v69, v70, 1.0
	v_fmac_f32_e32 v70, v71, v70
	v_div_scale_f32 v71, vcc, 1.0, v68, 1.0
	v_mfma_f32_32x32x16_bf16 v[48:63], v[76:79], v[92:95], v[48:63]
	v_mul_f32_e32 v72, v71, v70
	v_fma_f32 v73, -v69, v72, v71
	v_fmac_f32_e32 v72, v73, v70
	v_fma_f32 v69, -v69, v72, v71
	v_div_fmas_f32 v69, v69, v70, v72
	v_div_fixup_f32 v68, v69, v68, 1.0
	v_mul_f32_e32 v32, v32, v68
	s_nop 4
	v_mul_f32_e32 v32, v48, v32
	v_mul_f32_e32 v48, 0xbfb8aa3b, v33
	v_exp_f32_e32 v48, v48
	v_cvt_pk_bf16_f32 v32, v32, s0
	v_mad_i64_i32 v[68:69], s[4:5], v67, s37, v[64:65]
	v_add_f32_e32 v48, 1.0, v48
	v_div_scale_f32 v67, s[4:5], v48, v48, 1.0
	global_store_short v[68:69], v32, off
	v_rcp_f32_e32 v68, v67
	v_or_b32_e32 v32, v66, v135
	v_fma_f32 v69, -v67, v68, 1.0
	v_fmac_f32_e32 v68, v69, v68
	v_div_scale_f32 v69, vcc, 1.0, v48, 1.0
	v_mul_f32_e32 v70, v69, v68
	v_fma_f32 v71, -v67, v70, v69
	v_fmac_f32_e32 v70, v71, v68
	v_fma_f32 v67, -v67, v70, v69
	v_div_fmas_f32 v67, v67, v68, v70
	v_div_fixup_f32 v48, v67, v48, 1.0
	v_mul_f32_e32 v33, v33, v48
	v_mul_f32_e32 v33, v49, v33
	v_cvt_pk_bf16_f32 v48, v33, s0
	v_mad_i64_i32 v[32:33], s[4:5], v32, s37, v[64:65]
	global_store_short v[32:33], v48, off
	v_mul_f32_e32 v33, 0xbfb8aa3b, v34
	v_exp_f32_e32 v33, v33
	v_or_b32_e32 v32, v66, v136
	v_add_f32_e32 v33, 1.0, v33
	v_rcp_f32_e32 v33, v33
	s_nop 0
	v_mul_f32_e32 v33, v34, v33
	v_mul_f32_e32 v33, v50, v33
	v_cvt_pk_bf16_f32 v34, v33, s0
	v_mad_i64_i32 v[32:33], s[4:5], v32, s37, v[64:65]
	global_store_short v[32:33], v34, off
	v_mul_f32_e32 v33, 0xbfb8aa3b, v35
	v_exp_f32_e32 v33, v33
	v_or_b32_e32 v32, v66, v137
	v_add_f32_e32 v33, 1.0, v33
	v_rcp_f32_e32 v33, v33
	s_nop 0
	v_mul_f32_e32 v33, v35, v33
	v_mul_f32_e32 v33, v51, v33
	v_cvt_pk_bf16_f32 v34, v33, s0
	v_mad_i64_i32 v[32:33], s[4:5], v32, s37, v[64:65]
	global_store_short v[32:33], v34, off
	v_mul_f32_e32 v33, 0xbfb8aa3b, v36
	v_exp_f32_e32 v33, v33
	v_or_b32_e32 v32, v66, v138
	v_add_f32_e32 v33, 1.0, v33
	v_rcp_f32_e32 v33, v33
	s_nop 0
	v_mul_f32_e32 v33, v36, v33
	v_mul_f32_e32 v33, v52, v33
	v_cvt_pk_bf16_f32 v34, v33, s0
	v_mad_i64_i32 v[32:33], s[4:5], v32, s37, v[64:65]
	global_store_short v[32:33], v34, off
	v_mul_f32_e32 v33, 0xbfb8aa3b, v37
	v_exp_f32_e32 v33, v33
	v_or_b32_e32 v32, v66, v139
	v_add_f32_e32 v33, 1.0, v33
	v_rcp_f32_e32 v33, v33
	s_nop 0
	v_mul_f32_e32 v33, v37, v33
	v_mul_f32_e32 v33, v53, v33
	v_cvt_pk_bf16_f32 v34, v33, s0
	v_mad_i64_i32 v[32:33], s[4:5], v32, s37, v[64:65]
	global_store_short v[32:33], v34, off
	v_mul_f32_e32 v33, 0xbfb8aa3b, v38
	v_exp_f32_e32 v33, v33
	v_or_b32_e32 v32, v66, v140
	v_add_f32_e32 v33, 1.0, v33
	v_rcp_f32_e32 v33, v33
	s_nop 0
	v_mul_f32_e32 v33, v38, v33
	v_mul_f32_e32 v33, v54, v33
	v_cvt_pk_bf16_f32 v34, v33, s0
	v_mad_i64_i32 v[32:33], s[4:5], v32, s37, v[64:65]
	global_store_short v[32:33], v34, off
	v_mul_f32_e32 v33, 0xbfb8aa3b, v39
	v_exp_f32_e32 v33, v33
	v_or_b32_e32 v32, v66, v141
	v_add_f32_e32 v33, 1.0, v33
	v_rcp_f32_e32 v33, v33
	s_nop 0
	v_mul_f32_e32 v33, v39, v33
	v_mul_f32_e32 v33, v55, v33
	v_cvt_pk_bf16_f32 v34, v33, s0
	v_mad_i64_i32 v[32:33], s[4:5], v32, s37, v[64:65]
	global_store_short v[32:33], v34, off
	v_mul_f32_e32 v33, 0xbfb8aa3b, v40
	v_exp_f32_e32 v33, v33
	v_or_b32_e32 v32, v66, v142
	v_add_f32_e32 v33, 1.0, v33
	v_rcp_f32_e32 v33, v33
	s_nop 0
	v_mul_f32_e32 v33, v40, v33
	v_mul_f32_e32 v33, v56, v33
	v_cvt_pk_bf16_f32 v34, v33, s0
	v_mad_i64_i32 v[32:33], s[4:5], v32, s37, v[64:65]
	global_store_short v[32:33], v34, off
	v_mul_f32_e32 v33, 0xbfb8aa3b, v41
	v_exp_f32_e32 v33, v33
	v_or_b32_e32 v32, v66, v143
	v_add_f32_e32 v33, 1.0, v33
	v_rcp_f32_e32 v33, v33
	s_nop 0
	v_mul_f32_e32 v33, v41, v33
	v_mul_f32_e32 v33, v57, v33
	v_cvt_pk_bf16_f32 v34, v33, s0
	v_mad_i64_i32 v[32:33], s[4:5], v32, s37, v[64:65]
	global_store_short v[32:33], v34, off
	v_mul_f32_e32 v33, 0xbfb8aa3b, v42
	v_exp_f32_e32 v33, v33
	v_or_b32_e32 v32, v66, v144
	v_add_f32_e32 v33, 1.0, v33
	v_rcp_f32_e32 v33, v33
	s_nop 0
	v_mul_f32_e32 v33, v42, v33
	v_mul_f32_e32 v33, v58, v33
	v_cvt_pk_bf16_f32 v34, v33, s0
	v_mad_i64_i32 v[32:33], s[4:5], v32, s37, v[64:65]
	global_store_short v[32:33], v34, off
	v_mul_f32_e32 v33, 0xbfb8aa3b, v43
	v_exp_f32_e32 v33, v33
	v_or_b32_e32 v32, v66, v145
	v_add_f32_e32 v33, 1.0, v33
	v_rcp_f32_e32 v33, v33
	s_nop 0
	v_mul_f32_e32 v33, v43, v33
	v_mul_f32_e32 v33, v59, v33
	v_cvt_pk_bf16_f32 v34, v33, s0
	v_mad_i64_i32 v[32:33], s[4:5], v32, s37, v[64:65]
	global_store_short v[32:33], v34, off
	v_mul_f32_e32 v33, 0xbfb8aa3b, v44
	v_exp_f32_e32 v33, v33
	v_or_b32_e32 v32, v66, v146
	v_add_f32_e32 v33, 1.0, v33
	v_rcp_f32_e32 v33, v33
	s_nop 0
	v_mul_f32_e32 v33, v44, v33
	v_mul_f32_e32 v33, v60, v33
	v_cvt_pk_bf16_f32 v34, v33, s0
	v_mad_i64_i32 v[32:33], s[4:5], v32, s37, v[64:65]
	global_store_short v[32:33], v34, off
	v_mul_f32_e32 v33, 0xbfb8aa3b, v45
	v_exp_f32_e32 v33, v33
	v_or_b32_e32 v32, v66, v147
	v_add_f32_e32 v33, 1.0, v33
	v_rcp_f32_e32 v33, v33
	s_nop 0
	v_mul_f32_e32 v33, v45, v33
	v_mul_f32_e32 v33, v61, v33
	v_cvt_pk_bf16_f32 v34, v33, s0
	v_mad_i64_i32 v[32:33], s[4:5], v32, s37, v[64:65]
	global_store_short v[32:33], v34, off
	v_mul_f32_e32 v33, 0xbfb8aa3b, v46
	v_exp_f32_e32 v33, v33
	v_or_b32_e32 v32, v66, v148
	v_add_f32_e32 v33, 1.0, v33
	v_rcp_f32_e32 v33, v33
	s_nop 0
	v_mul_f32_e32 v33, v46, v33
	v_mul_f32_e32 v33, v62, v33
	v_cvt_pk_bf16_f32 v34, v33, s0
	v_mad_i64_i32 v[32:33], s[4:5], v32, s37, v[64:65]
	global_store_short v[32:33], v34, off
	v_mul_f32_e32 v33, 0xbfb8aa3b, v47
	v_exp_f32_e32 v33, v33
	v_or_b32_e32 v32, v66, v149
	v_add_f32_e32 v33, 1.0, v33
	v_rcp_f32_e32 v33, v33
	s_nop 0
	v_mul_f32_e32 v33, v47, v33
	v_mul_f32_e32 v33, v63, v33
	v_cvt_pk_bf16_f32 v34, v33, s0
	v_mad_i64_i32 v[32:33], s[4:5], v32, s37, v[64:65]
	global_store_short v[32:33], v34, off
	v_mul_f32_e32 v33, 0xbfb8aa3b, v16
	v_exp_f32_e32 v33, v33
	v_or_b32_e32 v32, v66, v150
	v_add_f32_e32 v33, 1.0, v33
	v_rcp_f32_e32 v33, v33
	s_nop 0
	v_mul_f32_e32 v16, v16, v33
	v_mul_f32_e32 v0, v0, v16
	v_mul_f32_e32 v16, 0xbfb8aa3b, v17
	v_exp_f32_e32 v16, v16
	v_cvt_pk_bf16_f32 v0, v0, s0
	v_mad_i64_i32 v[32:33], s[4:5], v32, s37, v[64:65]
	v_add_f32_e32 v16, 1.0, v16
	global_store_short v[32:33], v0, off
	v_div_scale_f32 v32, s[4:5], v16, v16, 1.0
	v_rcp_f32_e32 v33, v32
	v_or_b32_e32 v0, v66, v151
	v_fma_f32 v34, -v32, v33, 1.0
	v_fmac_f32_e32 v33, v34, v33
	v_div_scale_f32 v34, vcc, 1.0, v16, 1.0
	v_mul_f32_e32 v35, v34, v33
	v_fma_f32 v36, -v32, v35, v34
	v_fmac_f32_e32 v35, v36, v33
	v_fma_f32 v32, -v32, v35, v34
	v_div_fmas_f32 v32, v32, v33, v35
	v_div_fixup_f32 v16, v32, v16, 1.0
	v_mul_f32_e32 v16, v17, v16
	v_mul_f32_e32 v1, v1, v16
	v_cvt_pk_bf16_f32 v16, v1, s0
	v_mad_i64_i32 v[0:1], s[4:5], v0, s37, v[64:65]
	global_store_short v[0:1], v16, off
	v_mul_f32_e32 v1, 0xbfb8aa3b, v18
	v_exp_f32_e32 v1, v1
	v_or_b32_e32 v0, v66, v152
	v_add_f32_e32 v1, 1.0, v1
	v_rcp_f32_e32 v1, v1
	s_nop 0
	v_mul_f32_e32 v1, v18, v1
	v_mul_f32_e32 v1, v2, v1
	v_cvt_pk_bf16_f32 v2, v1, s0
	v_mad_i64_i32 v[0:1], s[4:5], v0, s37, v[64:65]
	global_store_short v[0:1], v2, off
	v_mul_f32_e32 v1, 0xbfb8aa3b, v19
	v_exp_f32_e32 v1, v1
	v_or_b32_e32 v0, v66, v153
	v_add_f32_e32 v1, 1.0, v1
	v_rcp_f32_e32 v1, v1
	s_nop 0
	v_mul_f32_e32 v1, v19, v1
	v_mul_f32_e32 v1, v3, v1
	v_cvt_pk_bf16_f32 v2, v1, s0
	v_mad_i64_i32 v[0:1], s[4:5], v0, s37, v[64:65]
	global_store_short v[0:1], v2, off
	v_mul_f32_e32 v1, 0xbfb8aa3b, v20
	v_exp_f32_e32 v1, v1
	v_or_b32_e32 v0, v66, v154
	v_add_f32_e32 v1, 1.0, v1
	v_rcp_f32_e32 v1, v1
	s_nop 0
	v_mul_f32_e32 v1, v20, v1
	v_mul_f32_e32 v1, v4, v1
	v_cvt_pk_bf16_f32 v2, v1, s0
	v_mad_i64_i32 v[0:1], s[4:5], v0, s37, v[64:65]
	global_store_short v[0:1], v2, off
	v_mul_f32_e32 v1, 0xbfb8aa3b, v21
	v_exp_f32_e32 v1, v1
	v_or_b32_e32 v0, v66, v155
	v_add_f32_e32 v1, 1.0, v1
	v_rcp_f32_e32 v1, v1
	s_nop 0
	v_mul_f32_e32 v1, v21, v1
	v_mul_f32_e32 v1, v5, v1
	v_cvt_pk_bf16_f32 v2, v1, s0
	v_mad_i64_i32 v[0:1], s[4:5], v0, s37, v[64:65]
	global_store_short v[0:1], v2, off
	v_mul_f32_e32 v1, 0xbfb8aa3b, v22
	v_exp_f32_e32 v1, v1
	v_or_b32_e32 v0, v66, v156
	v_add_f32_e32 v1, 1.0, v1
	v_rcp_f32_e32 v1, v1
	s_nop 0
	v_mul_f32_e32 v1, v22, v1
	v_mul_f32_e32 v1, v6, v1
	v_cvt_pk_bf16_f32 v2, v1, s0
	v_mad_i64_i32 v[0:1], s[4:5], v0, s37, v[64:65]
	global_store_short v[0:1], v2, off
	v_mul_f32_e32 v1, 0xbfb8aa3b, v23
	v_exp_f32_e32 v1, v1
	v_or_b32_e32 v0, v66, v157
	v_add_f32_e32 v1, 1.0, v1
	v_rcp_f32_e32 v1, v1
	s_nop 0
	v_mul_f32_e32 v1, v23, v1
	v_mul_f32_e32 v1, v7, v1
	v_cvt_pk_bf16_f32 v2, v1, s0
	v_mad_i64_i32 v[0:1], s[4:5], v0, s37, v[64:65]
	global_store_short v[0:1], v2, off
	v_mul_f32_e32 v1, 0xbfb8aa3b, v24
	v_exp_f32_e32 v1, v1
	v_or_b32_e32 v0, v66, v158
	v_add_f32_e32 v1, 1.0, v1
	v_rcp_f32_e32 v1, v1
	s_nop 0
	v_mul_f32_e32 v1, v24, v1
	v_mul_f32_e32 v1, v8, v1
	v_cvt_pk_bf16_f32 v2, v1, s0
	v_mad_i64_i32 v[0:1], s[4:5], v0, s37, v[64:65]
	global_store_short v[0:1], v2, off
	v_mul_f32_e32 v1, 0xbfb8aa3b, v25
	v_exp_f32_e32 v1, v1
	v_or_b32_e32 v0, v66, v159
	v_add_f32_e32 v1, 1.0, v1
	v_rcp_f32_e32 v1, v1
	s_nop 0
	v_mul_f32_e32 v1, v25, v1
	v_mul_f32_e32 v1, v9, v1
	v_cvt_pk_bf16_f32 v2, v1, s0
	v_mad_i64_i32 v[0:1], s[4:5], v0, s37, v[64:65]
	global_store_short v[0:1], v2, off
	v_mul_f32_e32 v1, 0xbfb8aa3b, v26
	v_exp_f32_e32 v1, v1
	v_or_b32_e32 v0, v66, v160
	v_add_f32_e32 v1, 1.0, v1
	v_rcp_f32_e32 v1, v1
	s_nop 0
	v_mul_f32_e32 v1, v26, v1
	v_mul_f32_e32 v1, v10, v1
	v_cvt_pk_bf16_f32 v2, v1, s0
	v_mad_i64_i32 v[0:1], s[4:5], v0, s37, v[64:65]
	global_store_short v[0:1], v2, off
	v_mul_f32_e32 v1, 0xbfb8aa3b, v27
	v_exp_f32_e32 v1, v1
	v_or_b32_e32 v0, v66, v163
	v_add_f32_e32 v1, 1.0, v1
	v_rcp_f32_e32 v1, v1
	s_nop 0
	v_mul_f32_e32 v1, v27, v1
	v_mul_f32_e32 v1, v11, v1
	v_cvt_pk_bf16_f32 v2, v1, s0
	v_mad_i64_i32 v[0:1], s[4:5], v0, s37, v[64:65]
	global_store_short v[0:1], v2, off
	v_mul_f32_e32 v1, 0xbfb8aa3b, v28
	v_exp_f32_e32 v1, v1
	v_or_b32_e32 v0, v66, v164
	v_add_f32_e32 v1, 1.0, v1
	v_rcp_f32_e32 v1, v1
	s_nop 0
	v_mul_f32_e32 v1, v28, v1
	v_mul_f32_e32 v1, v12, v1
	v_cvt_pk_bf16_f32 v2, v1, s0
	v_mad_i64_i32 v[0:1], s[4:5], v0, s37, v[64:65]
	global_store_short v[0:1], v2, off
	v_mul_f32_e32 v1, 0xbfb8aa3b, v29
	v_exp_f32_e32 v1, v1
	v_or_b32_e32 v0, v66, v165
	v_add_f32_e32 v1, 1.0, v1
	v_rcp_f32_e32 v1, v1
	s_nop 0
	v_mul_f32_e32 v1, v29, v1
	v_mul_f32_e32 v1, v13, v1
	v_cvt_pk_bf16_f32 v2, v1, s0
	v_mad_i64_i32 v[0:1], s[4:5], v0, s37, v[64:65]
	global_store_short v[0:1], v2, off
	v_mul_f32_e32 v1, 0xbfb8aa3b, v30
	v_exp_f32_e32 v1, v1
	v_or_b32_e32 v0, v66, v166
	v_add_f32_e32 v1, 1.0, v1
	v_rcp_f32_e32 v1, v1
	s_nop 0
	v_mul_f32_e32 v1, v30, v1
	v_mul_f32_e32 v1, v14, v1
	v_cvt_pk_bf16_f32 v2, v1, s0
	v_mad_i64_i32 v[0:1], s[4:5], v0, s37, v[64:65]
	global_store_short v[0:1], v2, off
	v_mul_f32_e32 v1, 0xbfb8aa3b, v31
	v_exp_f32_e32 v1, v1
	v_or_b32_e32 v0, v66, v167
	v_add_f32_e32 v1, 1.0, v1
	v_rcp_f32_e32 v1, v1
	s_nop 0
	v_mul_f32_e32 v1, v31, v1
	v_mul_f32_e32 v1, v15, v1
	v_cvt_pk_bf16_f32 v2, v1, s0
	v_mad_i64_i32 v[0:1], s[4:5], v0, s37, v[64:65]
	v_readlane_b32 s4, v252, 22
	s_add_i32 s16, s16, s4
	s_cmp_ge_i32 s16, s23
	global_store_short v[0:1], v2, off
	s_cbranch_scc1 .LBB0_2270
